# attention x6 steady loops: slot-derived SALU constant-folded away (about 16 scalar instructions per step pair)
# speedup vs baseline: 1.0028x; 1.0028x over previous
.Lst0_u6_loop:
	s_add_i32 s46, s58, 0
	s_mov_b32 m0, s46
	s_nop 0
	global_load_lds_dwordx4 v198, s[98:99]
	s_add_i32 m0, s46, 0x400
	s_nop 0
	global_load_lds_dwordx4 v194, s[98:99]
	s_add_i32 s48, s20, 0xffffc000
	s_add_i32 s48, s58, 0x8000
	s_add_i32 m0, s48, 0xc000
	s_nop 0
	global_load_lds_dwordx4 v196, s[100:101]
	s_add_i32 m0, s48, 0xc400
	s_nop 0
	global_load_lds_dwordx4 v192, s[100:101]
	s_add_i32 s46, s20, 0xffff4000
	ds_read_b128 v[96:99], v205 offset:16384
	ds_read_b128 v[100:103], v205 offset:24576
	s_waitcnt lgkmcnt(0)
	v_mfma_f32_32x32x16_bf16 v[112:127], v[96:99], v[160:163], 0
	ds_read_b128 v[128:131], v211 offset:16384
	ds_read_b128 v[132:135], v211 offset:24576
	ds_read_b128 v[136:139], v212 offset:16384
	v_exp_f32_e32 v140, v48
	v_exp_f32_e32 v141, v49
	v_exp_f32_e32 v142, v50
	v_exp_f32_e32 v143, v51
	ds_read_b128 v[48:51], v212 offset:24576
	v_mfma_f32_32x32x16_bf16 v[96:111], v[100:103], v[160:163], 0
	v_exp_f32_e32 v144, v52
	v_exp_f32_e32 v145, v53
	v_exp_f32_e32 v146, v54
	v_exp_f32_e32 v147, v55
	s_waitcnt lgkmcnt(0)
	v_mfma_f32_32x32x16_bf16 v[112:127], v[128:131], v[164:167], v[112:127]
	ds_read_b128 v[52:55], v213 offset:16384
	v_exp_f32_e32 v148, v56
	v_exp_f32_e32 v149, v57
	v_exp_f32_e32 v150, v58
	v_exp_f32_e32 v151, v59
	v_mfma_f32_32x32x16_bf16 v[96:111], v[132:135], v[164:167], v[96:111]
	ds_read_b128 v[56:59], v213 offset:24576
	v_exp_f32_e32 v128, v60
	v_exp_f32_e32 v129, v61
	v_exp_f32_e32 v130, v62
	v_exp_f32_e32 v131, v63
	v_mfma_f32_32x32x16_bf16 v[112:127], v[136:139], v[168:171], v[112:127]
	ds_read_b128 v[60:63], v206 offset:49152
	v_exp_f32_e32 v132, v32
	v_exp_f32_e32 v133, v33
	v_exp_f32_e32 v134, v34
	v_exp_f32_e32 v135, v35
	v_mfma_f32_32x32x16_bf16 v[96:111], v[48:51], v[168:171], v[96:111]
	ds_read_b128 v[32:35], v206 offset:53248
	v_exp_f32_e32 v136, v36
	v_exp_f32_e32 v137, v37
	v_exp_f32_e32 v138, v38
	v_exp_f32_e32 v139, v39
	s_waitcnt lgkmcnt(0)
	v_mfma_f32_32x32x16_bf16 v[112:127], v[52:55], v[172:175], v[112:127]
	ds_read_b128 v[36:39], v206 offset:57344
	v_exp_f32_e32 v152, v40
	v_exp_f32_e32 v153, v41
	v_exp_f32_e32 v154, v42
	v_exp_f32_e32 v155, v43
	v_mfma_f32_32x32x16_bf16 v[96:111], v[56:59], v[172:175], v[96:111]
	ds_read_b128 v[40:43], v206 offset:61440
	v_exp_f32_e32 v156, v44
	v_exp_f32_e32 v157, v45
	v_exp_f32_e32 v158, v46
	v_exp_f32_e32 v159, v47
	v_cvt_pk_bf16_f32 v44, v140, v141
	v_cvt_pk_bf16_f32 v45, v142, v143
	v_cvt_pk_bf16_f32 v46, v144, v145
	v_cvt_pk_bf16_f32 v47, v146, v147
	s_nop 1
	v_mfma_f32_32x32x16_bf16 v[80:95], v[60:63], v[44:47], v[80:95]
	ds_read_b128 v[48:51], v207 offset:49152
	v_cvt_pk_bf16_f32 v52, v148, v149
	v_cvt_pk_bf16_f32 v53, v150, v151
	v_cvt_pk_bf16_f32 v54, v128, v129
	v_cvt_pk_bf16_f32 v55, v130, v131
	v_mfma_f32_32x32x16_bf16 v[64:79], v[32:35], v[44:47], v[64:79]
	ds_read_b128 v[56:59], v207 offset:53248
	v_pk_add_f32 v[62:63], v[146:147], v[142:143]
	v_pk_add_f32 v[60:61], v[144:145], v[140:141]
	s_waitcnt lgkmcnt(0)
	v_mfma_f32_32x32x16_bf16 v[16:31], v[36:39], v[44:47], v[16:31]
	ds_read_b128 v[32:35], v207 offset:57344
	v_add_f32_e64 v62, v150, v62
	v_add_f32_e64 v63, v151, v63
	v_add_f32_e64 v60, v148, v60
	v_add_f32_e64 v61, v149, v61
	v_pk_add_f32 v[62:63], v[130:131], v[62:63]
	v_pk_add_f32 v[60:61], v[128:129], v[60:61]
	v_mfma_f32_32x32x16_bf16 v[0:15], v[40:43], v[44:47], v[0:15]
	ds_read_b128 v[36:39], v207 offset:61440
	v_mfma_f32_32x32x16_bf16 v[80:95], v[48:51], v[52:55], v[80:95]
	ds_read_b128 v[40:43], v208 offset:49152
	v_cvt_pk_bf16_f32 v44, v132, v133
	v_cvt_pk_bf16_f32 v45, v134, v135
	v_cvt_pk_bf16_f32 v46, v136, v137
	v_cvt_pk_bf16_f32 v47, v138, v139
	v_mfma_f32_32x32x16_bf16 v[64:79], v[56:59], v[52:55], v[64:79]
	ds_read_b128 v[48:51], v208 offset:53248
	v_add_f32_e64 v62, v134, v62
	v_add_f32_e64 v63, v135, v63
	v_add_f32_e64 v60, v132, v60
	v_add_f32_e64 v61, v133, v61
	v_pk_add_f32 v[62:63], v[138:139], v[62:63]
	v_pk_add_f32 v[60:61], v[136:137], v[60:61]
	s_waitcnt lgkmcnt(0)
	v_mfma_f32_32x32x16_bf16 v[16:31], v[32:35], v[52:55], v[16:31]
	ds_read_b128 v[56:59], v208 offset:57344
	v_add_f32_e64 v62, v154, v62
	v_add_f32_e64 v63, v155, v63
	v_add_f32_e64 v60, v152, v60
	v_add_f32_e64 v61, v153, v61
	v_pk_add_f32 v[130:131], v[158:159], v[62:63]
	v_pk_add_f32 v[128:129], v[156:157], v[60:61]
	v_mfma_f32_32x32x16_bf16 v[0:15], v[36:39], v[52:55], v[0:15]
	ds_read_b128 v[32:35], v208 offset:61440
	v_mfma_f32_32x32x16_bf16 v[80:95], v[40:43], v[44:47], v[80:95]
	ds_read_b128 v[36:39], v209 offset:49152
	v_cvt_pk_bf16_f32 v52, v152, v153
	v_cvt_pk_bf16_f32 v53, v154, v155
	v_cvt_pk_bf16_f32 v54, v156, v157
	v_cvt_pk_bf16_f32 v55, v158, v159
	v_mfma_f32_32x32x16_bf16 v[64:79], v[48:51], v[44:47], v[64:79]
	ds_read_b128 v[40:43], v209 offset:53248
	s_waitcnt lgkmcnt(0)
	v_mfma_f32_32x32x16_bf16 v[16:31], v[56:59], v[44:47], v[16:31]
	ds_read_b128 v[48:51], v209 offset:57344
	v_mfma_f32_32x32x16_bf16 v[0:15], v[32:35], v[44:47], v[0:15]
	ds_read_b128 v[56:59], v209 offset:61440
	v_mfma_f32_32x32x16_bf16 v[80:95], v[36:39], v[52:55], v[80:95]
	v_mfma_f32_32x32x16_bf16 v[64:79], v[40:43], v[52:55], v[64:79]
	s_waitcnt lgkmcnt(0)
	v_mfma_f32_32x32x16_bf16 v[16:31], v[48:51], v[52:55], v[16:31]
	v_mfma_f32_32x32x16_bf16 v[0:15], v[56:59], v[52:55], v[0:15]
	s_waitcnt vmcnt(4) lgkmcnt(0)
	s_barrier
	s_add_u32 s68, s98, 0x18000
	s_addc_u32 s69, s99, 0
	s_add_i32 s49, 0x4000, s57
	s_mov_b32 m0, s49
	s_nop 0
	global_load_lds_dwordx4 v198, s[68:69]
	s_add_i32 m0, s49, 0x400
	s_nop 0
	global_load_lds_dwordx4 v194, s[68:69]
	s_add_u32 s44, s100, 0x80
	s_addc_u32 s45, s101, 0
	s_add_i32 s49, s58, 0xc000
	s_add_i32 m0, s49, 0xc000
	s_nop 0
	global_load_lds_dwordx4 v196, s[44:45]
	s_add_i32 m0, s49, 0xc400
	s_nop 0
	global_load_lds_dwordx4 v192, s[44:45]
	v_exp_f32_e32 v144, v112
	ds_read_b128 v[32:35], v205 offset:32768
	ds_read_b128 v[36:39], v205 offset:40960
	s_waitcnt lgkmcnt(0)
	v_mfma_f32_32x32x16_bf16 v[48:63], v[32:35], v[160:163], 0
	ds_read_b128 v[132:135], v211 offset:32768
	ds_read_b128 v[136:139], v211 offset:40960
	ds_read_b128 v[140:143], v212 offset:32768
	v_exp_f32_e32 v145, v113
	v_exp_f32_e32 v146, v114
	v_exp_f32_e32 v147, v115
	ds_read_b128 v[112:115], v212 offset:40960
	v_mfma_f32_32x32x16_bf16 v[32:47], v[36:39], v[160:163], 0
	v_exp_f32_e32 v148, v116
	v_exp_f32_e32 v149, v117
	v_exp_f32_e32 v150, v118
	v_exp_f32_e32 v151, v119
	s_waitcnt lgkmcnt(0)
	v_mfma_f32_32x32x16_bf16 v[48:63], v[132:135], v[164:167], v[48:63]
	ds_read_b128 v[116:119], v213 offset:32768
	v_exp_f32_e32 v152, v120
	v_exp_f32_e32 v153, v121
	v_exp_f32_e32 v154, v122
	v_exp_f32_e32 v155, v123
	v_mfma_f32_32x32x16_bf16 v[32:47], v[136:139], v[164:167], v[32:47]
	ds_read_b128 v[120:123], v213 offset:40960
	v_exp_f32_e32 v156, v124
	v_exp_f32_e32 v157, v125
	v_exp_f32_e32 v158, v126
	v_exp_f32_e32 v159, v127
	v_mfma_f32_32x32x16_bf16 v[48:63], v[140:143], v[168:171], v[48:63]
	ds_read_b128 v[124:127], v236
	v_exp_f32_e32 v136, v96
	v_exp_f32_e32 v137, v97
	v_exp_f32_e32 v138, v98
	v_exp_f32_e32 v139, v99
	v_mfma_f32_32x32x16_bf16 v[32:47], v[112:115], v[168:171], v[32:47]
	ds_read_b128 v[96:99], v236 offset:4096
	v_exp_f32_e32 v140, v100
	v_exp_f32_e32 v141, v101
	v_exp_f32_e32 v142, v102
	v_exp_f32_e32 v143, v103
	s_waitcnt lgkmcnt(0)
	v_mfma_f32_32x32x16_bf16 v[48:63], v[116:119], v[172:175], v[48:63]
	ds_read_b128 v[100:103], v236 offset:8192
	v_exp_f32_e32 v178, v104
	v_exp_f32_e32 v179, v105
	v_exp_f32_e32 v180, v106
	v_exp_f32_e32 v181, v107
	v_mfma_f32_32x32x16_bf16 v[32:47], v[120:123], v[172:175], v[32:47]
	ds_read_b128 v[104:107], v236 offset:12288
	v_exp_f32_e32 v182, v108
	v_exp_f32_e32 v183, v109
	v_exp_f32_e32 v184, v110
	v_exp_f32_e32 v185, v111
	v_cvt_pk_bf16_f32 v108, v144, v145
	v_cvt_pk_bf16_f32 v109, v146, v147
	v_cvt_pk_bf16_f32 v110, v148, v149
	v_cvt_pk_bf16_f32 v111, v150, v151
	s_nop 1
	v_mfma_f32_32x32x16_bf16 v[80:95], v[124:127], v[108:111], v[80:95]
	ds_read_b128 v[112:115], v237
	v_cvt_pk_bf16_f32 v116, v152, v153
	v_cvt_pk_bf16_f32 v117, v154, v155
	v_cvt_pk_bf16_f32 v118, v156, v157
	v_cvt_pk_bf16_f32 v119, v158, v159
	v_mfma_f32_32x32x16_bf16 v[64:79], v[96:99], v[108:111], v[64:79]
	ds_read_b128 v[120:123], v237 offset:4096
	v_pk_add_f32 v[126:127], v[150:151], v[146:147]
	v_pk_add_f32 v[124:125], v[148:149], v[144:145]
	s_waitcnt lgkmcnt(0)
	v_mfma_f32_32x32x16_bf16 v[16:31], v[100:103], v[108:111], v[16:31]
	ds_read_b128 v[132:135], v237 offset:8192
	v_add_f32_e64 v98, v154, v126
	v_add_f32_e64 v99, v155, v127
	v_add_f32_e64 v96, v152, v124
	v_add_f32_e64 v97, v153, v125
	v_pk_add_f32 v[98:99], v[158:159], v[98:99]
	v_pk_add_f32 v[96:97], v[156:157], v[96:97]
	v_mfma_f32_32x32x16_bf16 v[0:15], v[104:107], v[108:111], v[0:15]
	ds_read_b128 v[100:103], v237 offset:12288
	v_mfma_f32_32x32x16_bf16 v[80:95], v[112:115], v[116:119], v[80:95]
	ds_read_b128 v[104:107], v238
	v_cvt_pk_bf16_f32 v108, v136, v137
	v_cvt_pk_bf16_f32 v109, v138, v139
	v_cvt_pk_bf16_f32 v110, v140, v141
	v_cvt_pk_bf16_f32 v111, v142, v143
	v_mfma_f32_32x32x16_bf16 v[64:79], v[120:123], v[116:119], v[64:79]
	ds_read_b128 v[112:115], v238 offset:4096
	v_add_f32_e64 v98, v138, v98
	v_add_f32_e64 v99, v139, v99
	v_add_f32_e64 v96, v136, v96
	v_add_f32_e64 v97, v137, v97
	v_pk_add_f32 v[98:99], v[142:143], v[98:99]
	v_pk_add_f32 v[96:97], v[140:141], v[96:97]
	s_waitcnt lgkmcnt(0)
	v_mfma_f32_32x32x16_bf16 v[16:31], v[132:135], v[116:119], v[16:31]
	ds_read_b128 v[120:123], v238 offset:8192
	v_add_f32_e64 v98, v180, v98
	v_add_f32_e64 v99, v181, v99
	v_add_f32_e64 v96, v178, v96
	v_add_f32_e64 v97, v179, v97
	v_pk_add_f32 v[98:99], v[184:185], v[98:99]
	v_pk_add_f32 v[96:97], v[182:183], v[96:97]
	v_mfma_f32_32x32x16_bf16 v[0:15], v[100:103], v[116:119], v[0:15]
	ds_read_b128 v[124:127], v238 offset:12288
	v_mfma_f32_32x32x16_bf16 v[80:95], v[104:107], v[108:111], v[80:95]
	ds_read_b128 v[100:103], v239
	v_cvt_pk_bf16_f32 v116, v178, v179
	v_cvt_pk_bf16_f32 v117, v180, v181
	v_cvt_pk_bf16_f32 v118, v182, v183
	v_cvt_pk_bf16_f32 v119, v184, v185
	v_mfma_f32_32x32x16_bf16 v[64:79], v[112:115], v[108:111], v[64:79]
	ds_read_b128 v[104:107], v239 offset:4096
	s_waitcnt lgkmcnt(0)
	v_mfma_f32_32x32x16_bf16 v[16:31], v[120:123], v[108:111], v[16:31]
	ds_read_b128 v[112:115], v239 offset:8192
	v_mfma_f32_32x32x16_bf16 v[0:15], v[124:127], v[108:111], v[0:15]
	ds_read_b128 v[120:123], v239 offset:12288
	v_mfma_f32_32x32x16_bf16 v[80:95], v[100:103], v[116:119], v[80:95]
	v_mfma_f32_32x32x16_bf16 v[64:79], v[104:107], v[116:119], v[64:79]
	s_waitcnt lgkmcnt(0)
	v_mfma_f32_32x32x16_bf16 v[16:31], v[112:115], v[116:119], v[16:31]
	v_mfma_f32_32x32x16_bf16 v[0:15], v[120:123], v[116:119], v[0:15]
	s_waitcnt vmcnt(4) lgkmcnt(0)
	v_add_f32_e32 v100, v128, v129
	v_add_f32_e32 v101, v130, v131
	v_add_f32_e32 v100, v100, v101
	v_add_f32_e32 v96, v96, v97
	v_add_f32_e32 v97, v98, v99
	s_barrier
	v_add_f32_e32 v100, v177, v100
	v_add_f32_e32 v96, v96, v97
	v_add_f32_e32 v177, v100, v96
	s_add_i32 s21, s21, 2
	s_addk_i32 s15, 0x80
	s_add_i32 s20, s20, 0x8000
	s_add_u32 s98, s98, 0x30000
	s_addc_u32 s99, s99, 0
	s_add_u32 s100, s100, 0x100
	s_addc_u32 s101, s101, 0
	s_add_i32 s46, s58, 0x8000
	s_mov_b32 m0, s46
	s_nop 0
	global_load_lds_dwordx4 v198, s[98:99]
	s_add_i32 m0, s46, 0x400
	s_nop 0
	global_load_lds_dwordx4 v194, s[98:99]
	s_add_i32 s48, s20, 0xffffc000
	s_add_i32 s48, s58, 0
	s_add_i32 m0, s48, 0xc000
	s_nop 0
	global_load_lds_dwordx4 v196, s[100:101]
	s_add_i32 m0, s48, 0xc400
	s_nop 0
	global_load_lds_dwordx4 v192, s[100:101]
	s_add_i32 s46, s20, 0xffff4000
	ds_read_b128 v[96:99], v205
	ds_read_b128 v[100:103], v205 offset:8192
	s_waitcnt lgkmcnt(0)
	v_mfma_f32_32x32x16_bf16 v[112:127], v[96:99], v[160:163], 0
	ds_read_b128 v[128:131], v211
	ds_read_b128 v[132:135], v211 offset:8192
	ds_read_b128 v[136:139], v212
	v_exp_f32_e32 v140, v48
	v_exp_f32_e32 v141, v49
	v_exp_f32_e32 v142, v50
	v_exp_f32_e32 v143, v51
	ds_read_b128 v[48:51], v212 offset:8192
	v_mfma_f32_32x32x16_bf16 v[96:111], v[100:103], v[160:163], 0
	v_exp_f32_e32 v144, v52
	v_exp_f32_e32 v145, v53
	v_exp_f32_e32 v146, v54
	v_exp_f32_e32 v147, v55
	s_waitcnt lgkmcnt(0)
	v_mfma_f32_32x32x16_bf16 v[112:127], v[128:131], v[164:167], v[112:127]
	ds_read_b128 v[52:55], v213
	v_exp_f32_e32 v148, v56
	v_exp_f32_e32 v149, v57
	v_exp_f32_e32 v150, v58
	v_exp_f32_e32 v151, v59
	v_mfma_f32_32x32x16_bf16 v[96:111], v[132:135], v[164:167], v[96:111]
	ds_read_b128 v[56:59], v213 offset:8192
	v_exp_f32_e32 v128, v60
	v_exp_f32_e32 v129, v61
	v_exp_f32_e32 v130, v62
	v_exp_f32_e32 v131, v63
	v_mfma_f32_32x32x16_bf16 v[112:127], v[136:139], v[168:171], v[112:127]
	ds_read_b128 v[60:63], v236 offset:16384
	v_exp_f32_e32 v132, v32
	v_exp_f32_e32 v133, v33
	v_exp_f32_e32 v134, v34
	v_exp_f32_e32 v135, v35
	v_mfma_f32_32x32x16_bf16 v[96:111], v[48:51], v[168:171], v[96:111]
	ds_read_b128 v[32:35], v236 offset:20480
	v_exp_f32_e32 v136, v36
	v_exp_f32_e32 v137, v37
	v_exp_f32_e32 v138, v38
	v_exp_f32_e32 v139, v39
	s_waitcnt lgkmcnt(0)
	v_mfma_f32_32x32x16_bf16 v[112:127], v[52:55], v[172:175], v[112:127]
	ds_read_b128 v[36:39], v236 offset:24576
	v_exp_f32_e32 v152, v40
	v_exp_f32_e32 v153, v41
	v_exp_f32_e32 v154, v42
	v_exp_f32_e32 v155, v43
	v_mfma_f32_32x32x16_bf16 v[96:111], v[56:59], v[172:175], v[96:111]
	ds_read_b128 v[40:43], v236 offset:28672
	v_exp_f32_e32 v156, v44
	v_exp_f32_e32 v157, v45
	v_exp_f32_e32 v158, v46
	v_exp_f32_e32 v159, v47
	v_cvt_pk_bf16_f32 v44, v140, v141
	v_cvt_pk_bf16_f32 v45, v142, v143
	v_cvt_pk_bf16_f32 v46, v144, v145
	v_cvt_pk_bf16_f32 v47, v146, v147
	s_nop 1
	v_mfma_f32_32x32x16_bf16 v[80:95], v[60:63], v[44:47], v[80:95]
	ds_read_b128 v[48:51], v237 offset:16384
	v_cvt_pk_bf16_f32 v52, v148, v149
	v_cvt_pk_bf16_f32 v53, v150, v151
	v_cvt_pk_bf16_f32 v54, v128, v129
	v_cvt_pk_bf16_f32 v55, v130, v131
	v_mfma_f32_32x32x16_bf16 v[64:79], v[32:35], v[44:47], v[64:79]
	ds_read_b128 v[56:59], v237 offset:20480
	v_pk_add_f32 v[62:63], v[146:147], v[142:143]
	v_pk_add_f32 v[60:61], v[144:145], v[140:141]
	s_waitcnt lgkmcnt(0)
	v_mfma_f32_32x32x16_bf16 v[16:31], v[36:39], v[44:47], v[16:31]
	ds_read_b128 v[32:35], v237 offset:24576
	v_add_f32_e64 v62, v150, v62
	v_add_f32_e64 v63, v151, v63
	v_add_f32_e64 v60, v148, v60
	v_add_f32_e64 v61, v149, v61
	v_pk_add_f32 v[62:63], v[130:131], v[62:63]
	v_pk_add_f32 v[60:61], v[128:129], v[60:61]
	v_mfma_f32_32x32x16_bf16 v[0:15], v[40:43], v[44:47], v[0:15]
	ds_read_b128 v[36:39], v237 offset:28672
	v_mfma_f32_32x32x16_bf16 v[80:95], v[48:51], v[52:55], v[80:95]
	ds_read_b128 v[40:43], v238 offset:16384
	v_cvt_pk_bf16_f32 v44, v132, v133
	v_cvt_pk_bf16_f32 v45, v134, v135
	v_cvt_pk_bf16_f32 v46, v136, v137
	v_cvt_pk_bf16_f32 v47, v138, v139
	v_mfma_f32_32x32x16_bf16 v[64:79], v[56:59], v[52:55], v[64:79]
	ds_read_b128 v[48:51], v238 offset:20480
	v_add_f32_e64 v62, v134, v62
	v_add_f32_e64 v63, v135, v63
	v_add_f32_e64 v60, v132, v60
	v_add_f32_e64 v61, v133, v61
	v_pk_add_f32 v[62:63], v[138:139], v[62:63]
	v_pk_add_f32 v[60:61], v[136:137], v[60:61]
	s_waitcnt lgkmcnt(0)
	v_mfma_f32_32x32x16_bf16 v[16:31], v[32:35], v[52:55], v[16:31]
	ds_read_b128 v[56:59], v238 offset:24576
	v_add_f32_e64 v62, v154, v62
	v_add_f32_e64 v63, v155, v63
	v_add_f32_e64 v60, v152, v60
	v_add_f32_e64 v61, v153, v61
	v_pk_add_f32 v[130:131], v[158:159], v[62:63]
	v_pk_add_f32 v[128:129], v[156:157], v[60:61]
	v_mfma_f32_32x32x16_bf16 v[0:15], v[36:39], v[52:55], v[0:15]
	ds_read_b128 v[32:35], v238 offset:28672
	v_mfma_f32_32x32x16_bf16 v[80:95], v[40:43], v[44:47], v[80:95]
	ds_read_b128 v[36:39], v239 offset:16384
	v_cvt_pk_bf16_f32 v52, v152, v153
	v_cvt_pk_bf16_f32 v53, v154, v155
	v_cvt_pk_bf16_f32 v54, v156, v157
	v_cvt_pk_bf16_f32 v55, v158, v159
	v_mfma_f32_32x32x16_bf16 v[64:79], v[48:51], v[44:47], v[64:79]
	ds_read_b128 v[40:43], v239 offset:20480
	s_waitcnt lgkmcnt(0)
	v_mfma_f32_32x32x16_bf16 v[16:31], v[56:59], v[44:47], v[16:31]
	ds_read_b128 v[48:51], v239 offset:24576
	v_mfma_f32_32x32x16_bf16 v[0:15], v[32:35], v[44:47], v[0:15]
	ds_read_b128 v[56:59], v239 offset:28672
	v_mfma_f32_32x32x16_bf16 v[80:95], v[36:39], v[52:55], v[80:95]
	v_mfma_f32_32x32x16_bf16 v[64:79], v[40:43], v[52:55], v[64:79]
	s_waitcnt lgkmcnt(0)
	v_mfma_f32_32x32x16_bf16 v[16:31], v[48:51], v[52:55], v[16:31]
	v_mfma_f32_32x32x16_bf16 v[0:15], v[56:59], v[52:55], v[0:15]
	s_waitcnt vmcnt(4) lgkmcnt(0)
	s_barrier
	s_add_u32 s68, s98, 0x18000
	s_addc_u32 s69, s99, 0
	s_add_i32 s49, 0, s57
	s_mov_b32 m0, s49
	s_nop 0
	global_load_lds_dwordx4 v198, s[68:69]
	s_add_i32 m0, s49, 0x400
	s_nop 0
	global_load_lds_dwordx4 v194, s[68:69]
	s_add_u32 s44, s100, 0x80
	s_addc_u32 s45, s101, 0
	s_add_i32 s49, s58, 0x4000
	s_add_i32 m0, s49, 0xc000
	s_nop 0
	global_load_lds_dwordx4 v196, s[44:45]
	s_add_i32 m0, s49, 0xc400
	s_nop 0
	global_load_lds_dwordx4 v192, s[44:45]
	v_exp_f32_e32 v144, v112
	ds_read_b128 v[32:35], v205 offset:16384
	ds_read_b128 v[36:39], v205 offset:24576
	s_waitcnt lgkmcnt(0)
	v_mfma_f32_32x32x16_bf16 v[48:63], v[32:35], v[160:163], 0
	ds_read_b128 v[132:135], v211 offset:16384
	ds_read_b128 v[136:139], v211 offset:24576
	ds_read_b128 v[140:143], v212 offset:16384
	v_exp_f32_e32 v145, v113
	v_exp_f32_e32 v146, v114
	v_exp_f32_e32 v147, v115
	ds_read_b128 v[112:115], v212 offset:24576
	v_mfma_f32_32x32x16_bf16 v[32:47], v[36:39], v[160:163], 0
	v_exp_f32_e32 v148, v116
	v_exp_f32_e32 v149, v117
	v_exp_f32_e32 v150, v118
	v_exp_f32_e32 v151, v119
	s_waitcnt lgkmcnt(0)
	v_mfma_f32_32x32x16_bf16 v[48:63], v[132:135], v[164:167], v[48:63]
	ds_read_b128 v[116:119], v213 offset:16384
	v_exp_f32_e32 v152, v120
	v_exp_f32_e32 v153, v121
	v_exp_f32_e32 v154, v122
	v_exp_f32_e32 v155, v123
	v_mfma_f32_32x32x16_bf16 v[32:47], v[136:139], v[164:167], v[32:47]
	ds_read_b128 v[120:123], v213 offset:24576
	v_exp_f32_e32 v156, v124
	v_exp_f32_e32 v157, v125
	v_exp_f32_e32 v158, v126
	v_exp_f32_e32 v159, v127
	v_mfma_f32_32x32x16_bf16 v[48:63], v[140:143], v[168:171], v[48:63]
	ds_read_b128 v[124:127], v236 offset:32768
	v_exp_f32_e32 v136, v96
	v_exp_f32_e32 v137, v97
	v_exp_f32_e32 v138, v98
	v_exp_f32_e32 v139, v99
	v_mfma_f32_32x32x16_bf16 v[32:47], v[112:115], v[168:171], v[32:47]
	ds_read_b128 v[96:99], v236 offset:36864
	v_exp_f32_e32 v140, v100
	v_exp_f32_e32 v141, v101
	v_exp_f32_e32 v142, v102
	v_exp_f32_e32 v143, v103
	s_waitcnt lgkmcnt(0)
	v_mfma_f32_32x32x16_bf16 v[48:63], v[116:119], v[172:175], v[48:63]
	ds_read_b128 v[100:103], v236 offset:40960
	v_exp_f32_e32 v178, v104
	v_exp_f32_e32 v179, v105
	v_exp_f32_e32 v180, v106
	v_exp_f32_e32 v181, v107
	v_mfma_f32_32x32x16_bf16 v[32:47], v[120:123], v[172:175], v[32:47]
	ds_read_b128 v[104:107], v236 offset:45056
	v_exp_f32_e32 v182, v108
	v_exp_f32_e32 v183, v109
	v_exp_f32_e32 v184, v110
	v_exp_f32_e32 v185, v111
	v_cvt_pk_bf16_f32 v108, v144, v145
	v_cvt_pk_bf16_f32 v109, v146, v147
	v_cvt_pk_bf16_f32 v110, v148, v149
	v_cvt_pk_bf16_f32 v111, v150, v151
	s_nop 1
	v_mfma_f32_32x32x16_bf16 v[80:95], v[124:127], v[108:111], v[80:95]
	ds_read_b128 v[112:115], v237 offset:32768
	v_cvt_pk_bf16_f32 v116, v152, v153
	v_cvt_pk_bf16_f32 v117, v154, v155
	v_cvt_pk_bf16_f32 v118, v156, v157
	v_cvt_pk_bf16_f32 v119, v158, v159
	v_mfma_f32_32x32x16_bf16 v[64:79], v[96:99], v[108:111], v[64:79]
	ds_read_b128 v[120:123], v237 offset:36864
	v_pk_add_f32 v[126:127], v[150:151], v[146:147]
	v_pk_add_f32 v[124:125], v[148:149], v[144:145]
	s_waitcnt lgkmcnt(0)
	v_mfma_f32_32x32x16_bf16 v[16:31], v[100:103], v[108:111], v[16:31]
	ds_read_b128 v[132:135], v237 offset:40960
	v_add_f32_e64 v98, v154, v126
	v_add_f32_e64 v99, v155, v127
	v_add_f32_e64 v96, v152, v124
	v_add_f32_e64 v97, v153, v125
	v_pk_add_f32 v[98:99], v[158:159], v[98:99]
	v_pk_add_f32 v[96:97], v[156:157], v[96:97]
	v_mfma_f32_32x32x16_bf16 v[0:15], v[104:107], v[108:111], v[0:15]
	ds_read_b128 v[100:103], v237 offset:45056
	v_mfma_f32_32x32x16_bf16 v[80:95], v[112:115], v[116:119], v[80:95]
	ds_read_b128 v[104:107], v238 offset:32768
	v_cvt_pk_bf16_f32 v108, v136, v137
	v_cvt_pk_bf16_f32 v109, v138, v139
	v_cvt_pk_bf16_f32 v110, v140, v141
	v_cvt_pk_bf16_f32 v111, v142, v143
	v_mfma_f32_32x32x16_bf16 v[64:79], v[120:123], v[116:119], v[64:79]
	ds_read_b128 v[112:115], v238 offset:36864
	v_add_f32_e64 v98, v138, v98
	v_add_f32_e64 v99, v139, v99
	v_add_f32_e64 v96, v136, v96
	v_add_f32_e64 v97, v137, v97
	v_pk_add_f32 v[98:99], v[142:143], v[98:99]
	v_pk_add_f32 v[96:97], v[140:141], v[96:97]
	s_waitcnt lgkmcnt(0)
	v_mfma_f32_32x32x16_bf16 v[16:31], v[132:135], v[116:119], v[16:31]
	ds_read_b128 v[120:123], v238 offset:40960
	v_add_f32_e64 v98, v180, v98
	v_add_f32_e64 v99, v181, v99
	v_add_f32_e64 v96, v178, v96
	v_add_f32_e64 v97, v179, v97
	v_pk_add_f32 v[98:99], v[184:185], v[98:99]
	v_pk_add_f32 v[96:97], v[182:183], v[96:97]
	v_mfma_f32_32x32x16_bf16 v[0:15], v[100:103], v[116:119], v[0:15]
	ds_read_b128 v[124:127], v238 offset:45056
	v_mfma_f32_32x32x16_bf16 v[80:95], v[104:107], v[108:111], v[80:95]
	ds_read_b128 v[100:103], v239 offset:32768
	v_cvt_pk_bf16_f32 v116, v178, v179
	v_cvt_pk_bf16_f32 v117, v180, v181
	v_cvt_pk_bf16_f32 v118, v182, v183
	v_cvt_pk_bf16_f32 v119, v184, v185
	v_mfma_f32_32x32x16_bf16 v[64:79], v[112:115], v[108:111], v[64:79]
	ds_read_b128 v[104:107], v239 offset:36864
	s_waitcnt lgkmcnt(0)
	v_mfma_f32_32x32x16_bf16 v[16:31], v[120:123], v[108:111], v[16:31]
	ds_read_b128 v[112:115], v239 offset:40960
	v_mfma_f32_32x32x16_bf16 v[0:15], v[124:127], v[108:111], v[0:15]
	ds_read_b128 v[120:123], v239 offset:45056
	v_mfma_f32_32x32x16_bf16 v[80:95], v[100:103], v[116:119], v[80:95]
	v_mfma_f32_32x32x16_bf16 v[64:79], v[104:107], v[116:119], v[64:79]
	s_waitcnt lgkmcnt(0)
	v_mfma_f32_32x32x16_bf16 v[16:31], v[112:115], v[116:119], v[16:31]
	v_mfma_f32_32x32x16_bf16 v[0:15], v[120:123], v[116:119], v[0:15]
	s_waitcnt vmcnt(4) lgkmcnt(0)
	v_add_f32_e32 v100, v128, v129
	v_add_f32_e32 v101, v130, v131
	v_add_f32_e32 v100, v100, v101
	v_add_f32_e32 v96, v96, v97
	v_add_f32_e32 v97, v98, v99
	s_barrier
	v_add_f32_e32 v100, v177, v100
	v_add_f32_e32 v96, v96, v97
	v_add_f32_e32 v177, v100, v96
	s_add_i32 s21, s21, 2
	s_addk_i32 s15, 0x80
	s_add_i32 s20, s20, 0x8000
	s_add_u32 s98, s98, 0x30000
	s_addc_u32 s99, s99, 0
	s_add_u32 s100, s100, 0x100
	s_addc_u32 s101, s101, 0
	s_add_i32 s46, s58, 0x4000
	s_mov_b32 m0, s46
	s_nop 0
	global_load_lds_dwordx4 v198, s[98:99]
	s_add_i32 m0, s46, 0x400
	s_nop 0
	global_load_lds_dwordx4 v194, s[98:99]
	s_add_i32 s48, s20, 0xffffc000
	s_add_i32 s48, s58, 0x8000
	s_add_i32 m0, s48, 0xc000
	s_nop 0
	global_load_lds_dwordx4 v196, s[100:101]
	s_add_i32 m0, s48, 0xc400
	s_nop 0
	global_load_lds_dwordx4 v192, s[100:101]
	s_add_i32 s46, s20, 0xffff4000
	ds_read_b128 v[96:99], v205 offset:32768
	ds_read_b128 v[100:103], v205 offset:40960
	s_waitcnt lgkmcnt(0)
	v_mfma_f32_32x32x16_bf16 v[112:127], v[96:99], v[160:163], 0
	ds_read_b128 v[128:131], v211 offset:32768
	ds_read_b128 v[132:135], v211 offset:40960
	ds_read_b128 v[136:139], v212 offset:32768
	v_exp_f32_e32 v140, v48
	v_exp_f32_e32 v141, v49
	v_exp_f32_e32 v142, v50
	v_exp_f32_e32 v143, v51
	ds_read_b128 v[48:51], v212 offset:40960
	v_mfma_f32_32x32x16_bf16 v[96:111], v[100:103], v[160:163], 0
	v_exp_f32_e32 v144, v52
	v_exp_f32_e32 v145, v53
	v_exp_f32_e32 v146, v54
	v_exp_f32_e32 v147, v55
	s_waitcnt lgkmcnt(0)
	v_mfma_f32_32x32x16_bf16 v[112:127], v[128:131], v[164:167], v[112:127]
	ds_read_b128 v[52:55], v213 offset:32768
	v_exp_f32_e32 v148, v56
	v_exp_f32_e32 v149, v57
	v_exp_f32_e32 v150, v58
	v_exp_f32_e32 v151, v59
	v_mfma_f32_32x32x16_bf16 v[96:111], v[132:135], v[164:167], v[96:111]
	ds_read_b128 v[56:59], v213 offset:40960
	v_exp_f32_e32 v128, v60
	v_exp_f32_e32 v129, v61
	v_exp_f32_e32 v130, v62
	v_exp_f32_e32 v131, v63
	v_mfma_f32_32x32x16_bf16 v[112:127], v[136:139], v[168:171], v[112:127]
	ds_read_b128 v[60:63], v206 offset:49152
	v_exp_f32_e32 v132, v32
	v_exp_f32_e32 v133, v33
	v_exp_f32_e32 v134, v34
	v_exp_f32_e32 v135, v35
	v_mfma_f32_32x32x16_bf16 v[96:111], v[48:51], v[168:171], v[96:111]
	ds_read_b128 v[32:35], v206 offset:53248
	v_exp_f32_e32 v136, v36
	v_exp_f32_e32 v137, v37
	v_exp_f32_e32 v138, v38
	v_exp_f32_e32 v139, v39
	s_waitcnt lgkmcnt(0)
	v_mfma_f32_32x32x16_bf16 v[112:127], v[52:55], v[172:175], v[112:127]
	ds_read_b128 v[36:39], v206 offset:57344
	v_exp_f32_e32 v152, v40
	v_exp_f32_e32 v153, v41
	v_exp_f32_e32 v154, v42
	v_exp_f32_e32 v155, v43
	v_mfma_f32_32x32x16_bf16 v[96:111], v[56:59], v[172:175], v[96:111]
	ds_read_b128 v[40:43], v206 offset:61440
	v_exp_f32_e32 v156, v44
	v_exp_f32_e32 v157, v45
	v_exp_f32_e32 v158, v46
	v_exp_f32_e32 v159, v47
	v_cvt_pk_bf16_f32 v44, v140, v141
	v_cvt_pk_bf16_f32 v45, v142, v143
	v_cvt_pk_bf16_f32 v46, v144, v145
	v_cvt_pk_bf16_f32 v47, v146, v147
	s_nop 1
	v_mfma_f32_32x32x16_bf16 v[80:95], v[60:63], v[44:47], v[80:95]
	ds_read_b128 v[48:51], v207 offset:49152
	v_cvt_pk_bf16_f32 v52, v148, v149
	v_cvt_pk_bf16_f32 v53, v150, v151
	v_cvt_pk_bf16_f32 v54, v128, v129
	v_cvt_pk_bf16_f32 v55, v130, v131
	v_mfma_f32_32x32x16_bf16 v[64:79], v[32:35], v[44:47], v[64:79]
	ds_read_b128 v[56:59], v207 offset:53248
	v_pk_add_f32 v[62:63], v[146:147], v[142:143]
	v_pk_add_f32 v[60:61], v[144:145], v[140:141]
	s_waitcnt lgkmcnt(0)
	v_mfma_f32_32x32x16_bf16 v[16:31], v[36:39], v[44:47], v[16:31]
	ds_read_b128 v[32:35], v207 offset:57344
	v_add_f32_e64 v62, v150, v62
	v_add_f32_e64 v63, v151, v63
	v_add_f32_e64 v60, v148, v60
	v_add_f32_e64 v61, v149, v61
	v_pk_add_f32 v[62:63], v[130:131], v[62:63]
	v_pk_add_f32 v[60:61], v[128:129], v[60:61]
	v_mfma_f32_32x32x16_bf16 v[0:15], v[40:43], v[44:47], v[0:15]
	ds_read_b128 v[36:39], v207 offset:61440
	v_mfma_f32_32x32x16_bf16 v[80:95], v[48:51], v[52:55], v[80:95]
	ds_read_b128 v[40:43], v208 offset:49152
	v_cvt_pk_bf16_f32 v44, v132, v133
	v_cvt_pk_bf16_f32 v45, v134, v135
	v_cvt_pk_bf16_f32 v46, v136, v137
	v_cvt_pk_bf16_f32 v47, v138, v139
	v_mfma_f32_32x32x16_bf16 v[64:79], v[56:59], v[52:55], v[64:79]
	ds_read_b128 v[48:51], v208 offset:53248
	v_add_f32_e64 v62, v134, v62
	v_add_f32_e64 v63, v135, v63
	v_add_f32_e64 v60, v132, v60
	v_add_f32_e64 v61, v133, v61
	v_pk_add_f32 v[62:63], v[138:139], v[62:63]
	v_pk_add_f32 v[60:61], v[136:137], v[60:61]
	s_waitcnt lgkmcnt(0)
	v_mfma_f32_32x32x16_bf16 v[16:31], v[32:35], v[52:55], v[16:31]
	ds_read_b128 v[56:59], v208 offset:57344
	v_add_f32_e64 v62, v154, v62
	v_add_f32_e64 v63, v155, v63
	v_add_f32_e64 v60, v152, v60
	v_add_f32_e64 v61, v153, v61
	v_pk_add_f32 v[130:131], v[158:159], v[62:63]
	v_pk_add_f32 v[128:129], v[156:157], v[60:61]
	v_mfma_f32_32x32x16_bf16 v[0:15], v[36:39], v[52:55], v[0:15]
	ds_read_b128 v[32:35], v208 offset:61440
	v_mfma_f32_32x32x16_bf16 v[80:95], v[40:43], v[44:47], v[80:95]
	ds_read_b128 v[36:39], v209 offset:49152
	v_cvt_pk_bf16_f32 v52, v152, v153
	v_cvt_pk_bf16_f32 v53, v154, v155
	v_cvt_pk_bf16_f32 v54, v156, v157
	v_cvt_pk_bf16_f32 v55, v158, v159
	v_mfma_f32_32x32x16_bf16 v[64:79], v[48:51], v[44:47], v[64:79]
	ds_read_b128 v[40:43], v209 offset:53248
	s_waitcnt lgkmcnt(0)
	v_mfma_f32_32x32x16_bf16 v[16:31], v[56:59], v[44:47], v[16:31]
	ds_read_b128 v[48:51], v209 offset:57344
	v_mfma_f32_32x32x16_bf16 v[0:15], v[32:35], v[44:47], v[0:15]
	ds_read_b128 v[56:59], v209 offset:61440
	v_mfma_f32_32x32x16_bf16 v[80:95], v[36:39], v[52:55], v[80:95]
	v_mfma_f32_32x32x16_bf16 v[64:79], v[40:43], v[52:55], v[64:79]
	s_waitcnt lgkmcnt(0)
	v_mfma_f32_32x32x16_bf16 v[16:31], v[48:51], v[52:55], v[16:31]
	v_mfma_f32_32x32x16_bf16 v[0:15], v[56:59], v[52:55], v[0:15]
	s_waitcnt vmcnt(4) lgkmcnt(0)
	s_barrier
	s_add_u32 s68, s98, 0x18000
	s_addc_u32 s69, s99, 0
	s_add_i32 s49, 0x8000, s57
	s_mov_b32 m0, s49
	s_nop 0
	global_load_lds_dwordx4 v198, s[68:69]
	s_add_i32 m0, s49, 0x400
	s_nop 0
	global_load_lds_dwordx4 v194, s[68:69]
	s_add_u32 s44, s100, 0x80
	s_addc_u32 s45, s101, 0
	s_add_i32 s49, s58, 0xc000
	s_add_i32 m0, s49, 0xc000
	s_nop 0
	global_load_lds_dwordx4 v196, s[44:45]
	s_add_i32 m0, s49, 0xc400
	s_nop 0
	global_load_lds_dwordx4 v192, s[44:45]
	v_exp_f32_e32 v144, v112
	ds_read_b128 v[32:35], v205
	ds_read_b128 v[36:39], v205 offset:8192
	s_waitcnt lgkmcnt(0)
	v_mfma_f32_32x32x16_bf16 v[48:63], v[32:35], v[160:163], 0
	ds_read_b128 v[132:135], v211
	ds_read_b128 v[136:139], v211 offset:8192
	ds_read_b128 v[140:143], v212
	v_exp_f32_e32 v145, v113
	v_exp_f32_e32 v146, v114
	v_exp_f32_e32 v147, v115
	ds_read_b128 v[112:115], v212 offset:8192
	v_mfma_f32_32x32x16_bf16 v[32:47], v[36:39], v[160:163], 0
	v_exp_f32_e32 v148, v116
	v_exp_f32_e32 v149, v117
	v_exp_f32_e32 v150, v118
	v_exp_f32_e32 v151, v119
	s_waitcnt lgkmcnt(0)
	v_mfma_f32_32x32x16_bf16 v[48:63], v[132:135], v[164:167], v[48:63]
	ds_read_b128 v[116:119], v213
	v_exp_f32_e32 v152, v120
	v_exp_f32_e32 v153, v121
	v_exp_f32_e32 v154, v122
	v_exp_f32_e32 v155, v123
	v_mfma_f32_32x32x16_bf16 v[32:47], v[136:139], v[164:167], v[32:47]
	ds_read_b128 v[120:123], v213 offset:8192
	v_exp_f32_e32 v156, v124
	v_exp_f32_e32 v157, v125
	v_exp_f32_e32 v158, v126
	v_exp_f32_e32 v159, v127
	v_mfma_f32_32x32x16_bf16 v[48:63], v[140:143], v[168:171], v[48:63]
	ds_read_b128 v[124:127], v236
	v_exp_f32_e32 v136, v96
	v_exp_f32_e32 v137, v97
	v_exp_f32_e32 v138, v98
	v_exp_f32_e32 v139, v99
	v_mfma_f32_32x32x16_bf16 v[32:47], v[112:115], v[168:171], v[32:47]
	ds_read_b128 v[96:99], v236 offset:4096
	v_exp_f32_e32 v140, v100
	v_exp_f32_e32 v141, v101
	v_exp_f32_e32 v142, v102
	v_exp_f32_e32 v143, v103
	s_waitcnt lgkmcnt(0)
	v_mfma_f32_32x32x16_bf16 v[48:63], v[116:119], v[172:175], v[48:63]
	ds_read_b128 v[100:103], v236 offset:8192
	v_exp_f32_e32 v178, v104
	v_exp_f32_e32 v179, v105
	v_exp_f32_e32 v180, v106
	v_exp_f32_e32 v181, v107
	v_mfma_f32_32x32x16_bf16 v[32:47], v[120:123], v[172:175], v[32:47]
	ds_read_b128 v[104:107], v236 offset:12288
	v_exp_f32_e32 v182, v108
	v_exp_f32_e32 v183, v109
	v_exp_f32_e32 v184, v110
	v_exp_f32_e32 v185, v111
	v_cvt_pk_bf16_f32 v108, v144, v145
	v_cvt_pk_bf16_f32 v109, v146, v147
	v_cvt_pk_bf16_f32 v110, v148, v149
	v_cvt_pk_bf16_f32 v111, v150, v151
	s_nop 1
	v_mfma_f32_32x32x16_bf16 v[80:95], v[124:127], v[108:111], v[80:95]
	ds_read_b128 v[112:115], v237
	v_cvt_pk_bf16_f32 v116, v152, v153
	v_cvt_pk_bf16_f32 v117, v154, v155
	v_cvt_pk_bf16_f32 v118, v156, v157
	v_cvt_pk_bf16_f32 v119, v158, v159
	v_mfma_f32_32x32x16_bf16 v[64:79], v[96:99], v[108:111], v[64:79]
	ds_read_b128 v[120:123], v237 offset:4096
	v_pk_add_f32 v[126:127], v[150:151], v[146:147]
	v_pk_add_f32 v[124:125], v[148:149], v[144:145]
	s_waitcnt lgkmcnt(0)
	v_mfma_f32_32x32x16_bf16 v[16:31], v[100:103], v[108:111], v[16:31]
	ds_read_b128 v[132:135], v237 offset:8192
	v_add_f32_e64 v98, v154, v126
	v_add_f32_e64 v99, v155, v127
	v_add_f32_e64 v96, v152, v124
	v_add_f32_e64 v97, v153, v125
	v_pk_add_f32 v[98:99], v[158:159], v[98:99]
	v_pk_add_f32 v[96:97], v[156:157], v[96:97]
	v_mfma_f32_32x32x16_bf16 v[0:15], v[104:107], v[108:111], v[0:15]
	ds_read_b128 v[100:103], v237 offset:12288
	v_mfma_f32_32x32x16_bf16 v[80:95], v[112:115], v[116:119], v[80:95]
	ds_read_b128 v[104:107], v238
	v_cvt_pk_bf16_f32 v108, v136, v137
	v_cvt_pk_bf16_f32 v109, v138, v139
	v_cvt_pk_bf16_f32 v110, v140, v141
	v_cvt_pk_bf16_f32 v111, v142, v143
	v_mfma_f32_32x32x16_bf16 v[64:79], v[120:123], v[116:119], v[64:79]
	ds_read_b128 v[112:115], v238 offset:4096
	v_add_f32_e64 v98, v138, v98
	v_add_f32_e64 v99, v139, v99
	v_add_f32_e64 v96, v136, v96
	v_add_f32_e64 v97, v137, v97
	v_pk_add_f32 v[98:99], v[142:143], v[98:99]
	v_pk_add_f32 v[96:97], v[140:141], v[96:97]
	s_waitcnt lgkmcnt(0)
	v_mfma_f32_32x32x16_bf16 v[16:31], v[132:135], v[116:119], v[16:31]
	ds_read_b128 v[120:123], v238 offset:8192
	v_add_f32_e64 v98, v180, v98
	v_add_f32_e64 v99, v181, v99
	v_add_f32_e64 v96, v178, v96
	v_add_f32_e64 v97, v179, v97
	v_pk_add_f32 v[98:99], v[184:185], v[98:99]
	v_pk_add_f32 v[96:97], v[182:183], v[96:97]
	v_mfma_f32_32x32x16_bf16 v[0:15], v[100:103], v[116:119], v[0:15]
	ds_read_b128 v[124:127], v238 offset:12288
	v_mfma_f32_32x32x16_bf16 v[80:95], v[104:107], v[108:111], v[80:95]
	ds_read_b128 v[100:103], v239
	v_cvt_pk_bf16_f32 v116, v178, v179
	v_cvt_pk_bf16_f32 v117, v180, v181
	v_cvt_pk_bf16_f32 v118, v182, v183
	v_cvt_pk_bf16_f32 v119, v184, v185
	v_mfma_f32_32x32x16_bf16 v[64:79], v[112:115], v[108:111], v[64:79]
	ds_read_b128 v[104:107], v239 offset:4096
	s_waitcnt lgkmcnt(0)
	v_mfma_f32_32x32x16_bf16 v[16:31], v[120:123], v[108:111], v[16:31]
	ds_read_b128 v[112:115], v239 offset:8192
	v_mfma_f32_32x32x16_bf16 v[0:15], v[124:127], v[108:111], v[0:15]
	ds_read_b128 v[120:123], v239 offset:12288
	v_mfma_f32_32x32x16_bf16 v[80:95], v[100:103], v[116:119], v[80:95]
	v_mfma_f32_32x32x16_bf16 v[64:79], v[104:107], v[116:119], v[64:79]
	s_waitcnt lgkmcnt(0)
	v_mfma_f32_32x32x16_bf16 v[16:31], v[112:115], v[116:119], v[16:31]
	v_mfma_f32_32x32x16_bf16 v[0:15], v[120:123], v[116:119], v[0:15]
	s_waitcnt vmcnt(4) lgkmcnt(0)
	v_add_f32_e32 v100, v128, v129
	v_add_f32_e32 v101, v130, v131
	v_add_f32_e32 v100, v100, v101
	v_add_f32_e32 v96, v96, v97
	v_add_f32_e32 v97, v98, v99
	s_barrier
	v_add_f32_e32 v100, v177, v100
	v_add_f32_e32 v96, v96, v97
	v_add_f32_e32 v177, v100, v96
	s_add_i32 s21, s21, 2
	s_addk_i32 s15, 0x80
	s_add_i32 s20, s20, 0x8000
	s_add_u32 s98, s98, 0x30000
	s_addc_u32 s99, s99, 0
	s_add_u32 s100, s100, 0x100
	s_addc_u32 s101, s101, 0
	s_add_i32 s46, s58, 0
	s_mov_b32 m0, s46
	s_nop 0
	global_load_lds_dwordx4 v198, s[98:99]
	s_add_i32 m0, s46, 0x400
	s_nop 0
	global_load_lds_dwordx4 v194, s[98:99]
	s_add_i32 s48, s20, 0xffffc000
	s_add_i32 s48, s58, 0
	s_add_i32 m0, s48, 0xc000
	s_nop 0
	global_load_lds_dwordx4 v196, s[100:101]
	s_add_i32 m0, s48, 0xc400
	s_nop 0
	global_load_lds_dwordx4 v192, s[100:101]
	s_add_i32 s46, s20, 0xffff4000
	ds_read_b128 v[96:99], v205 offset:16384
	ds_read_b128 v[100:103], v205 offset:24576
	s_waitcnt lgkmcnt(0)
	v_mfma_f32_32x32x16_bf16 v[112:127], v[96:99], v[160:163], 0
	ds_read_b128 v[128:131], v211 offset:16384
	ds_read_b128 v[132:135], v211 offset:24576
	ds_read_b128 v[136:139], v212 offset:16384
	v_exp_f32_e32 v140, v48
	v_exp_f32_e32 v141, v49
	v_exp_f32_e32 v142, v50
	v_exp_f32_e32 v143, v51
	ds_read_b128 v[48:51], v212 offset:24576
	v_mfma_f32_32x32x16_bf16 v[96:111], v[100:103], v[160:163], 0
	v_exp_f32_e32 v144, v52
	v_exp_f32_e32 v145, v53
	v_exp_f32_e32 v146, v54
	v_exp_f32_e32 v147, v55
	s_waitcnt lgkmcnt(0)
	v_mfma_f32_32x32x16_bf16 v[112:127], v[128:131], v[164:167], v[112:127]
	ds_read_b128 v[52:55], v213 offset:16384
	v_exp_f32_e32 v148, v56
	v_exp_f32_e32 v149, v57
	v_exp_f32_e32 v150, v58
	v_exp_f32_e32 v151, v59
	v_mfma_f32_32x32x16_bf16 v[96:111], v[132:135], v[164:167], v[96:111]
	ds_read_b128 v[56:59], v213 offset:24576
	v_exp_f32_e32 v128, v60
	v_exp_f32_e32 v129, v61
	v_exp_f32_e32 v130, v62
	v_exp_f32_e32 v131, v63
	v_mfma_f32_32x32x16_bf16 v[112:127], v[136:139], v[168:171], v[112:127]
	ds_read_b128 v[60:63], v236 offset:16384
	v_exp_f32_e32 v132, v32
	v_exp_f32_e32 v133, v33
	v_exp_f32_e32 v134, v34
	v_exp_f32_e32 v135, v35
	v_mfma_f32_32x32x16_bf16 v[96:111], v[48:51], v[168:171], v[96:111]
	ds_read_b128 v[32:35], v236 offset:20480
	v_exp_f32_e32 v136, v36
	v_exp_f32_e32 v137, v37
	v_exp_f32_e32 v138, v38
	v_exp_f32_e32 v139, v39
	s_waitcnt lgkmcnt(0)
	v_mfma_f32_32x32x16_bf16 v[112:127], v[52:55], v[172:175], v[112:127]
	ds_read_b128 v[36:39], v236 offset:24576
	v_exp_f32_e32 v152, v40
	v_exp_f32_e32 v153, v41
	v_exp_f32_e32 v154, v42
	v_exp_f32_e32 v155, v43
	v_mfma_f32_32x32x16_bf16 v[96:111], v[56:59], v[172:175], v[96:111]
	ds_read_b128 v[40:43], v236 offset:28672
	v_exp_f32_e32 v156, v44
	v_exp_f32_e32 v157, v45
	v_exp_f32_e32 v158, v46
	v_exp_f32_e32 v159, v47
	v_cvt_pk_bf16_f32 v44, v140, v141
	v_cvt_pk_bf16_f32 v45, v142, v143
	v_cvt_pk_bf16_f32 v46, v144, v145
	v_cvt_pk_bf16_f32 v47, v146, v147
	s_nop 1
	v_mfma_f32_32x32x16_bf16 v[80:95], v[60:63], v[44:47], v[80:95]
	ds_read_b128 v[48:51], v237 offset:16384
	v_cvt_pk_bf16_f32 v52, v148, v149
	v_cvt_pk_bf16_f32 v53, v150, v151
	v_cvt_pk_bf16_f32 v54, v128, v129
	v_cvt_pk_bf16_f32 v55, v130, v131
	v_mfma_f32_32x32x16_bf16 v[64:79], v[32:35], v[44:47], v[64:79]
	ds_read_b128 v[56:59], v237 offset:20480
	v_pk_add_f32 v[62:63], v[146:147], v[142:143]
	v_pk_add_f32 v[60:61], v[144:145], v[140:141]
	s_waitcnt lgkmcnt(0)
	v_mfma_f32_32x32x16_bf16 v[16:31], v[36:39], v[44:47], v[16:31]
	ds_read_b128 v[32:35], v237 offset:24576
	v_add_f32_e64 v62, v150, v62
	v_add_f32_e64 v63, v151, v63
	v_add_f32_e64 v60, v148, v60
	v_add_f32_e64 v61, v149, v61
	v_pk_add_f32 v[62:63], v[130:131], v[62:63]
	v_pk_add_f32 v[60:61], v[128:129], v[60:61]
	v_mfma_f32_32x32x16_bf16 v[0:15], v[40:43], v[44:47], v[0:15]
	ds_read_b128 v[36:39], v237 offset:28672
	v_mfma_f32_32x32x16_bf16 v[80:95], v[48:51], v[52:55], v[80:95]
	ds_read_b128 v[40:43], v238 offset:16384
	v_cvt_pk_bf16_f32 v44, v132, v133
	v_cvt_pk_bf16_f32 v45, v134, v135
	v_cvt_pk_bf16_f32 v46, v136, v137
	v_cvt_pk_bf16_f32 v47, v138, v139
	v_mfma_f32_32x32x16_bf16 v[64:79], v[56:59], v[52:55], v[64:79]
	ds_read_b128 v[48:51], v238 offset:20480
	v_add_f32_e64 v62, v134, v62
	v_add_f32_e64 v63, v135, v63
	v_add_f32_e64 v60, v132, v60
	v_add_f32_e64 v61, v133, v61
	v_pk_add_f32 v[62:63], v[138:139], v[62:63]
	v_pk_add_f32 v[60:61], v[136:137], v[60:61]
	s_waitcnt lgkmcnt(0)
	v_mfma_f32_32x32x16_bf16 v[16:31], v[32:35], v[52:55], v[16:31]
	ds_read_b128 v[56:59], v238 offset:24576
	v_add_f32_e64 v62, v154, v62
	v_add_f32_e64 v63, v155, v63
	v_add_f32_e64 v60, v152, v60
	v_add_f32_e64 v61, v153, v61
	v_pk_add_f32 v[130:131], v[158:159], v[62:63]
	v_pk_add_f32 v[128:129], v[156:157], v[60:61]
	v_mfma_f32_32x32x16_bf16 v[0:15], v[36:39], v[52:55], v[0:15]
	ds_read_b128 v[32:35], v238 offset:28672
	v_mfma_f32_32x32x16_bf16 v[80:95], v[40:43], v[44:47], v[80:95]
	ds_read_b128 v[36:39], v239 offset:16384
	v_cvt_pk_bf16_f32 v52, v152, v153
	v_cvt_pk_bf16_f32 v53, v154, v155
	v_cvt_pk_bf16_f32 v54, v156, v157
	v_cvt_pk_bf16_f32 v55, v158, v159
	v_mfma_f32_32x32x16_bf16 v[64:79], v[48:51], v[44:47], v[64:79]
	ds_read_b128 v[40:43], v239 offset:20480
	s_waitcnt lgkmcnt(0)
	v_mfma_f32_32x32x16_bf16 v[16:31], v[56:59], v[44:47], v[16:31]
	ds_read_b128 v[48:51], v239 offset:24576
	v_mfma_f32_32x32x16_bf16 v[0:15], v[32:35], v[44:47], v[0:15]
	ds_read_b128 v[56:59], v239 offset:28672
	v_mfma_f32_32x32x16_bf16 v[80:95], v[36:39], v[52:55], v[80:95]
	v_mfma_f32_32x32x16_bf16 v[64:79], v[40:43], v[52:55], v[64:79]
	s_waitcnt lgkmcnt(0)
	v_mfma_f32_32x32x16_bf16 v[16:31], v[48:51], v[52:55], v[16:31]
	v_mfma_f32_32x32x16_bf16 v[0:15], v[56:59], v[52:55], v[0:15]
	s_waitcnt vmcnt(4) lgkmcnt(0)
	s_barrier
	s_add_u32 s68, s98, 0x18000
	s_addc_u32 s69, s99, 0
	s_add_i32 s49, 0x4000, s57
	s_mov_b32 m0, s49
	s_nop 0
	global_load_lds_dwordx4 v198, s[68:69]
	s_add_i32 m0, s49, 0x400
	s_nop 0
	global_load_lds_dwordx4 v194, s[68:69]
	s_add_u32 s44, s100, 0x80
	s_addc_u32 s45, s101, 0
	s_add_i32 s49, s58, 0x4000
	s_add_i32 m0, s49, 0xc000
	s_nop 0
	global_load_lds_dwordx4 v196, s[44:45]
	s_add_i32 m0, s49, 0xc400
	s_nop 0
	global_load_lds_dwordx4 v192, s[44:45]
	v_exp_f32_e32 v144, v112
	ds_read_b128 v[32:35], v205 offset:32768
	ds_read_b128 v[36:39], v205 offset:40960
	s_waitcnt lgkmcnt(0)
	v_mfma_f32_32x32x16_bf16 v[48:63], v[32:35], v[160:163], 0
	ds_read_b128 v[132:135], v211 offset:32768
	ds_read_b128 v[136:139], v211 offset:40960
	ds_read_b128 v[140:143], v212 offset:32768
	v_exp_f32_e32 v145, v113
	v_exp_f32_e32 v146, v114
	v_exp_f32_e32 v147, v115
	ds_read_b128 v[112:115], v212 offset:40960
	v_mfma_f32_32x32x16_bf16 v[32:47], v[36:39], v[160:163], 0
	v_exp_f32_e32 v148, v116
	v_exp_f32_e32 v149, v117
	v_exp_f32_e32 v150, v118
	v_exp_f32_e32 v151, v119
	s_waitcnt lgkmcnt(0)
	v_mfma_f32_32x32x16_bf16 v[48:63], v[132:135], v[164:167], v[48:63]
	ds_read_b128 v[116:119], v213 offset:32768
	v_exp_f32_e32 v152, v120
	v_exp_f32_e32 v153, v121
	v_exp_f32_e32 v154, v122
	v_exp_f32_e32 v155, v123
	v_mfma_f32_32x32x16_bf16 v[32:47], v[136:139], v[164:167], v[32:47]
	ds_read_b128 v[120:123], v213 offset:40960
	v_exp_f32_e32 v156, v124
	v_exp_f32_e32 v157, v125
	v_exp_f32_e32 v158, v126
	v_exp_f32_e32 v159, v127
	v_mfma_f32_32x32x16_bf16 v[48:63], v[140:143], v[168:171], v[48:63]
	ds_read_b128 v[124:127], v236 offset:32768
	v_exp_f32_e32 v136, v96
	v_exp_f32_e32 v137, v97
	v_exp_f32_e32 v138, v98
	v_exp_f32_e32 v139, v99
	v_mfma_f32_32x32x16_bf16 v[32:47], v[112:115], v[168:171], v[32:47]
	ds_read_b128 v[96:99], v236 offset:36864
	v_exp_f32_e32 v140, v100
	v_exp_f32_e32 v141, v101
	v_exp_f32_e32 v142, v102
	v_exp_f32_e32 v143, v103
	s_waitcnt lgkmcnt(0)
	v_mfma_f32_32x32x16_bf16 v[48:63], v[116:119], v[172:175], v[48:63]
	ds_read_b128 v[100:103], v236 offset:40960
	v_exp_f32_e32 v178, v104
	v_exp_f32_e32 v179, v105
	v_exp_f32_e32 v180, v106
	v_exp_f32_e32 v181, v107
	v_mfma_f32_32x32x16_bf16 v[32:47], v[120:123], v[172:175], v[32:47]
	ds_read_b128 v[104:107], v236 offset:45056
	v_exp_f32_e32 v182, v108
	v_exp_f32_e32 v183, v109
	v_exp_f32_e32 v184, v110
	v_exp_f32_e32 v185, v111
	v_cvt_pk_bf16_f32 v108, v144, v145
	v_cvt_pk_bf16_f32 v109, v146, v147
	v_cvt_pk_bf16_f32 v110, v148, v149
	v_cvt_pk_bf16_f32 v111, v150, v151
	s_nop 1
	v_mfma_f32_32x32x16_bf16 v[80:95], v[124:127], v[108:111], v[80:95]
	ds_read_b128 v[112:115], v237 offset:32768
	v_cvt_pk_bf16_f32 v116, v152, v153
	v_cvt_pk_bf16_f32 v117, v154, v155
	v_cvt_pk_bf16_f32 v118, v156, v157
	v_cvt_pk_bf16_f32 v119, v158, v159
	v_mfma_f32_32x32x16_bf16 v[64:79], v[96:99], v[108:111], v[64:79]
	ds_read_b128 v[120:123], v237 offset:36864
	v_pk_add_f32 v[126:127], v[150:151], v[146:147]
	v_pk_add_f32 v[124:125], v[148:149], v[144:145]
	s_waitcnt lgkmcnt(0)
	v_mfma_f32_32x32x16_bf16 v[16:31], v[100:103], v[108:111], v[16:31]
	ds_read_b128 v[132:135], v237 offset:40960
	v_add_f32_e64 v98, v154, v126
	v_add_f32_e64 v99, v155, v127
	v_add_f32_e64 v96, v152, v124
	v_add_f32_e64 v97, v153, v125
	v_pk_add_f32 v[98:99], v[158:159], v[98:99]
	v_pk_add_f32 v[96:97], v[156:157], v[96:97]
	v_mfma_f32_32x32x16_bf16 v[0:15], v[104:107], v[108:111], v[0:15]
	ds_read_b128 v[100:103], v237 offset:45056
	v_mfma_f32_32x32x16_bf16 v[80:95], v[112:115], v[116:119], v[80:95]
	ds_read_b128 v[104:107], v238 offset:32768
	v_cvt_pk_bf16_f32 v108, v136, v137
	v_cvt_pk_bf16_f32 v109, v138, v139
	v_cvt_pk_bf16_f32 v110, v140, v141
	v_cvt_pk_bf16_f32 v111, v142, v143
	v_mfma_f32_32x32x16_bf16 v[64:79], v[120:123], v[116:119], v[64:79]
	ds_read_b128 v[112:115], v238 offset:36864
	v_add_f32_e64 v98, v138, v98
	v_add_f32_e64 v99, v139, v99
	v_add_f32_e64 v96, v136, v96
	v_add_f32_e64 v97, v137, v97
	v_pk_add_f32 v[98:99], v[142:143], v[98:99]
	v_pk_add_f32 v[96:97], v[140:141], v[96:97]
	s_waitcnt lgkmcnt(0)
	v_mfma_f32_32x32x16_bf16 v[16:31], v[132:135], v[116:119], v[16:31]
	ds_read_b128 v[120:123], v238 offset:40960
	v_add_f32_e64 v98, v180, v98
	v_add_f32_e64 v99, v181, v99
	v_add_f32_e64 v96, v178, v96
	v_add_f32_e64 v97, v179, v97
	v_pk_add_f32 v[98:99], v[184:185], v[98:99]
	v_pk_add_f32 v[96:97], v[182:183], v[96:97]
	v_mfma_f32_32x32x16_bf16 v[0:15], v[100:103], v[116:119], v[0:15]
	ds_read_b128 v[124:127], v238 offset:45056
	v_mfma_f32_32x32x16_bf16 v[80:95], v[104:107], v[108:111], v[80:95]
	ds_read_b128 v[100:103], v239 offset:32768
	v_cvt_pk_bf16_f32 v116, v178, v179
	v_cvt_pk_bf16_f32 v117, v180, v181
	v_cvt_pk_bf16_f32 v118, v182, v183
	v_cvt_pk_bf16_f32 v119, v184, v185
	v_mfma_f32_32x32x16_bf16 v[64:79], v[112:115], v[108:111], v[64:79]
	ds_read_b128 v[104:107], v239 offset:36864
	s_waitcnt lgkmcnt(0)
	v_mfma_f32_32x32x16_bf16 v[16:31], v[120:123], v[108:111], v[16:31]
	ds_read_b128 v[112:115], v239 offset:40960
	v_mfma_f32_32x32x16_bf16 v[0:15], v[124:127], v[108:111], v[0:15]
	ds_read_b128 v[120:123], v239 offset:45056
	v_mfma_f32_32x32x16_bf16 v[80:95], v[100:103], v[116:119], v[80:95]
	v_mfma_f32_32x32x16_bf16 v[64:79], v[104:107], v[116:119], v[64:79]
	s_waitcnt lgkmcnt(0)
	v_mfma_f32_32x32x16_bf16 v[16:31], v[112:115], v[116:119], v[16:31]
	v_mfma_f32_32x32x16_bf16 v[0:15], v[120:123], v[116:119], v[0:15]
	s_waitcnt vmcnt(4) lgkmcnt(0)
	v_add_f32_e32 v100, v128, v129
	v_add_f32_e32 v101, v130, v131
	v_add_f32_e32 v100, v100, v101
	v_add_f32_e32 v96, v96, v97
	v_add_f32_e32 v97, v98, v99
	s_barrier
	v_add_f32_e32 v100, v177, v100
	v_add_f32_e32 v96, v96, v97
	v_add_f32_e32 v177, v100, v96
	s_add_i32 s21, s21, 2
	s_addk_i32 s15, 0x80
	s_add_i32 s20, s20, 0x8000
	s_add_u32 s98, s98, 0x30000
	s_addc_u32 s99, s99, 0
	s_add_u32 s100, s100, 0x100
	s_addc_u32 s101, s101, 0
	s_add_i32 s46, s58, 0x8000
	s_mov_b32 m0, s46
	s_nop 0
	global_load_lds_dwordx4 v198, s[98:99]
	s_add_i32 m0, s46, 0x400
	s_nop 0
	global_load_lds_dwordx4 v194, s[98:99]
	s_add_i32 s48, s20, 0xffffc000
	s_add_i32 s48, s58, 0x8000
	s_add_i32 m0, s48, 0xc000
	s_nop 0
	global_load_lds_dwordx4 v196, s[100:101]
	s_add_i32 m0, s48, 0xc400
	s_nop 0
	global_load_lds_dwordx4 v192, s[100:101]
	s_add_i32 s46, s20, 0xffff4000
	ds_read_b128 v[96:99], v205
	ds_read_b128 v[100:103], v205 offset:8192
	s_waitcnt lgkmcnt(0)
	v_mfma_f32_32x32x16_bf16 v[112:127], v[96:99], v[160:163], 0
	ds_read_b128 v[128:131], v211
	ds_read_b128 v[132:135], v211 offset:8192
	ds_read_b128 v[136:139], v212
	v_exp_f32_e32 v140, v48
	v_exp_f32_e32 v141, v49
	v_exp_f32_e32 v142, v50
	v_exp_f32_e32 v143, v51
	ds_read_b128 v[48:51], v212 offset:8192
	v_mfma_f32_32x32x16_bf16 v[96:111], v[100:103], v[160:163], 0
	v_exp_f32_e32 v144, v52
	v_exp_f32_e32 v145, v53
	v_exp_f32_e32 v146, v54
	v_exp_f32_e32 v147, v55
	s_waitcnt lgkmcnt(0)
	v_mfma_f32_32x32x16_bf16 v[112:127], v[128:131], v[164:167], v[112:127]
	ds_read_b128 v[52:55], v213
	v_exp_f32_e32 v148, v56
	v_exp_f32_e32 v149, v57
	v_exp_f32_e32 v150, v58
	v_exp_f32_e32 v151, v59
	v_mfma_f32_32x32x16_bf16 v[96:111], v[132:135], v[164:167], v[96:111]
	ds_read_b128 v[56:59], v213 offset:8192
	v_exp_f32_e32 v128, v60
	v_exp_f32_e32 v129, v61
	v_exp_f32_e32 v130, v62
	v_exp_f32_e32 v131, v63
	v_mfma_f32_32x32x16_bf16 v[112:127], v[136:139], v[168:171], v[112:127]
	ds_read_b128 v[60:63], v206 offset:49152
	v_exp_f32_e32 v132, v32
	v_exp_f32_e32 v133, v33
	v_exp_f32_e32 v134, v34
	v_exp_f32_e32 v135, v35
	v_mfma_f32_32x32x16_bf16 v[96:111], v[48:51], v[168:171], v[96:111]
	ds_read_b128 v[32:35], v206 offset:53248
	v_exp_f32_e32 v136, v36
	v_exp_f32_e32 v137, v37
	v_exp_f32_e32 v138, v38
	v_exp_f32_e32 v139, v39
	s_waitcnt lgkmcnt(0)
	v_mfma_f32_32x32x16_bf16 v[112:127], v[52:55], v[172:175], v[112:127]
	ds_read_b128 v[36:39], v206 offset:57344
	v_exp_f32_e32 v152, v40
	v_exp_f32_e32 v153, v41
	v_exp_f32_e32 v154, v42
	v_exp_f32_e32 v155, v43
	v_mfma_f32_32x32x16_bf16 v[96:111], v[56:59], v[172:175], v[96:111]
	ds_read_b128 v[40:43], v206 offset:61440
	v_exp_f32_e32 v156, v44
	v_exp_f32_e32 v157, v45
	v_exp_f32_e32 v158, v46
	v_exp_f32_e32 v159, v47
	v_cvt_pk_bf16_f32 v44, v140, v141
	v_cvt_pk_bf16_f32 v45, v142, v143
	v_cvt_pk_bf16_f32 v46, v144, v145
	v_cvt_pk_bf16_f32 v47, v146, v147
	s_nop 1
	v_mfma_f32_32x32x16_bf16 v[80:95], v[60:63], v[44:47], v[80:95]
	ds_read_b128 v[48:51], v207 offset:49152
	v_cvt_pk_bf16_f32 v52, v148, v149
	v_cvt_pk_bf16_f32 v53, v150, v151
	v_cvt_pk_bf16_f32 v54, v128, v129
	v_cvt_pk_bf16_f32 v55, v130, v131
	v_mfma_f32_32x32x16_bf16 v[64:79], v[32:35], v[44:47], v[64:79]
	ds_read_b128 v[56:59], v207 offset:53248
	v_pk_add_f32 v[62:63], v[146:147], v[142:143]
	v_pk_add_f32 v[60:61], v[144:145], v[140:141]
	s_waitcnt lgkmcnt(0)
	v_mfma_f32_32x32x16_bf16 v[16:31], v[36:39], v[44:47], v[16:31]
	ds_read_b128 v[32:35], v207 offset:57344
	v_add_f32_e64 v62, v150, v62
	v_add_f32_e64 v63, v151, v63
	v_add_f32_e64 v60, v148, v60
	v_add_f32_e64 v61, v149, v61
	v_pk_add_f32 v[62:63], v[130:131], v[62:63]
	v_pk_add_f32 v[60:61], v[128:129], v[60:61]
	v_mfma_f32_32x32x16_bf16 v[0:15], v[40:43], v[44:47], v[0:15]
	ds_read_b128 v[36:39], v207 offset:61440
	v_mfma_f32_32x32x16_bf16 v[80:95], v[48:51], v[52:55], v[80:95]
	ds_read_b128 v[40:43], v208 offset:49152
	v_cvt_pk_bf16_f32 v44, v132, v133
	v_cvt_pk_bf16_f32 v45, v134, v135
	v_cvt_pk_bf16_f32 v46, v136, v137
	v_cvt_pk_bf16_f32 v47, v138, v139
	v_mfma_f32_32x32x16_bf16 v[64:79], v[56:59], v[52:55], v[64:79]
	ds_read_b128 v[48:51], v208 offset:53248
	v_add_f32_e64 v62, v134, v62
	v_add_f32_e64 v63, v135, v63
	v_add_f32_e64 v60, v132, v60
	v_add_f32_e64 v61, v133, v61
	v_pk_add_f32 v[62:63], v[138:139], v[62:63]
	v_pk_add_f32 v[60:61], v[136:137], v[60:61]
	s_waitcnt lgkmcnt(0)
	v_mfma_f32_32x32x16_bf16 v[16:31], v[32:35], v[52:55], v[16:31]
	ds_read_b128 v[56:59], v208 offset:57344
	v_add_f32_e64 v62, v154, v62
	v_add_f32_e64 v63, v155, v63
	v_add_f32_e64 v60, v152, v60
	v_add_f32_e64 v61, v153, v61
	v_pk_add_f32 v[130:131], v[158:159], v[62:63]
	v_pk_add_f32 v[128:129], v[156:157], v[60:61]
	v_mfma_f32_32x32x16_bf16 v[0:15], v[36:39], v[52:55], v[0:15]
	ds_read_b128 v[32:35], v208 offset:61440
	v_mfma_f32_32x32x16_bf16 v[80:95], v[40:43], v[44:47], v[80:95]
	ds_read_b128 v[36:39], v209 offset:49152
	v_cvt_pk_bf16_f32 v52, v152, v153
	v_cvt_pk_bf16_f32 v53, v154, v155
	v_cvt_pk_bf16_f32 v54, v156, v157
	v_cvt_pk_bf16_f32 v55, v158, v159
	v_mfma_f32_32x32x16_bf16 v[64:79], v[48:51], v[44:47], v[64:79]
	ds_read_b128 v[40:43], v209 offset:53248
	s_waitcnt lgkmcnt(0)
	v_mfma_f32_32x32x16_bf16 v[16:31], v[56:59], v[44:47], v[16:31]
	ds_read_b128 v[48:51], v209 offset:57344
	v_mfma_f32_32x32x16_bf16 v[0:15], v[32:35], v[44:47], v[0:15]
	ds_read_b128 v[56:59], v209 offset:61440
	v_mfma_f32_32x32x16_bf16 v[80:95], v[36:39], v[52:55], v[80:95]
	v_mfma_f32_32x32x16_bf16 v[64:79], v[40:43], v[52:55], v[64:79]
	s_waitcnt lgkmcnt(0)
	v_mfma_f32_32x32x16_bf16 v[16:31], v[48:51], v[52:55], v[16:31]
	v_mfma_f32_32x32x16_bf16 v[0:15], v[56:59], v[52:55], v[0:15]
	s_waitcnt vmcnt(4) lgkmcnt(0)
	s_barrier
	s_add_u32 s68, s98, 0x18000
	s_addc_u32 s69, s99, 0
	s_add_i32 s49, 0, s57
	s_mov_b32 m0, s49
	s_nop 0
	global_load_lds_dwordx4 v198, s[68:69]
	s_add_i32 m0, s49, 0x400
	s_nop 0
	global_load_lds_dwordx4 v194, s[68:69]
	s_add_u32 s44, s100, 0x80
	s_addc_u32 s45, s101, 0
	s_add_i32 s49, s58, 0xc000
	s_add_i32 m0, s49, 0xc000
	s_nop 0
	global_load_lds_dwordx4 v196, s[44:45]
	s_add_i32 m0, s49, 0xc400
	s_nop 0
	global_load_lds_dwordx4 v192, s[44:45]
	v_exp_f32_e32 v144, v112
	ds_read_b128 v[32:35], v205 offset:16384
	ds_read_b128 v[36:39], v205 offset:24576
	s_waitcnt lgkmcnt(0)
	v_mfma_f32_32x32x16_bf16 v[48:63], v[32:35], v[160:163], 0
	ds_read_b128 v[132:135], v211 offset:16384
	ds_read_b128 v[136:139], v211 offset:24576
	ds_read_b128 v[140:143], v212 offset:16384
	v_exp_f32_e32 v145, v113
	v_exp_f32_e32 v146, v114
	v_exp_f32_e32 v147, v115
	ds_read_b128 v[112:115], v212 offset:24576
	v_mfma_f32_32x32x16_bf16 v[32:47], v[36:39], v[160:163], 0
	v_exp_f32_e32 v148, v116
	v_exp_f32_e32 v149, v117
	v_exp_f32_e32 v150, v118
	v_exp_f32_e32 v151, v119
	s_waitcnt lgkmcnt(0)
	v_mfma_f32_32x32x16_bf16 v[48:63], v[132:135], v[164:167], v[48:63]
	ds_read_b128 v[116:119], v213 offset:16384
	v_exp_f32_e32 v152, v120
	v_exp_f32_e32 v153, v121
	v_exp_f32_e32 v154, v122
	v_exp_f32_e32 v155, v123
	v_mfma_f32_32x32x16_bf16 v[32:47], v[136:139], v[164:167], v[32:47]
	ds_read_b128 v[120:123], v213 offset:24576
	v_exp_f32_e32 v156, v124
	v_exp_f32_e32 v157, v125
	v_exp_f32_e32 v158, v126
	v_exp_f32_e32 v159, v127
	v_mfma_f32_32x32x16_bf16 v[48:63], v[140:143], v[168:171], v[48:63]
	ds_read_b128 v[124:127], v236
	v_exp_f32_e32 v136, v96
	v_exp_f32_e32 v137, v97
	v_exp_f32_e32 v138, v98
	v_exp_f32_e32 v139, v99
	v_mfma_f32_32x32x16_bf16 v[32:47], v[112:115], v[168:171], v[32:47]
	ds_read_b128 v[96:99], v236 offset:4096
	v_exp_f32_e32 v140, v100
	v_exp_f32_e32 v141, v101
	v_exp_f32_e32 v142, v102
	v_exp_f32_e32 v143, v103
	s_waitcnt lgkmcnt(0)
	v_mfma_f32_32x32x16_bf16 v[48:63], v[116:119], v[172:175], v[48:63]
	ds_read_b128 v[100:103], v236 offset:8192
	v_exp_f32_e32 v178, v104
	v_exp_f32_e32 v179, v105
	v_exp_f32_e32 v180, v106
	v_exp_f32_e32 v181, v107
	v_mfma_f32_32x32x16_bf16 v[32:47], v[120:123], v[172:175], v[32:47]
	ds_read_b128 v[104:107], v236 offset:12288
	v_exp_f32_e32 v182, v108
	v_exp_f32_e32 v183, v109
	v_exp_f32_e32 v184, v110
	v_exp_f32_e32 v185, v111
	v_cvt_pk_bf16_f32 v108, v144, v145
	v_cvt_pk_bf16_f32 v109, v146, v147
	v_cvt_pk_bf16_f32 v110, v148, v149
	v_cvt_pk_bf16_f32 v111, v150, v151
	s_nop 1
	v_mfma_f32_32x32x16_bf16 v[80:95], v[124:127], v[108:111], v[80:95]
	ds_read_b128 v[112:115], v237
	v_cvt_pk_bf16_f32 v116, v152, v153
	v_cvt_pk_bf16_f32 v117, v154, v155
	v_cvt_pk_bf16_f32 v118, v156, v157
	v_cvt_pk_bf16_f32 v119, v158, v159
	v_mfma_f32_32x32x16_bf16 v[64:79], v[96:99], v[108:111], v[64:79]
	ds_read_b128 v[120:123], v237 offset:4096
	v_pk_add_f32 v[126:127], v[150:151], v[146:147]
	v_pk_add_f32 v[124:125], v[148:149], v[144:145]
	s_waitcnt lgkmcnt(0)
	v_mfma_f32_32x32x16_bf16 v[16:31], v[100:103], v[108:111], v[16:31]
	ds_read_b128 v[132:135], v237 offset:8192
	v_add_f32_e64 v98, v154, v126
	v_add_f32_e64 v99, v155, v127
	v_add_f32_e64 v96, v152, v124
	v_add_f32_e64 v97, v153, v125
	v_pk_add_f32 v[98:99], v[158:159], v[98:99]
	v_pk_add_f32 v[96:97], v[156:157], v[96:97]
	v_mfma_f32_32x32x16_bf16 v[0:15], v[104:107], v[108:111], v[0:15]
	ds_read_b128 v[100:103], v237 offset:12288
	v_mfma_f32_32x32x16_bf16 v[80:95], v[112:115], v[116:119], v[80:95]
	ds_read_b128 v[104:107], v238
	v_cvt_pk_bf16_f32 v108, v136, v137
	v_cvt_pk_bf16_f32 v109, v138, v139
	v_cvt_pk_bf16_f32 v110, v140, v141
	v_cvt_pk_bf16_f32 v111, v142, v143
	v_mfma_f32_32x32x16_bf16 v[64:79], v[120:123], v[116:119], v[64:79]
	ds_read_b128 v[112:115], v238 offset:4096
	v_add_f32_e64 v98, v138, v98
	v_add_f32_e64 v99, v139, v99
	v_add_f32_e64 v96, v136, v96
	v_add_f32_e64 v97, v137, v97
	v_pk_add_f32 v[98:99], v[142:143], v[98:99]
	v_pk_add_f32 v[96:97], v[140:141], v[96:97]
	s_waitcnt lgkmcnt(0)
	v_mfma_f32_32x32x16_bf16 v[16:31], v[132:135], v[116:119], v[16:31]
	ds_read_b128 v[120:123], v238 offset:8192
	v_add_f32_e64 v98, v180, v98
	v_add_f32_e64 v99, v181, v99
	v_add_f32_e64 v96, v178, v96
	v_add_f32_e64 v97, v179, v97
	v_pk_add_f32 v[98:99], v[184:185], v[98:99]
	v_pk_add_f32 v[96:97], v[182:183], v[96:97]
	v_mfma_f32_32x32x16_bf16 v[0:15], v[100:103], v[116:119], v[0:15]
	ds_read_b128 v[124:127], v238 offset:12288
	v_mfma_f32_32x32x16_bf16 v[80:95], v[104:107], v[108:111], v[80:95]
	ds_read_b128 v[100:103], v239
	v_cvt_pk_bf16_f32 v116, v178, v179
	v_cvt_pk_bf16_f32 v117, v180, v181
	v_cvt_pk_bf16_f32 v118, v182, v183
	v_cvt_pk_bf16_f32 v119, v184, v185
	v_mfma_f32_32x32x16_bf16 v[64:79], v[112:115], v[108:111], v[64:79]
	ds_read_b128 v[104:107], v239 offset:4096
	s_waitcnt lgkmcnt(0)
	v_mfma_f32_32x32x16_bf16 v[16:31], v[120:123], v[108:111], v[16:31]
	ds_read_b128 v[112:115], v239 offset:8192
	v_mfma_f32_32x32x16_bf16 v[0:15], v[124:127], v[108:111], v[0:15]
	ds_read_b128 v[120:123], v239 offset:12288
	v_mfma_f32_32x32x16_bf16 v[80:95], v[100:103], v[116:119], v[80:95]
	v_mfma_f32_32x32x16_bf16 v[64:79], v[104:107], v[116:119], v[64:79]
	s_waitcnt lgkmcnt(0)
	v_mfma_f32_32x32x16_bf16 v[16:31], v[112:115], v[116:119], v[16:31]
	v_mfma_f32_32x32x16_bf16 v[0:15], v[120:123], v[116:119], v[0:15]
	s_waitcnt vmcnt(4) lgkmcnt(0)
	v_add_f32_e32 v100, v128, v129
	v_add_f32_e32 v101, v130, v131
	v_add_f32_e32 v100, v100, v101
	v_add_f32_e32 v96, v96, v97
	v_add_f32_e32 v97, v98, v99
	s_barrier
	v_add_f32_e32 v100, v177, v100
	v_add_f32_e32 v96, v96, v97
	v_add_f32_e32 v177, v100, v96
	s_add_i32 s21, s21, 2
	s_addk_i32 s15, 0x80
	s_add_i32 s20, s20, 0x8000
	s_add_u32 s98, s98, 0x30000
	s_addc_u32 s99, s99, 0
	s_add_u32 s100, s100, 0x100
	s_addc_u32 s101, s101, 0
	s_add_i32 s46, s58, 0x4000
	s_mov_b32 m0, s46
	s_nop 0
	global_load_lds_dwordx4 v198, s[98:99]
	s_add_i32 m0, s46, 0x400
	s_nop 0
	global_load_lds_dwordx4 v194, s[98:99]
	s_add_i32 s48, s20, 0xffffc000
	s_add_i32 s48, s58, 0
	s_add_i32 m0, s48, 0xc000
	s_nop 0
	global_load_lds_dwordx4 v196, s[100:101]
	s_add_i32 m0, s48, 0xc400
	s_nop 0
	global_load_lds_dwordx4 v192, s[100:101]
	s_add_i32 s46, s20, 0xffff4000
	ds_read_b128 v[96:99], v205 offset:32768
	ds_read_b128 v[100:103], v205 offset:40960
	s_waitcnt lgkmcnt(0)
	v_mfma_f32_32x32x16_bf16 v[112:127], v[96:99], v[160:163], 0
	ds_read_b128 v[128:131], v211 offset:32768
	ds_read_b128 v[132:135], v211 offset:40960
	ds_read_b128 v[136:139], v212 offset:32768
	v_exp_f32_e32 v140, v48
	v_exp_f32_e32 v141, v49
	v_exp_f32_e32 v142, v50
	v_exp_f32_e32 v143, v51
	ds_read_b128 v[48:51], v212 offset:40960
	v_mfma_f32_32x32x16_bf16 v[96:111], v[100:103], v[160:163], 0
	v_exp_f32_e32 v144, v52
	v_exp_f32_e32 v145, v53
	v_exp_f32_e32 v146, v54
	v_exp_f32_e32 v147, v55
	s_waitcnt lgkmcnt(0)
	v_mfma_f32_32x32x16_bf16 v[112:127], v[128:131], v[164:167], v[112:127]
	ds_read_b128 v[52:55], v213 offset:32768
	v_exp_f32_e32 v148, v56
	v_exp_f32_e32 v149, v57
	v_exp_f32_e32 v150, v58
	v_exp_f32_e32 v151, v59
	v_mfma_f32_32x32x16_bf16 v[96:111], v[132:135], v[164:167], v[96:111]
	ds_read_b128 v[56:59], v213 offset:40960
	v_exp_f32_e32 v128, v60
	v_exp_f32_e32 v129, v61
	v_exp_f32_e32 v130, v62
	v_exp_f32_e32 v131, v63
	v_mfma_f32_32x32x16_bf16 v[112:127], v[136:139], v[168:171], v[112:127]
	ds_read_b128 v[60:63], v236 offset:16384
	v_exp_f32_e32 v132, v32
	v_exp_f32_e32 v133, v33
	v_exp_f32_e32 v134, v34
	v_exp_f32_e32 v135, v35
	v_mfma_f32_32x32x16_bf16 v[96:111], v[48:51], v[168:171], v[96:111]
	ds_read_b128 v[32:35], v236 offset:20480
	v_exp_f32_e32 v136, v36
	v_exp_f32_e32 v137, v37
	v_exp_f32_e32 v138, v38
	v_exp_f32_e32 v139, v39
	s_waitcnt lgkmcnt(0)
	v_mfma_f32_32x32x16_bf16 v[112:127], v[52:55], v[172:175], v[112:127]
	ds_read_b128 v[36:39], v236 offset:24576
	v_exp_f32_e32 v152, v40
	v_exp_f32_e32 v153, v41
	v_exp_f32_e32 v154, v42
	v_exp_f32_e32 v155, v43
	v_mfma_f32_32x32x16_bf16 v[96:111], v[56:59], v[172:175], v[96:111]
	ds_read_b128 v[40:43], v236 offset:28672
	v_exp_f32_e32 v156, v44
	v_exp_f32_e32 v157, v45
	v_exp_f32_e32 v158, v46
	v_exp_f32_e32 v159, v47
	v_cvt_pk_bf16_f32 v44, v140, v141
	v_cvt_pk_bf16_f32 v45, v142, v143
	v_cvt_pk_bf16_f32 v46, v144, v145
	v_cvt_pk_bf16_f32 v47, v146, v147
	s_nop 1
	v_mfma_f32_32x32x16_bf16 v[80:95], v[60:63], v[44:47], v[80:95]
	ds_read_b128 v[48:51], v237 offset:16384
	v_cvt_pk_bf16_f32 v52, v148, v149
	v_cvt_pk_bf16_f32 v53, v150, v151
	v_cvt_pk_bf16_f32 v54, v128, v129
	v_cvt_pk_bf16_f32 v55, v130, v131
	v_mfma_f32_32x32x16_bf16 v[64:79], v[32:35], v[44:47], v[64:79]
	ds_read_b128 v[56:59], v237 offset:20480
	v_pk_add_f32 v[62:63], v[146:147], v[142:143]
	v_pk_add_f32 v[60:61], v[144:145], v[140:141]
	s_waitcnt lgkmcnt(0)
	v_mfma_f32_32x32x16_bf16 v[16:31], v[36:39], v[44:47], v[16:31]
	ds_read_b128 v[32:35], v237 offset:24576
	v_add_f32_e64 v62, v150, v62
	v_add_f32_e64 v63, v151, v63
	v_add_f32_e64 v60, v148, v60
	v_add_f32_e64 v61, v149, v61
	v_pk_add_f32 v[62:63], v[130:131], v[62:63]
	v_pk_add_f32 v[60:61], v[128:129], v[60:61]
	v_mfma_f32_32x32x16_bf16 v[0:15], v[40:43], v[44:47], v[0:15]
	ds_read_b128 v[36:39], v237 offset:28672
	v_mfma_f32_32x32x16_bf16 v[80:95], v[48:51], v[52:55], v[80:95]
	ds_read_b128 v[40:43], v238 offset:16384
	v_cvt_pk_bf16_f32 v44, v132, v133
	v_cvt_pk_bf16_f32 v45, v134, v135
	v_cvt_pk_bf16_f32 v46, v136, v137
	v_cvt_pk_bf16_f32 v47, v138, v139
	v_mfma_f32_32x32x16_bf16 v[64:79], v[56:59], v[52:55], v[64:79]
	ds_read_b128 v[48:51], v238 offset:20480
	v_add_f32_e64 v62, v134, v62
	v_add_f32_e64 v63, v135, v63
	v_add_f32_e64 v60, v132, v60
	v_add_f32_e64 v61, v133, v61
	v_pk_add_f32 v[62:63], v[138:139], v[62:63]
	v_pk_add_f32 v[60:61], v[136:137], v[60:61]
	s_waitcnt lgkmcnt(0)
	v_mfma_f32_32x32x16_bf16 v[16:31], v[32:35], v[52:55], v[16:31]
	ds_read_b128 v[56:59], v238 offset:24576
	v_add_f32_e64 v62, v154, v62
	v_add_f32_e64 v63, v155, v63
	v_add_f32_e64 v60, v152, v60
	v_add_f32_e64 v61, v153, v61
	v_pk_add_f32 v[130:131], v[158:159], v[62:63]
	v_pk_add_f32 v[128:129], v[156:157], v[60:61]
	v_mfma_f32_32x32x16_bf16 v[0:15], v[36:39], v[52:55], v[0:15]
	ds_read_b128 v[32:35], v238 offset:28672
	v_mfma_f32_32x32x16_bf16 v[80:95], v[40:43], v[44:47], v[80:95]
	ds_read_b128 v[36:39], v239 offset:16384
	v_cvt_pk_bf16_f32 v52, v152, v153
	v_cvt_pk_bf16_f32 v53, v154, v155
	v_cvt_pk_bf16_f32 v54, v156, v157
	v_cvt_pk_bf16_f32 v55, v158, v159
	v_mfma_f32_32x32x16_bf16 v[64:79], v[48:51], v[44:47], v[64:79]
	ds_read_b128 v[40:43], v239 offset:20480
	s_waitcnt lgkmcnt(0)
	v_mfma_f32_32x32x16_bf16 v[16:31], v[56:59], v[44:47], v[16:31]
	ds_read_b128 v[48:51], v239 offset:24576
	v_mfma_f32_32x32x16_bf16 v[0:15], v[32:35], v[44:47], v[0:15]
	ds_read_b128 v[56:59], v239 offset:28672
	v_mfma_f32_32x32x16_bf16 v[80:95], v[36:39], v[52:55], v[80:95]
	v_mfma_f32_32x32x16_bf16 v[64:79], v[40:43], v[52:55], v[64:79]
	s_waitcnt lgkmcnt(0)
	v_mfma_f32_32x32x16_bf16 v[16:31], v[48:51], v[52:55], v[16:31]
	v_mfma_f32_32x32x16_bf16 v[0:15], v[56:59], v[52:55], v[0:15]
	s_waitcnt vmcnt(4) lgkmcnt(0)
	s_barrier
	s_add_u32 s68, s98, 0x18000
	s_addc_u32 s69, s99, 0
	s_add_i32 s49, 0x8000, s57
	s_mov_b32 m0, s49
	s_nop 0
	global_load_lds_dwordx4 v198, s[68:69]
	s_add_i32 m0, s49, 0x400
	s_nop 0
	global_load_lds_dwordx4 v194, s[68:69]
	s_add_u32 s44, s100, 0x80
	s_addc_u32 s45, s101, 0
	s_add_i32 s49, s58, 0x4000
	s_add_i32 m0, s49, 0xc000
	s_nop 0
	global_load_lds_dwordx4 v196, s[44:45]
	s_add_i32 m0, s49, 0xc400
	s_nop 0
	global_load_lds_dwordx4 v192, s[44:45]
	v_exp_f32_e32 v144, v112
	ds_read_b128 v[32:35], v205
	ds_read_b128 v[36:39], v205 offset:8192
	s_waitcnt lgkmcnt(0)
	v_mfma_f32_32x32x16_bf16 v[48:63], v[32:35], v[160:163], 0
	ds_read_b128 v[132:135], v211
	ds_read_b128 v[136:139], v211 offset:8192
	ds_read_b128 v[140:143], v212
	v_exp_f32_e32 v145, v113
	v_exp_f32_e32 v146, v114
	v_exp_f32_e32 v147, v115
	ds_read_b128 v[112:115], v212 offset:8192
	v_mfma_f32_32x32x16_bf16 v[32:47], v[36:39], v[160:163], 0
	v_exp_f32_e32 v148, v116
	v_exp_f32_e32 v149, v117
	v_exp_f32_e32 v150, v118
	v_exp_f32_e32 v151, v119
	s_waitcnt lgkmcnt(0)
	v_mfma_f32_32x32x16_bf16 v[48:63], v[132:135], v[164:167], v[48:63]
	ds_read_b128 v[116:119], v213
	v_exp_f32_e32 v152, v120
	v_exp_f32_e32 v153, v121
	v_exp_f32_e32 v154, v122
	v_exp_f32_e32 v155, v123
	v_mfma_f32_32x32x16_bf16 v[32:47], v[136:139], v[164:167], v[32:47]
	ds_read_b128 v[120:123], v213 offset:8192
	v_exp_f32_e32 v156, v124
	v_exp_f32_e32 v157, v125
	v_exp_f32_e32 v158, v126
	v_exp_f32_e32 v159, v127
	v_mfma_f32_32x32x16_bf16 v[48:63], v[140:143], v[168:171], v[48:63]
	ds_read_b128 v[124:127], v236 offset:32768
	v_exp_f32_e32 v136, v96
	v_exp_f32_e32 v137, v97
	v_exp_f32_e32 v138, v98
	v_exp_f32_e32 v139, v99
	v_mfma_f32_32x32x16_bf16 v[32:47], v[112:115], v[168:171], v[32:47]
	ds_read_b128 v[96:99], v236 offset:36864
	v_exp_f32_e32 v140, v100
	v_exp_f32_e32 v141, v101
	v_exp_f32_e32 v142, v102
	v_exp_f32_e32 v143, v103
	s_waitcnt lgkmcnt(0)
	v_mfma_f32_32x32x16_bf16 v[48:63], v[116:119], v[172:175], v[48:63]
	ds_read_b128 v[100:103], v236 offset:40960
	v_exp_f32_e32 v178, v104
	v_exp_f32_e32 v179, v105
	v_exp_f32_e32 v180, v106
	v_exp_f32_e32 v181, v107
	v_mfma_f32_32x32x16_bf16 v[32:47], v[120:123], v[172:175], v[32:47]
	ds_read_b128 v[104:107], v236 offset:45056
	v_exp_f32_e32 v182, v108
	v_exp_f32_e32 v183, v109
	v_exp_f32_e32 v184, v110
	v_exp_f32_e32 v185, v111
	v_cvt_pk_bf16_f32 v108, v144, v145
	v_cvt_pk_bf16_f32 v109, v146, v147
	v_cvt_pk_bf16_f32 v110, v148, v149
	v_cvt_pk_bf16_f32 v111, v150, v151
	s_nop 1
	v_mfma_f32_32x32x16_bf16 v[80:95], v[124:127], v[108:111], v[80:95]
	ds_read_b128 v[112:115], v237 offset:32768
	v_cvt_pk_bf16_f32 v116, v152, v153
	v_cvt_pk_bf16_f32 v117, v154, v155
	v_cvt_pk_bf16_f32 v118, v156, v157
	v_cvt_pk_bf16_f32 v119, v158, v159
	v_mfma_f32_32x32x16_bf16 v[64:79], v[96:99], v[108:111], v[64:79]
	ds_read_b128 v[120:123], v237 offset:36864
	v_pk_add_f32 v[126:127], v[150:151], v[146:147]
	v_pk_add_f32 v[124:125], v[148:149], v[144:145]
	s_waitcnt lgkmcnt(0)
	v_mfma_f32_32x32x16_bf16 v[16:31], v[100:103], v[108:111], v[16:31]
	ds_read_b128 v[132:135], v237 offset:40960
	v_add_f32_e64 v98, v154, v126
	v_add_f32_e64 v99, v155, v127
	v_add_f32_e64 v96, v152, v124
	v_add_f32_e64 v97, v153, v125
	v_pk_add_f32 v[98:99], v[158:159], v[98:99]
	v_pk_add_f32 v[96:97], v[156:157], v[96:97]
	v_mfma_f32_32x32x16_bf16 v[0:15], v[104:107], v[108:111], v[0:15]
	ds_read_b128 v[100:103], v237 offset:45056
	v_mfma_f32_32x32x16_bf16 v[80:95], v[112:115], v[116:119], v[80:95]
	ds_read_b128 v[104:107], v238 offset:32768
	v_cvt_pk_bf16_f32 v108, v136, v137
	v_cvt_pk_bf16_f32 v109, v138, v139
	v_cvt_pk_bf16_f32 v110, v140, v141
	v_cvt_pk_bf16_f32 v111, v142, v143
	v_mfma_f32_32x32x16_bf16 v[64:79], v[120:123], v[116:119], v[64:79]
	ds_read_b128 v[112:115], v238 offset:36864
	v_add_f32_e64 v98, v138, v98
	v_add_f32_e64 v99, v139, v99
	v_add_f32_e64 v96, v136, v96
	v_add_f32_e64 v97, v137, v97
	v_pk_add_f32 v[98:99], v[142:143], v[98:99]
	v_pk_add_f32 v[96:97], v[140:141], v[96:97]
	s_waitcnt lgkmcnt(0)
	v_mfma_f32_32x32x16_bf16 v[16:31], v[132:135], v[116:119], v[16:31]
	ds_read_b128 v[120:123], v238 offset:40960
	v_add_f32_e64 v98, v180, v98
	v_add_f32_e64 v99, v181, v99
	v_add_f32_e64 v96, v178, v96
	v_add_f32_e64 v97, v179, v97
	v_pk_add_f32 v[98:99], v[184:185], v[98:99]
	v_pk_add_f32 v[96:97], v[182:183], v[96:97]
	v_mfma_f32_32x32x16_bf16 v[0:15], v[100:103], v[116:119], v[0:15]
	ds_read_b128 v[124:127], v238 offset:45056
	v_mfma_f32_32x32x16_bf16 v[80:95], v[104:107], v[108:111], v[80:95]
	ds_read_b128 v[100:103], v239 offset:32768
	v_cvt_pk_bf16_f32 v116, v178, v179
	v_cvt_pk_bf16_f32 v117, v180, v181
	v_cvt_pk_bf16_f32 v118, v182, v183
	v_cvt_pk_bf16_f32 v119, v184, v185
	v_mfma_f32_32x32x16_bf16 v[64:79], v[112:115], v[108:111], v[64:79]
	ds_read_b128 v[104:107], v239 offset:36864
	s_waitcnt lgkmcnt(0)
	v_mfma_f32_32x32x16_bf16 v[16:31], v[120:123], v[108:111], v[16:31]
	ds_read_b128 v[112:115], v239 offset:40960
	v_mfma_f32_32x32x16_bf16 v[0:15], v[124:127], v[108:111], v[0:15]
	ds_read_b128 v[120:123], v239 offset:45056
	v_mfma_f32_32x32x16_bf16 v[80:95], v[100:103], v[116:119], v[80:95]
	v_mfma_f32_32x32x16_bf16 v[64:79], v[104:107], v[116:119], v[64:79]
	s_waitcnt lgkmcnt(0)
	v_mfma_f32_32x32x16_bf16 v[16:31], v[112:115], v[116:119], v[16:31]
	v_mfma_f32_32x32x16_bf16 v[0:15], v[120:123], v[116:119], v[0:15]
	s_waitcnt vmcnt(4) lgkmcnt(0)
	v_add_f32_e32 v100, v128, v129
	v_add_f32_e32 v101, v130, v131
	v_add_f32_e32 v100, v100, v101
	v_add_f32_e32 v96, v96, v97
	v_add_f32_e32 v97, v98, v99
	s_barrier
	v_add_f32_e32 v100, v177, v100
	v_add_f32_e32 v96, v96, v97
	v_add_f32_e32 v177, v100, v96
	s_add_i32 s21, s21, 2
	s_addk_i32 s15, 0x80
	s_add_i32 s20, s20, 0x8000
	s_add_u32 s98, s98, 0x30000
	s_addc_u32 s99, s99, 0
	s_add_u32 s100, s100, 0x100
	s_addc_u32 s101, s101, 0
	s_cmp_lt_u32 s21, 50
	s_cbranch_scc1 .Lst0_u6_loop
	s_cmp_lt_u32 s21, 60
	s_cbranch_scc1 .Lst0_single

.Lst1_u6_loop:
	s_add_i32 s49, s58, 0
	s_mov_b32 m0, s49
	s_nop 0
	global_load_lds_dwordx4 v198, s[98:99]
	s_add_i32 m0, s49, 0x400
	s_nop 0
	global_load_lds_dwordx4 v194, s[98:99]
	s_add_i32 s49, s46, 0xffffc000
	s_add_i32 s49, s58, 0x4000
	s_add_i32 m0, s49, 0xc000
	s_nop 0
	global_load_lds_dwordx4 v196, s[100:101]
	s_add_i32 m0, s49, 0xc400
	s_nop 0
	global_load_lds_dwordx4 v192, s[100:101]
	ds_read_b128 v[140:143], v236 offset:16384
	ds_read_b128 v[148:151], v236 offset:20480
	ds_read_b128 v[152:155], v236 offset:24576
	ds_read_b128 v[156:159], v236 offset:28672
	s_waitcnt lgkmcnt(0)
	v_mfma_f32_32x32x16_bf16 v[80:95], v[140:143], v[144:147], v[80:95]
	ds_read_b128 v[140:143], v237 offset:16384
	v_mfma_f32_32x32x16_bf16 v[64:79], v[148:151], v[144:147], v[64:79]
	ds_read_b128 v[148:151], v237 offset:20480
	v_mfma_f32_32x32x16_bf16 v[16:31], v[152:155], v[144:147], v[16:31]
	ds_read_b128 v[152:155], v237 offset:24576
	v_mfma_f32_32x32x16_bf16 v[0:15], v[156:159], v[144:147], v[0:15]
	ds_read_b128 v[144:147], v237 offset:28672
	s_waitcnt lgkmcnt(0)
	v_mfma_f32_32x32x16_bf16 v[80:95], v[140:143], v[128:131], v[80:95]
	ds_read_b128 v[140:143], v238 offset:16384
	v_mfma_f32_32x32x16_bf16 v[64:79], v[148:151], v[128:131], v[64:79]
	ds_read_b128 v[148:151], v238 offset:20480
	v_mfma_f32_32x32x16_bf16 v[16:31], v[152:155], v[128:131], v[16:31]
	ds_read_b128 v[152:155], v238 offset:24576
	v_mfma_f32_32x32x16_bf16 v[0:15], v[144:147], v[128:131], v[0:15]
	ds_read_b128 v[128:131], v238 offset:28672
	s_waitcnt lgkmcnt(0)
	v_mfma_f32_32x32x16_bf16 v[80:95], v[140:143], v[132:135], v[80:95]
	ds_read_b128 v[140:143], v239 offset:16384
	v_mfma_f32_32x32x16_bf16 v[64:79], v[148:151], v[132:135], v[64:79]
	ds_read_b128 v[144:147], v239 offset:20480
	v_mfma_f32_32x32x16_bf16 v[16:31], v[152:155], v[132:135], v[16:31]
	ds_read_b128 v[148:151], v239 offset:24576
	v_mfma_f32_32x32x16_bf16 v[0:15], v[128:131], v[132:135], v[0:15]
	ds_read_b128 v[128:131], v239 offset:28672
	s_waitcnt lgkmcnt(0)
	v_mfma_f32_32x32x16_bf16 v[80:95], v[140:143], v[136:139], v[80:95]
	ds_read_b128 v[132:135], v205 offset:16384
	v_mfma_f32_32x32x16_bf16 v[64:79], v[144:147], v[136:139], v[64:79]
	ds_read_b128 v[140:143], v205 offset:24576
	v_mfma_f32_32x32x16_bf16 v[16:31], v[148:151], v[136:139], v[16:31]
	ds_read_b128 v[176:179], v211 offset:16384
	v_mfma_f32_32x32x16_bf16 v[0:15], v[128:131], v[136:139], v[0:15]
	ds_read_b128 v[182:185], v211 offset:24576
	s_waitcnt lgkmcnt(0)
	v_mfma_f32_32x32x16_bf16 v[144:159], v[132:135], v[160:163], 0
	ds_read_b128 v[186:189], v212 offset:16384
	v_exp_f32_e32 v220, v112
	v_exp_f32_e32 v221, v113
	v_exp_f32_e32 v222, v114
	v_exp_f32_e32 v223, v115
	v_mfma_f32_32x32x16_bf16 v[128:143], v[140:143], v[160:163], 0
	ds_read_b128 v[216:219], v212 offset:24576
	v_exp_f32_e32 v224, v116
	v_exp_f32_e32 v225, v117
	v_exp_f32_e32 v226, v118
	v_exp_f32_e32 v227, v119
	v_mfma_f32_32x32x16_bf16 v[144:159], v[176:179], v[164:167], v[144:159]
	ds_read_b128 v[116:119], v213 offset:16384
	v_exp_f32_e32 v228, v120
	v_exp_f32_e32 v229, v121
	v_exp_f32_e32 v230, v122
	v_exp_f32_e32 v231, v123
	v_cvt_pk_bf16_f32 v112, v220, v221
	v_cvt_pk_bf16_f32 v113, v222, v223
	v_cvt_pk_bf16_f32 v114, v224, v225
	v_cvt_pk_bf16_f32 v115, v226, v227
	v_pk_add_f32 v[122:123], v[226:227], v[222:223]
	v_pk_add_f32 v[120:121], v[224:225], v[220:221]
	v_mfma_f32_32x32x16_bf16 v[128:143], v[182:185], v[164:167], v[128:143]
	ds_read_b128 v[176:179], v213 offset:24576
	v_exp_f32_e32 v124, v124
	v_exp_f32_e32 v125, v125
	v_exp_f32_e32 v126, v126
	v_exp_f32_e32 v127, v127
	s_waitcnt lgkmcnt(0)
	v_mfma_f32_32x32x16_bf16 v[144:159], v[186:189], v[168:171], v[144:159]
	v_add_f32_e64 v122, v230, v122
	v_add_f32_e64 v123, v231, v123
	v_add_f32_e64 v120, v228, v120
	v_add_f32_e64 v121, v229, v121
	v_exp_f32_e32 v182, v96
	v_exp_f32_e32 v183, v97
	v_exp_f32_e32 v184, v98
	v_exp_f32_e32 v185, v99
	v_cvt_pk_bf16_f32 v96, v228, v229
	v_cvt_pk_bf16_f32 v97, v230, v231
	v_cvt_pk_bf16_f32 v98, v124, v125
	v_cvt_pk_bf16_f32 v99, v126, v127
	v_pk_add_f32 v[122:123], v[126:127], v[122:123]
	v_pk_add_f32 v[120:121], v[124:125], v[120:121]
	v_mfma_f32_32x32x16_bf16 v[128:143], v[216:219], v[168:171], v[128:143]
	v_exp_f32_e32 v124, v100
	v_exp_f32_e32 v125, v101
	v_exp_f32_e32 v126, v102
	v_exp_f32_e32 v127, v103
	v_mfma_f32_32x32x16_bf16 v[144:159], v[116:119], v[172:175], v[144:159]
	v_exp_f32_e32 v186, v104
	v_exp_f32_e32 v187, v105
	v_exp_f32_e32 v188, v106
	v_exp_f32_e32 v189, v107
	v_pk_add_f32 v[106:107], v[184:185], v[122:123]
	v_pk_add_f32 v[104:105], v[182:183], v[120:121]
	v_cvt_pk_bf16_f32 v100, v182, v183
	v_cvt_pk_bf16_f32 v101, v184, v185
	v_cvt_pk_bf16_f32 v102, v124, v125
	v_cvt_pk_bf16_f32 v103, v126, v127
	v_pk_add_f32 v[118:119], v[126:127], v[106:107]
	v_pk_add_f32 v[116:117], v[124:125], v[104:105]
	v_mfma_f32_32x32x16_bf16 v[128:143], v[176:179], v[172:175], v[128:143]
	v_exp_f32_e32 v120, v108
	v_exp_f32_e32 v121, v109
	v_exp_f32_e32 v122, v110
	v_exp_f32_e32 v123, v111
	v_pk_add_f32 v[110:111], v[188:189], v[118:119]
	v_pk_add_f32 v[108:109], v[186:187], v[116:117]
	v_cvt_pk_bf16_f32 v104, v186, v187
	v_cvt_pk_bf16_f32 v105, v188, v189
	v_cvt_pk_bf16_f32 v106, v120, v121
	v_cvt_pk_bf16_f32 v107, v122, v123
	v_pk_add_f32 v[178:179], v[122:123], v[110:111]
	v_pk_add_f32 v[176:177], v[120:121], v[108:109]
	s_waitcnt vmcnt(4) lgkmcnt(0)
	s_barrier
	s_add_u32 s70, s98, 0x18000
	s_addc_u32 s71, s99, 0
	s_add_i32 s68, 0x4000, s57
	s_mov_b32 m0, s68
	s_nop 0
	global_load_lds_dwordx4 v198, s[70:71]
	s_add_i32 m0, s68, 0x400
	s_nop 0
	global_load_lds_dwordx4 v194, s[70:71]
	s_add_u32 s2, s100, 0x80
	s_addc_u32 s3, s101, 0
	s_add_i32 s49, s58, 0x8000
	s_add_i32 m0, s49, 0xc000
	s_nop 0
	global_load_lds_dwordx4 v196, s[2:3]
	s_add_i32 m0, s49, 0xc400
	s_nop 0
	global_load_lds_dwordx4 v192, s[2:3]
	s_add_i32 s2, s46, 0xffff4000
	ds_read_b128 v[108:111], v236 offset:32768
	ds_read_b128 v[116:119], v236 offset:36864
	ds_read_b128 v[120:123], v236 offset:40960
	ds_read_b128 v[124:127], v236 offset:45056
	s_waitcnt lgkmcnt(0)
	v_mfma_f32_32x32x16_bf16 v[80:95], v[108:111], v[112:115], v[80:95]
	ds_read_b128 v[108:111], v237 offset:32768
	v_mfma_f32_32x32x16_bf16 v[64:79], v[116:119], v[112:115], v[64:79]
	ds_read_b128 v[116:119], v237 offset:36864
	v_mfma_f32_32x32x16_bf16 v[16:31], v[120:123], v[112:115], v[16:31]
	ds_read_b128 v[120:123], v237 offset:40960
	v_mfma_f32_32x32x16_bf16 v[0:15], v[124:127], v[112:115], v[0:15]
	ds_read_b128 v[112:115], v237 offset:45056
	s_waitcnt lgkmcnt(0)
	v_mfma_f32_32x32x16_bf16 v[80:95], v[108:111], v[96:99], v[80:95]
	ds_read_b128 v[108:111], v238 offset:32768
	v_mfma_f32_32x32x16_bf16 v[64:79], v[116:119], v[96:99], v[64:79]
	ds_read_b128 v[116:119], v238 offset:36864
	v_mfma_f32_32x32x16_bf16 v[16:31], v[120:123], v[96:99], v[16:31]
	ds_read_b128 v[120:123], v238 offset:40960
	v_mfma_f32_32x32x16_bf16 v[0:15], v[112:115], v[96:99], v[0:15]
	ds_read_b128 v[96:99], v238 offset:45056
	s_waitcnt lgkmcnt(0)
	v_mfma_f32_32x32x16_bf16 v[80:95], v[108:111], v[100:103], v[80:95]
	ds_read_b128 v[108:111], v239 offset:32768
	v_mfma_f32_32x32x16_bf16 v[64:79], v[116:119], v[100:103], v[64:79]
	ds_read_b128 v[112:115], v239 offset:36864
	v_mfma_f32_32x32x16_bf16 v[16:31], v[120:123], v[100:103], v[16:31]
	ds_read_b128 v[116:119], v239 offset:40960
	v_mfma_f32_32x32x16_bf16 v[0:15], v[96:99], v[100:103], v[0:15]
	ds_read_b128 v[120:123], v239 offset:45056
	s_waitcnt lgkmcnt(0)
	v_mfma_f32_32x32x16_bf16 v[80:95], v[108:111], v[104:107], v[80:95]
	ds_read_b128 v[96:99], v205 offset:32768
	v_mfma_f32_32x32x16_bf16 v[64:79], v[112:115], v[104:107], v[64:79]
	ds_read_b128 v[100:103], v205 offset:40960
	v_mfma_f32_32x32x16_bf16 v[16:31], v[116:119], v[104:107], v[16:31]
	ds_read_b128 v[182:185], v211 offset:32768
	v_mfma_f32_32x32x16_bf16 v[0:15], v[120:123], v[104:107], v[0:15]
	ds_read_b128 v[186:189], v211 offset:40960
	s_waitcnt lgkmcnt(0)
	v_mfma_f32_32x32x16_bf16 v[112:127], v[96:99], v[160:163], 0
	ds_read_b128 v[216:219], v212 offset:32768
	v_exp_f32_e32 v224, v144
	v_exp_f32_e32 v225, v145
	v_exp_f32_e32 v226, v146
	v_exp_f32_e32 v227, v147
	ds_read_b128 v[220:223], v212 offset:40960
	v_mfma_f32_32x32x16_bf16 v[96:111], v[100:103], v[160:163], 0
	v_exp_f32_e32 v228, v148
	v_exp_f32_e32 v229, v149
	v_exp_f32_e32 v230, v150
	v_exp_f32_e32 v231, v151
	v_mfma_f32_32x32x16_bf16 v[112:127], v[182:185], v[164:167], v[112:127]
	ds_read_b128 v[148:151], v213 offset:32768
	v_exp_f32_e32 v232, v152
	v_exp_f32_e32 v233, v153
	v_exp_f32_e32 v234, v154
	v_exp_f32_e32 v235, v155
	v_cvt_pk_bf16_f32 v144, v224, v225
	v_cvt_pk_bf16_f32 v145, v226, v227
	v_cvt_pk_bf16_f32 v146, v228, v229
	v_cvt_pk_bf16_f32 v147, v230, v231
	v_pk_add_f32 v[154:155], v[230:231], v[226:227]
	v_pk_add_f32 v[152:153], v[228:229], v[224:225]
	v_mfma_f32_32x32x16_bf16 v[96:111], v[186:189], v[164:167], v[96:111]
	ds_read_b128 v[182:185], v213 offset:40960
	v_exp_f32_e32 v156, v156
	v_exp_f32_e32 v157, v157
	v_exp_f32_e32 v158, v158
	v_exp_f32_e32 v159, v159
	s_waitcnt lgkmcnt(0)
	v_mfma_f32_32x32x16_bf16 v[112:127], v[216:219], v[168:171], v[112:127]
	v_add_f32_e64 v154, v234, v154
	v_add_f32_e64 v155, v235, v155
	v_add_f32_e64 v152, v232, v152
	v_add_f32_e64 v153, v233, v153
	v_exp_f32_e32 v186, v128
	v_exp_f32_e32 v187, v129
	v_exp_f32_e32 v188, v130
	v_exp_f32_e32 v189, v131
	v_cvt_pk_bf16_f32 v128, v232, v233
	v_cvt_pk_bf16_f32 v129, v234, v235
	v_cvt_pk_bf16_f32 v130, v156, v157
	v_cvt_pk_bf16_f32 v131, v158, v159
	v_pk_add_f32 v[154:155], v[158:159], v[154:155]
	v_pk_add_f32 v[152:153], v[156:157], v[152:153]
	v_mfma_f32_32x32x16_bf16 v[96:111], v[220:223], v[168:171], v[96:111]
	v_exp_f32_e32 v156, v132
	v_exp_f32_e32 v157, v133
	v_exp_f32_e32 v158, v134
	v_exp_f32_e32 v159, v135
	v_mfma_f32_32x32x16_bf16 v[112:127], v[148:151], v[172:175], v[112:127]
	v_exp_f32_e32 v216, v136
	v_exp_f32_e32 v217, v137
	v_exp_f32_e32 v218, v138
	v_exp_f32_e32 v219, v139
	v_pk_add_f32 v[138:139], v[188:189], v[154:155]
	v_pk_add_f32 v[136:137], v[186:187], v[152:153]
	v_cvt_pk_bf16_f32 v132, v186, v187
	v_cvt_pk_bf16_f32 v133, v188, v189
	v_cvt_pk_bf16_f32 v134, v156, v157
	v_cvt_pk_bf16_f32 v135, v158, v159
	v_pk_add_f32 v[150:151], v[158:159], v[138:139]
	v_pk_add_f32 v[148:149], v[156:157], v[136:137]
	v_mfma_f32_32x32x16_bf16 v[96:111], v[182:185], v[172:175], v[96:111]
	v_exp_f32_e32 v152, v140
	v_exp_f32_e32 v153, v141
	v_exp_f32_e32 v154, v142
	v_exp_f32_e32 v155, v143
	v_pk_add_f32 v[142:143], v[218:219], v[150:151]
	v_pk_add_f32 v[140:141], v[216:217], v[148:149]
	v_cvt_pk_bf16_f32 v136, v216, v217
	v_cvt_pk_bf16_f32 v137, v218, v219
	v_cvt_pk_bf16_f32 v138, v152, v153
	v_cvt_pk_bf16_f32 v139, v154, v155
	v_pk_add_f32 v[142:143], v[154:155], v[142:143]
	v_pk_add_f32 v[140:141], v[152:153], v[140:141]
	s_waitcnt vmcnt(4) lgkmcnt(0)
	v_add_f32_e32 v148, v176, v177
	v_add_f32_e32 v149, v178, v179
	v_add_f32_e32 v148, v148, v149
	v_add_f32_e32 v140, v140, v141
	v_add_f32_e32 v141, v142, v143
	s_barrier
	v_add_f32_e32 v148, v180, v148
	v_add_f32_e32 v140, v140, v141
	v_add_f32_e32 v180, v148, v140
	s_add_i32 s47, s47, 2
	s_addk_i32 s41, 0x80
	s_add_i32 s46, s46, 0x8000
	s_add_u32 s98, s98, 0x30000
	s_addc_u32 s99, s99, 0
	s_add_u32 s100, s100, 0x100
	s_addc_u32 s101, s101, 0
	s_add_i32 s49, s58, 0x8000
	s_mov_b32 m0, s49
	s_nop 0
	global_load_lds_dwordx4 v198, s[98:99]
	s_add_i32 m0, s49, 0x400
	s_nop 0
	global_load_lds_dwordx4 v194, s[98:99]
	s_add_i32 s49, s46, 0xffffc000
	s_add_i32 s49, s58, 0xc000
	s_add_i32 m0, s49, 0xc000
	s_nop 0
	global_load_lds_dwordx4 v196, s[100:101]
	s_add_i32 m0, s49, 0xc400
	s_nop 0
	global_load_lds_dwordx4 v192, s[100:101]
	ds_read_b128 v[140:143], v206 offset:49152
	ds_read_b128 v[148:151], v206 offset:53248
	ds_read_b128 v[152:155], v206 offset:57344
	ds_read_b128 v[156:159], v206 offset:61440
	s_waitcnt lgkmcnt(0)
	v_mfma_f32_32x32x16_bf16 v[80:95], v[140:143], v[144:147], v[80:95]
	ds_read_b128 v[140:143], v207 offset:49152
	v_mfma_f32_32x32x16_bf16 v[64:79], v[148:151], v[144:147], v[64:79]
	ds_read_b128 v[148:151], v207 offset:53248
	v_mfma_f32_32x32x16_bf16 v[16:31], v[152:155], v[144:147], v[16:31]
	ds_read_b128 v[152:155], v207 offset:57344
	v_mfma_f32_32x32x16_bf16 v[0:15], v[156:159], v[144:147], v[0:15]
	ds_read_b128 v[144:147], v207 offset:61440
	s_waitcnt lgkmcnt(0)
	v_mfma_f32_32x32x16_bf16 v[80:95], v[140:143], v[128:131], v[80:95]
	ds_read_b128 v[140:143], v208 offset:49152
	v_mfma_f32_32x32x16_bf16 v[64:79], v[148:151], v[128:131], v[64:79]
	ds_read_b128 v[148:151], v208 offset:53248
	v_mfma_f32_32x32x16_bf16 v[16:31], v[152:155], v[128:131], v[16:31]
	ds_read_b128 v[152:155], v208 offset:57344
	v_mfma_f32_32x32x16_bf16 v[0:15], v[144:147], v[128:131], v[0:15]
	ds_read_b128 v[128:131], v208 offset:61440
	s_waitcnt lgkmcnt(0)
	v_mfma_f32_32x32x16_bf16 v[80:95], v[140:143], v[132:135], v[80:95]
	ds_read_b128 v[140:143], v209 offset:49152
	v_mfma_f32_32x32x16_bf16 v[64:79], v[148:151], v[132:135], v[64:79]
	ds_read_b128 v[144:147], v209 offset:53248
	v_mfma_f32_32x32x16_bf16 v[16:31], v[152:155], v[132:135], v[16:31]
	ds_read_b128 v[148:151], v209 offset:57344
	v_mfma_f32_32x32x16_bf16 v[0:15], v[128:131], v[132:135], v[0:15]
	ds_read_b128 v[128:131], v209 offset:61440
	s_waitcnt lgkmcnt(0)
	v_mfma_f32_32x32x16_bf16 v[80:95], v[140:143], v[136:139], v[80:95]
	ds_read_b128 v[132:135], v205
	v_mfma_f32_32x32x16_bf16 v[64:79], v[144:147], v[136:139], v[64:79]
	ds_read_b128 v[140:143], v205 offset:8192
	v_mfma_f32_32x32x16_bf16 v[16:31], v[148:151], v[136:139], v[16:31]
	ds_read_b128 v[176:179], v211
	v_mfma_f32_32x32x16_bf16 v[0:15], v[128:131], v[136:139], v[0:15]
	ds_read_b128 v[182:185], v211 offset:8192
	s_waitcnt lgkmcnt(0)
	v_mfma_f32_32x32x16_bf16 v[144:159], v[132:135], v[160:163], 0
	ds_read_b128 v[186:189], v212
	v_exp_f32_e32 v220, v112
	v_exp_f32_e32 v221, v113
	v_exp_f32_e32 v222, v114
	v_exp_f32_e32 v223, v115
	v_mfma_f32_32x32x16_bf16 v[128:143], v[140:143], v[160:163], 0
	ds_read_b128 v[216:219], v212 offset:8192
	v_exp_f32_e32 v224, v116
	v_exp_f32_e32 v225, v117
	v_exp_f32_e32 v226, v118
	v_exp_f32_e32 v227, v119
	v_mfma_f32_32x32x16_bf16 v[144:159], v[176:179], v[164:167], v[144:159]
	ds_read_b128 v[116:119], v213
	v_exp_f32_e32 v228, v120
	v_exp_f32_e32 v229, v121
	v_exp_f32_e32 v230, v122
	v_exp_f32_e32 v231, v123
	v_cvt_pk_bf16_f32 v112, v220, v221
	v_cvt_pk_bf16_f32 v113, v222, v223
	v_cvt_pk_bf16_f32 v114, v224, v225
	v_cvt_pk_bf16_f32 v115, v226, v227
	v_pk_add_f32 v[122:123], v[226:227], v[222:223]
	v_pk_add_f32 v[120:121], v[224:225], v[220:221]
	v_mfma_f32_32x32x16_bf16 v[128:143], v[182:185], v[164:167], v[128:143]
	ds_read_b128 v[176:179], v213 offset:8192
	v_exp_f32_e32 v124, v124
	v_exp_f32_e32 v125, v125
	v_exp_f32_e32 v126, v126
	v_exp_f32_e32 v127, v127
	s_waitcnt lgkmcnt(0)
	v_mfma_f32_32x32x16_bf16 v[144:159], v[186:189], v[168:171], v[144:159]
	v_add_f32_e64 v122, v230, v122
	v_add_f32_e64 v123, v231, v123
	v_add_f32_e64 v120, v228, v120
	v_add_f32_e64 v121, v229, v121
	v_exp_f32_e32 v182, v96
	v_exp_f32_e32 v183, v97
	v_exp_f32_e32 v184, v98
	v_exp_f32_e32 v185, v99
	v_cvt_pk_bf16_f32 v96, v228, v229
	v_cvt_pk_bf16_f32 v97, v230, v231
	v_cvt_pk_bf16_f32 v98, v124, v125
	v_cvt_pk_bf16_f32 v99, v126, v127
	v_pk_add_f32 v[122:123], v[126:127], v[122:123]
	v_pk_add_f32 v[120:121], v[124:125], v[120:121]
	v_mfma_f32_32x32x16_bf16 v[128:143], v[216:219], v[168:171], v[128:143]
	v_exp_f32_e32 v124, v100
	v_exp_f32_e32 v125, v101
	v_exp_f32_e32 v126, v102
	v_exp_f32_e32 v127, v103
	v_mfma_f32_32x32x16_bf16 v[144:159], v[116:119], v[172:175], v[144:159]
	v_exp_f32_e32 v186, v104
	v_exp_f32_e32 v187, v105
	v_exp_f32_e32 v188, v106
	v_exp_f32_e32 v189, v107
	v_pk_add_f32 v[106:107], v[184:185], v[122:123]
	v_pk_add_f32 v[104:105], v[182:183], v[120:121]
	v_cvt_pk_bf16_f32 v100, v182, v183
	v_cvt_pk_bf16_f32 v101, v184, v185
	v_cvt_pk_bf16_f32 v102, v124, v125
	v_cvt_pk_bf16_f32 v103, v126, v127
	v_pk_add_f32 v[118:119], v[126:127], v[106:107]
	v_pk_add_f32 v[116:117], v[124:125], v[104:105]
	v_mfma_f32_32x32x16_bf16 v[128:143], v[176:179], v[172:175], v[128:143]
	v_exp_f32_e32 v120, v108
	v_exp_f32_e32 v121, v109
	v_exp_f32_e32 v122, v110
	v_exp_f32_e32 v123, v111
	v_pk_add_f32 v[110:111], v[188:189], v[118:119]
	v_pk_add_f32 v[108:109], v[186:187], v[116:117]
	v_cvt_pk_bf16_f32 v104, v186, v187
	v_cvt_pk_bf16_f32 v105, v188, v189
	v_cvt_pk_bf16_f32 v106, v120, v121
	v_cvt_pk_bf16_f32 v107, v122, v123
	v_pk_add_f32 v[178:179], v[122:123], v[110:111]
	v_pk_add_f32 v[176:177], v[120:121], v[108:109]
	s_waitcnt vmcnt(4) lgkmcnt(0)
	s_barrier
	s_add_u32 s70, s98, 0x18000
	s_addc_u32 s71, s99, 0
	s_add_i32 s68, 0, s57
	s_mov_b32 m0, s68
	s_nop 0
	global_load_lds_dwordx4 v198, s[70:71]
	s_add_i32 m0, s68, 0x400
	s_nop 0
	global_load_lds_dwordx4 v194, s[70:71]
	s_add_u32 s2, s100, 0x80
	s_addc_u32 s3, s101, 0
	s_add_i32 s49, s58, 0
	s_add_i32 m0, s49, 0xc000
	s_nop 0
	global_load_lds_dwordx4 v196, s[2:3]
	s_add_i32 m0, s49, 0xc400
	s_nop 0
	global_load_lds_dwordx4 v192, s[2:3]
	s_add_i32 s2, s46, 0xffff4000
	ds_read_b128 v[108:111], v236
	ds_read_b128 v[116:119], v236 offset:4096
	ds_read_b128 v[120:123], v236 offset:8192
	ds_read_b128 v[124:127], v236 offset:12288
	s_waitcnt lgkmcnt(0)
	v_mfma_f32_32x32x16_bf16 v[80:95], v[108:111], v[112:115], v[80:95]
	ds_read_b128 v[108:111], v237
	v_mfma_f32_32x32x16_bf16 v[64:79], v[116:119], v[112:115], v[64:79]
	ds_read_b128 v[116:119], v237 offset:4096
	v_mfma_f32_32x32x16_bf16 v[16:31], v[120:123], v[112:115], v[16:31]
	ds_read_b128 v[120:123], v237 offset:8192
	v_mfma_f32_32x32x16_bf16 v[0:15], v[124:127], v[112:115], v[0:15]
	ds_read_b128 v[112:115], v237 offset:12288
	s_waitcnt lgkmcnt(0)
	v_mfma_f32_32x32x16_bf16 v[80:95], v[108:111], v[96:99], v[80:95]
	ds_read_b128 v[108:111], v238
	v_mfma_f32_32x32x16_bf16 v[64:79], v[116:119], v[96:99], v[64:79]
	ds_read_b128 v[116:119], v238 offset:4096
	v_mfma_f32_32x32x16_bf16 v[16:31], v[120:123], v[96:99], v[16:31]
	ds_read_b128 v[120:123], v238 offset:8192
	v_mfma_f32_32x32x16_bf16 v[0:15], v[112:115], v[96:99], v[0:15]
	ds_read_b128 v[96:99], v238 offset:12288
	s_waitcnt lgkmcnt(0)
	v_mfma_f32_32x32x16_bf16 v[80:95], v[108:111], v[100:103], v[80:95]
	ds_read_b128 v[108:111], v239
	v_mfma_f32_32x32x16_bf16 v[64:79], v[116:119], v[100:103], v[64:79]
	ds_read_b128 v[112:115], v239 offset:4096
	v_mfma_f32_32x32x16_bf16 v[16:31], v[120:123], v[100:103], v[16:31]
	ds_read_b128 v[116:119], v239 offset:8192
	v_mfma_f32_32x32x16_bf16 v[0:15], v[96:99], v[100:103], v[0:15]
	ds_read_b128 v[120:123], v239 offset:12288
	s_waitcnt lgkmcnt(0)
	v_mfma_f32_32x32x16_bf16 v[80:95], v[108:111], v[104:107], v[80:95]
	ds_read_b128 v[96:99], v205 offset:16384
	v_mfma_f32_32x32x16_bf16 v[64:79], v[112:115], v[104:107], v[64:79]
	ds_read_b128 v[100:103], v205 offset:24576
	v_mfma_f32_32x32x16_bf16 v[16:31], v[116:119], v[104:107], v[16:31]
	ds_read_b128 v[182:185], v211 offset:16384
	v_mfma_f32_32x32x16_bf16 v[0:15], v[120:123], v[104:107], v[0:15]
	ds_read_b128 v[186:189], v211 offset:24576
	s_waitcnt lgkmcnt(0)
	v_mfma_f32_32x32x16_bf16 v[112:127], v[96:99], v[160:163], 0
	ds_read_b128 v[216:219], v212 offset:16384
	v_exp_f32_e32 v224, v144
	v_exp_f32_e32 v225, v145
	v_exp_f32_e32 v226, v146
	v_exp_f32_e32 v227, v147
	ds_read_b128 v[220:223], v212 offset:24576
	v_mfma_f32_32x32x16_bf16 v[96:111], v[100:103], v[160:163], 0
	v_exp_f32_e32 v228, v148
	v_exp_f32_e32 v229, v149
	v_exp_f32_e32 v230, v150
	v_exp_f32_e32 v231, v151
	v_mfma_f32_32x32x16_bf16 v[112:127], v[182:185], v[164:167], v[112:127]
	ds_read_b128 v[148:151], v213 offset:16384
	v_exp_f32_e32 v232, v152
	v_exp_f32_e32 v233, v153
	v_exp_f32_e32 v234, v154
	v_exp_f32_e32 v235, v155
	v_cvt_pk_bf16_f32 v144, v224, v225
	v_cvt_pk_bf16_f32 v145, v226, v227
	v_cvt_pk_bf16_f32 v146, v228, v229
	v_cvt_pk_bf16_f32 v147, v230, v231
	v_pk_add_f32 v[154:155], v[230:231], v[226:227]
	v_pk_add_f32 v[152:153], v[228:229], v[224:225]
	v_mfma_f32_32x32x16_bf16 v[96:111], v[186:189], v[164:167], v[96:111]
	ds_read_b128 v[182:185], v213 offset:24576
	v_exp_f32_e32 v156, v156
	v_exp_f32_e32 v157, v157
	v_exp_f32_e32 v158, v158
	v_exp_f32_e32 v159, v159
	s_waitcnt lgkmcnt(0)
	v_mfma_f32_32x32x16_bf16 v[112:127], v[216:219], v[168:171], v[112:127]
	v_add_f32_e64 v154, v234, v154
	v_add_f32_e64 v155, v235, v155
	v_add_f32_e64 v152, v232, v152
	v_add_f32_e64 v153, v233, v153
	v_exp_f32_e32 v186, v128
	v_exp_f32_e32 v187, v129
	v_exp_f32_e32 v188, v130
	v_exp_f32_e32 v189, v131
	v_cvt_pk_bf16_f32 v128, v232, v233
	v_cvt_pk_bf16_f32 v129, v234, v235
	v_cvt_pk_bf16_f32 v130, v156, v157
	v_cvt_pk_bf16_f32 v131, v158, v159
	v_pk_add_f32 v[154:155], v[158:159], v[154:155]
	v_pk_add_f32 v[152:153], v[156:157], v[152:153]
	v_mfma_f32_32x32x16_bf16 v[96:111], v[220:223], v[168:171], v[96:111]
	v_exp_f32_e32 v156, v132
	v_exp_f32_e32 v157, v133
	v_exp_f32_e32 v158, v134
	v_exp_f32_e32 v159, v135
	v_mfma_f32_32x32x16_bf16 v[112:127], v[148:151], v[172:175], v[112:127]
	v_exp_f32_e32 v216, v136
	v_exp_f32_e32 v217, v137
	v_exp_f32_e32 v218, v138
	v_exp_f32_e32 v219, v139
	v_pk_add_f32 v[138:139], v[188:189], v[154:155]
	v_pk_add_f32 v[136:137], v[186:187], v[152:153]
	v_cvt_pk_bf16_f32 v132, v186, v187
	v_cvt_pk_bf16_f32 v133, v188, v189
	v_cvt_pk_bf16_f32 v134, v156, v157
	v_cvt_pk_bf16_f32 v135, v158, v159
	v_pk_add_f32 v[150:151], v[158:159], v[138:139]
	v_pk_add_f32 v[148:149], v[156:157], v[136:137]
	v_mfma_f32_32x32x16_bf16 v[96:111], v[182:185], v[172:175], v[96:111]
	v_exp_f32_e32 v152, v140
	v_exp_f32_e32 v153, v141
	v_exp_f32_e32 v154, v142
	v_exp_f32_e32 v155, v143
	v_pk_add_f32 v[142:143], v[218:219], v[150:151]
	v_pk_add_f32 v[140:141], v[216:217], v[148:149]
	v_cvt_pk_bf16_f32 v136, v216, v217
	v_cvt_pk_bf16_f32 v137, v218, v219
	v_cvt_pk_bf16_f32 v138, v152, v153
	v_cvt_pk_bf16_f32 v139, v154, v155
	v_pk_add_f32 v[142:143], v[154:155], v[142:143]
	v_pk_add_f32 v[140:141], v[152:153], v[140:141]
	s_waitcnt vmcnt(4) lgkmcnt(0)
	v_add_f32_e32 v148, v176, v177
	v_add_f32_e32 v149, v178, v179
	v_add_f32_e32 v148, v148, v149
	v_add_f32_e32 v140, v140, v141
	v_add_f32_e32 v141, v142, v143
	s_barrier
	v_add_f32_e32 v148, v180, v148
	v_add_f32_e32 v140, v140, v141
	v_add_f32_e32 v180, v148, v140
	s_add_i32 s47, s47, 2
	s_addk_i32 s41, 0x80
	s_add_i32 s46, s46, 0x8000
	s_add_u32 s98, s98, 0x30000
	s_addc_u32 s99, s99, 0
	s_add_u32 s100, s100, 0x100
	s_addc_u32 s101, s101, 0
	s_add_i32 s49, s58, 0x4000
	s_mov_b32 m0, s49
	s_nop 0
	global_load_lds_dwordx4 v198, s[98:99]
	s_add_i32 m0, s49, 0x400
	s_nop 0
	global_load_lds_dwordx4 v194, s[98:99]
	s_add_i32 s49, s46, 0xffffc000
	s_add_i32 s49, s58, 0x4000
	s_add_i32 m0, s49, 0xc000
	s_nop 0
	global_load_lds_dwordx4 v196, s[100:101]
	s_add_i32 m0, s49, 0xc400
	s_nop 0
	global_load_lds_dwordx4 v192, s[100:101]
	ds_read_b128 v[140:143], v236 offset:16384
	ds_read_b128 v[148:151], v236 offset:20480
	ds_read_b128 v[152:155], v236 offset:24576
	ds_read_b128 v[156:159], v236 offset:28672
	s_waitcnt lgkmcnt(0)
	v_mfma_f32_32x32x16_bf16 v[80:95], v[140:143], v[144:147], v[80:95]
	ds_read_b128 v[140:143], v237 offset:16384
	v_mfma_f32_32x32x16_bf16 v[64:79], v[148:151], v[144:147], v[64:79]
	ds_read_b128 v[148:151], v237 offset:20480
	v_mfma_f32_32x32x16_bf16 v[16:31], v[152:155], v[144:147], v[16:31]
	ds_read_b128 v[152:155], v237 offset:24576
	v_mfma_f32_32x32x16_bf16 v[0:15], v[156:159], v[144:147], v[0:15]
	ds_read_b128 v[144:147], v237 offset:28672
	s_waitcnt lgkmcnt(0)
	v_mfma_f32_32x32x16_bf16 v[80:95], v[140:143], v[128:131], v[80:95]
	ds_read_b128 v[140:143], v238 offset:16384
	v_mfma_f32_32x32x16_bf16 v[64:79], v[148:151], v[128:131], v[64:79]
	ds_read_b128 v[148:151], v238 offset:20480
	v_mfma_f32_32x32x16_bf16 v[16:31], v[152:155], v[128:131], v[16:31]
	ds_read_b128 v[152:155], v238 offset:24576
	v_mfma_f32_32x32x16_bf16 v[0:15], v[144:147], v[128:131], v[0:15]
	ds_read_b128 v[128:131], v238 offset:28672
	s_waitcnt lgkmcnt(0)
	v_mfma_f32_32x32x16_bf16 v[80:95], v[140:143], v[132:135], v[80:95]
	ds_read_b128 v[140:143], v239 offset:16384
	v_mfma_f32_32x32x16_bf16 v[64:79], v[148:151], v[132:135], v[64:79]
	ds_read_b128 v[144:147], v239 offset:20480
	v_mfma_f32_32x32x16_bf16 v[16:31], v[152:155], v[132:135], v[16:31]
	ds_read_b128 v[148:151], v239 offset:24576
	v_mfma_f32_32x32x16_bf16 v[0:15], v[128:131], v[132:135], v[0:15]
	ds_read_b128 v[128:131], v239 offset:28672
	s_waitcnt lgkmcnt(0)
	v_mfma_f32_32x32x16_bf16 v[80:95], v[140:143], v[136:139], v[80:95]
	ds_read_b128 v[132:135], v205 offset:32768
	v_mfma_f32_32x32x16_bf16 v[64:79], v[144:147], v[136:139], v[64:79]
	ds_read_b128 v[140:143], v205 offset:40960
	v_mfma_f32_32x32x16_bf16 v[16:31], v[148:151], v[136:139], v[16:31]
	ds_read_b128 v[176:179], v211 offset:32768
	v_mfma_f32_32x32x16_bf16 v[0:15], v[128:131], v[136:139], v[0:15]
	ds_read_b128 v[182:185], v211 offset:40960
	s_waitcnt lgkmcnt(0)
	v_mfma_f32_32x32x16_bf16 v[144:159], v[132:135], v[160:163], 0
	ds_read_b128 v[186:189], v212 offset:32768
	v_exp_f32_e32 v220, v112
	v_exp_f32_e32 v221, v113
	v_exp_f32_e32 v222, v114
	v_exp_f32_e32 v223, v115
	v_mfma_f32_32x32x16_bf16 v[128:143], v[140:143], v[160:163], 0
	ds_read_b128 v[216:219], v212 offset:40960
	v_exp_f32_e32 v224, v116
	v_exp_f32_e32 v225, v117
	v_exp_f32_e32 v226, v118
	v_exp_f32_e32 v227, v119
	v_mfma_f32_32x32x16_bf16 v[144:159], v[176:179], v[164:167], v[144:159]
	ds_read_b128 v[116:119], v213 offset:32768
	v_exp_f32_e32 v228, v120
	v_exp_f32_e32 v229, v121
	v_exp_f32_e32 v230, v122
	v_exp_f32_e32 v231, v123
	v_cvt_pk_bf16_f32 v112, v220, v221
	v_cvt_pk_bf16_f32 v113, v222, v223
	v_cvt_pk_bf16_f32 v114, v224, v225
	v_cvt_pk_bf16_f32 v115, v226, v227
	v_pk_add_f32 v[122:123], v[226:227], v[222:223]
	v_pk_add_f32 v[120:121], v[224:225], v[220:221]
	v_mfma_f32_32x32x16_bf16 v[128:143], v[182:185], v[164:167], v[128:143]
	ds_read_b128 v[176:179], v213 offset:40960
	v_exp_f32_e32 v124, v124
	v_exp_f32_e32 v125, v125
	v_exp_f32_e32 v126, v126
	v_exp_f32_e32 v127, v127
	s_waitcnt lgkmcnt(0)
	v_mfma_f32_32x32x16_bf16 v[144:159], v[186:189], v[168:171], v[144:159]
	v_add_f32_e64 v122, v230, v122
	v_add_f32_e64 v123, v231, v123
	v_add_f32_e64 v120, v228, v120
	v_add_f32_e64 v121, v229, v121
	v_exp_f32_e32 v182, v96
	v_exp_f32_e32 v183, v97
	v_exp_f32_e32 v184, v98
	v_exp_f32_e32 v185, v99
	v_cvt_pk_bf16_f32 v96, v228, v229
	v_cvt_pk_bf16_f32 v97, v230, v231
	v_cvt_pk_bf16_f32 v98, v124, v125
	v_cvt_pk_bf16_f32 v99, v126, v127
	v_pk_add_f32 v[122:123], v[126:127], v[122:123]
	v_pk_add_f32 v[120:121], v[124:125], v[120:121]
	v_mfma_f32_32x32x16_bf16 v[128:143], v[216:219], v[168:171], v[128:143]
	v_exp_f32_e32 v124, v100
	v_exp_f32_e32 v125, v101
	v_exp_f32_e32 v126, v102
	v_exp_f32_e32 v127, v103
	v_mfma_f32_32x32x16_bf16 v[144:159], v[116:119], v[172:175], v[144:159]
	v_exp_f32_e32 v186, v104
	v_exp_f32_e32 v187, v105
	v_exp_f32_e32 v188, v106
	v_exp_f32_e32 v189, v107
	v_pk_add_f32 v[106:107], v[184:185], v[122:123]
	v_pk_add_f32 v[104:105], v[182:183], v[120:121]
	v_cvt_pk_bf16_f32 v100, v182, v183
	v_cvt_pk_bf16_f32 v101, v184, v185
	v_cvt_pk_bf16_f32 v102, v124, v125
	v_cvt_pk_bf16_f32 v103, v126, v127
	v_pk_add_f32 v[118:119], v[126:127], v[106:107]
	v_pk_add_f32 v[116:117], v[124:125], v[104:105]
	v_mfma_f32_32x32x16_bf16 v[128:143], v[176:179], v[172:175], v[128:143]
	v_exp_f32_e32 v120, v108
	v_exp_f32_e32 v121, v109
	v_exp_f32_e32 v122, v110
	v_exp_f32_e32 v123, v111
	v_pk_add_f32 v[110:111], v[188:189], v[118:119]
	v_pk_add_f32 v[108:109], v[186:187], v[116:117]
	v_cvt_pk_bf16_f32 v104, v186, v187
	v_cvt_pk_bf16_f32 v105, v188, v189
	v_cvt_pk_bf16_f32 v106, v120, v121
	v_cvt_pk_bf16_f32 v107, v122, v123
	v_pk_add_f32 v[178:179], v[122:123], v[110:111]
	v_pk_add_f32 v[176:177], v[120:121], v[108:109]
	s_waitcnt vmcnt(4) lgkmcnt(0)
	s_barrier
	s_add_u32 s70, s98, 0x18000
	s_addc_u32 s71, s99, 0
	s_add_i32 s68, 0x8000, s57
	s_mov_b32 m0, s68
	s_nop 0
	global_load_lds_dwordx4 v198, s[70:71]
	s_add_i32 m0, s68, 0x400
	s_nop 0
	global_load_lds_dwordx4 v194, s[70:71]
	s_add_u32 s2, s100, 0x80
	s_addc_u32 s3, s101, 0
	s_add_i32 s49, s58, 0x8000
	s_add_i32 m0, s49, 0xc000
	s_nop 0
	global_load_lds_dwordx4 v196, s[2:3]
	s_add_i32 m0, s49, 0xc400
	s_nop 0
	global_load_lds_dwordx4 v192, s[2:3]
	s_add_i32 s2, s46, 0xffff4000
	ds_read_b128 v[108:111], v236 offset:32768
	ds_read_b128 v[116:119], v236 offset:36864
	ds_read_b128 v[120:123], v236 offset:40960
	ds_read_b128 v[124:127], v236 offset:45056
	s_waitcnt lgkmcnt(0)
	v_mfma_f32_32x32x16_bf16 v[80:95], v[108:111], v[112:115], v[80:95]
	ds_read_b128 v[108:111], v237 offset:32768
	v_mfma_f32_32x32x16_bf16 v[64:79], v[116:119], v[112:115], v[64:79]
	ds_read_b128 v[116:119], v237 offset:36864
	v_mfma_f32_32x32x16_bf16 v[16:31], v[120:123], v[112:115], v[16:31]
	ds_read_b128 v[120:123], v237 offset:40960
	v_mfma_f32_32x32x16_bf16 v[0:15], v[124:127], v[112:115], v[0:15]
	ds_read_b128 v[112:115], v237 offset:45056
	s_waitcnt lgkmcnt(0)
	v_mfma_f32_32x32x16_bf16 v[80:95], v[108:111], v[96:99], v[80:95]
	ds_read_b128 v[108:111], v238 offset:32768
	v_mfma_f32_32x32x16_bf16 v[64:79], v[116:119], v[96:99], v[64:79]
	ds_read_b128 v[116:119], v238 offset:36864
	v_mfma_f32_32x32x16_bf16 v[16:31], v[120:123], v[96:99], v[16:31]
	ds_read_b128 v[120:123], v238 offset:40960
	v_mfma_f32_32x32x16_bf16 v[0:15], v[112:115], v[96:99], v[0:15]
	ds_read_b128 v[96:99], v238 offset:45056
	s_waitcnt lgkmcnt(0)
	v_mfma_f32_32x32x16_bf16 v[80:95], v[108:111], v[100:103], v[80:95]
	ds_read_b128 v[108:111], v239 offset:32768
	v_mfma_f32_32x32x16_bf16 v[64:79], v[116:119], v[100:103], v[64:79]
	ds_read_b128 v[112:115], v239 offset:36864
	v_mfma_f32_32x32x16_bf16 v[16:31], v[120:123], v[100:103], v[16:31]
	ds_read_b128 v[116:119], v239 offset:40960
	v_mfma_f32_32x32x16_bf16 v[0:15], v[96:99], v[100:103], v[0:15]
	ds_read_b128 v[120:123], v239 offset:45056
	s_waitcnt lgkmcnt(0)
	v_mfma_f32_32x32x16_bf16 v[80:95], v[108:111], v[104:107], v[80:95]
	ds_read_b128 v[96:99], v205
	v_mfma_f32_32x32x16_bf16 v[64:79], v[112:115], v[104:107], v[64:79]
	ds_read_b128 v[100:103], v205 offset:8192
	v_mfma_f32_32x32x16_bf16 v[16:31], v[116:119], v[104:107], v[16:31]
	ds_read_b128 v[182:185], v211
	v_mfma_f32_32x32x16_bf16 v[0:15], v[120:123], v[104:107], v[0:15]
	ds_read_b128 v[186:189], v211 offset:8192
	s_waitcnt lgkmcnt(0)
	v_mfma_f32_32x32x16_bf16 v[112:127], v[96:99], v[160:163], 0
	ds_read_b128 v[216:219], v212
	v_exp_f32_e32 v224, v144
	v_exp_f32_e32 v225, v145
	v_exp_f32_e32 v226, v146
	v_exp_f32_e32 v227, v147
	ds_read_b128 v[220:223], v212 offset:8192
	v_mfma_f32_32x32x16_bf16 v[96:111], v[100:103], v[160:163], 0
	v_exp_f32_e32 v228, v148
	v_exp_f32_e32 v229, v149
	v_exp_f32_e32 v230, v150
	v_exp_f32_e32 v231, v151
	v_mfma_f32_32x32x16_bf16 v[112:127], v[182:185], v[164:167], v[112:127]
	ds_read_b128 v[148:151], v213
	v_exp_f32_e32 v232, v152
	v_exp_f32_e32 v233, v153
	v_exp_f32_e32 v234, v154
	v_exp_f32_e32 v235, v155
	v_cvt_pk_bf16_f32 v144, v224, v225
	v_cvt_pk_bf16_f32 v145, v226, v227
	v_cvt_pk_bf16_f32 v146, v228, v229
	v_cvt_pk_bf16_f32 v147, v230, v231
	v_pk_add_f32 v[154:155], v[230:231], v[226:227]
	v_pk_add_f32 v[152:153], v[228:229], v[224:225]
	v_mfma_f32_32x32x16_bf16 v[96:111], v[186:189], v[164:167], v[96:111]
	ds_read_b128 v[182:185], v213 offset:8192
	v_exp_f32_e32 v156, v156
	v_exp_f32_e32 v157, v157
	v_exp_f32_e32 v158, v158
	v_exp_f32_e32 v159, v159
	s_waitcnt lgkmcnt(0)
	v_mfma_f32_32x32x16_bf16 v[112:127], v[216:219], v[168:171], v[112:127]
	v_add_f32_e64 v154, v234, v154
	v_add_f32_e64 v155, v235, v155
	v_add_f32_e64 v152, v232, v152
	v_add_f32_e64 v153, v233, v153
	v_exp_f32_e32 v186, v128
	v_exp_f32_e32 v187, v129
	v_exp_f32_e32 v188, v130
	v_exp_f32_e32 v189, v131
	v_cvt_pk_bf16_f32 v128, v232, v233
	v_cvt_pk_bf16_f32 v129, v234, v235
	v_cvt_pk_bf16_f32 v130, v156, v157
	v_cvt_pk_bf16_f32 v131, v158, v159
	v_pk_add_f32 v[154:155], v[158:159], v[154:155]
	v_pk_add_f32 v[152:153], v[156:157], v[152:153]
	v_mfma_f32_32x32x16_bf16 v[96:111], v[220:223], v[168:171], v[96:111]
	v_exp_f32_e32 v156, v132
	v_exp_f32_e32 v157, v133
	v_exp_f32_e32 v158, v134
	v_exp_f32_e32 v159, v135
	v_mfma_f32_32x32x16_bf16 v[112:127], v[148:151], v[172:175], v[112:127]
	v_exp_f32_e32 v216, v136
	v_exp_f32_e32 v217, v137
	v_exp_f32_e32 v218, v138
	v_exp_f32_e32 v219, v139
	v_pk_add_f32 v[138:139], v[188:189], v[154:155]
	v_pk_add_f32 v[136:137], v[186:187], v[152:153]
	v_cvt_pk_bf16_f32 v132, v186, v187
	v_cvt_pk_bf16_f32 v133, v188, v189
	v_cvt_pk_bf16_f32 v134, v156, v157
	v_cvt_pk_bf16_f32 v135, v158, v159
	v_pk_add_f32 v[150:151], v[158:159], v[138:139]
	v_pk_add_f32 v[148:149], v[156:157], v[136:137]
	v_mfma_f32_32x32x16_bf16 v[96:111], v[182:185], v[172:175], v[96:111]
	v_exp_f32_e32 v152, v140
	v_exp_f32_e32 v153, v141
	v_exp_f32_e32 v154, v142
	v_exp_f32_e32 v155, v143
	v_pk_add_f32 v[142:143], v[218:219], v[150:151]
	v_pk_add_f32 v[140:141], v[216:217], v[148:149]
	v_cvt_pk_bf16_f32 v136, v216, v217
	v_cvt_pk_bf16_f32 v137, v218, v219
	v_cvt_pk_bf16_f32 v138, v152, v153
	v_cvt_pk_bf16_f32 v139, v154, v155
	v_pk_add_f32 v[142:143], v[154:155], v[142:143]
	v_pk_add_f32 v[140:141], v[152:153], v[140:141]
	s_waitcnt vmcnt(4) lgkmcnt(0)
	v_add_f32_e32 v148, v176, v177
	v_add_f32_e32 v149, v178, v179
	v_add_f32_e32 v148, v148, v149
	v_add_f32_e32 v140, v140, v141
	v_add_f32_e32 v141, v142, v143
	s_barrier
	v_add_f32_e32 v148, v180, v148
	v_add_f32_e32 v140, v140, v141
	v_add_f32_e32 v180, v148, v140
	s_add_i32 s47, s47, 2
	s_addk_i32 s41, 0x80
	s_add_i32 s46, s46, 0x8000
	s_add_u32 s98, s98, 0x30000
	s_addc_u32 s99, s99, 0
	s_add_u32 s100, s100, 0x100
	s_addc_u32 s101, s101, 0
	s_add_i32 s49, s58, 0
	s_mov_b32 m0, s49
	s_nop 0
	global_load_lds_dwordx4 v198, s[98:99]
	s_add_i32 m0, s49, 0x400
	s_nop 0
	global_load_lds_dwordx4 v194, s[98:99]
	s_add_i32 s49, s46, 0xffffc000
	s_add_i32 s49, s58, 0xc000
	s_add_i32 m0, s49, 0xc000
	s_nop 0
	global_load_lds_dwordx4 v196, s[100:101]
	s_add_i32 m0, s49, 0xc400
	s_nop 0
	global_load_lds_dwordx4 v192, s[100:101]
	ds_read_b128 v[140:143], v206 offset:49152
	ds_read_b128 v[148:151], v206 offset:53248
	ds_read_b128 v[152:155], v206 offset:57344
	ds_read_b128 v[156:159], v206 offset:61440
	s_waitcnt lgkmcnt(0)
	v_mfma_f32_32x32x16_bf16 v[80:95], v[140:143], v[144:147], v[80:95]
	ds_read_b128 v[140:143], v207 offset:49152
	v_mfma_f32_32x32x16_bf16 v[64:79], v[148:151], v[144:147], v[64:79]
	ds_read_b128 v[148:151], v207 offset:53248
	v_mfma_f32_32x32x16_bf16 v[16:31], v[152:155], v[144:147], v[16:31]
	ds_read_b128 v[152:155], v207 offset:57344
	v_mfma_f32_32x32x16_bf16 v[0:15], v[156:159], v[144:147], v[0:15]
	ds_read_b128 v[144:147], v207 offset:61440
	s_waitcnt lgkmcnt(0)
	v_mfma_f32_32x32x16_bf16 v[80:95], v[140:143], v[128:131], v[80:95]
	ds_read_b128 v[140:143], v208 offset:49152
	v_mfma_f32_32x32x16_bf16 v[64:79], v[148:151], v[128:131], v[64:79]
	ds_read_b128 v[148:151], v208 offset:53248
	v_mfma_f32_32x32x16_bf16 v[16:31], v[152:155], v[128:131], v[16:31]
	ds_read_b128 v[152:155], v208 offset:57344
	v_mfma_f32_32x32x16_bf16 v[0:15], v[144:147], v[128:131], v[0:15]
	ds_read_b128 v[128:131], v208 offset:61440
	s_waitcnt lgkmcnt(0)
	v_mfma_f32_32x32x16_bf16 v[80:95], v[140:143], v[132:135], v[80:95]
	ds_read_b128 v[140:143], v209 offset:49152
	v_mfma_f32_32x32x16_bf16 v[64:79], v[148:151], v[132:135], v[64:79]
	ds_read_b128 v[144:147], v209 offset:53248
	v_mfma_f32_32x32x16_bf16 v[16:31], v[152:155], v[132:135], v[16:31]
	ds_read_b128 v[148:151], v209 offset:57344
	v_mfma_f32_32x32x16_bf16 v[0:15], v[128:131], v[132:135], v[0:15]
	ds_read_b128 v[128:131], v209 offset:61440
	s_waitcnt lgkmcnt(0)
	v_mfma_f32_32x32x16_bf16 v[80:95], v[140:143], v[136:139], v[80:95]
	ds_read_b128 v[132:135], v205 offset:16384
	v_mfma_f32_32x32x16_bf16 v[64:79], v[144:147], v[136:139], v[64:79]
	ds_read_b128 v[140:143], v205 offset:24576
	v_mfma_f32_32x32x16_bf16 v[16:31], v[148:151], v[136:139], v[16:31]
	ds_read_b128 v[176:179], v211 offset:16384
	v_mfma_f32_32x32x16_bf16 v[0:15], v[128:131], v[136:139], v[0:15]
	ds_read_b128 v[182:185], v211 offset:24576
	s_waitcnt lgkmcnt(0)
	v_mfma_f32_32x32x16_bf16 v[144:159], v[132:135], v[160:163], 0
	ds_read_b128 v[186:189], v212 offset:16384
	v_exp_f32_e32 v220, v112
	v_exp_f32_e32 v221, v113
	v_exp_f32_e32 v222, v114
	v_exp_f32_e32 v223, v115
	v_mfma_f32_32x32x16_bf16 v[128:143], v[140:143], v[160:163], 0
	ds_read_b128 v[216:219], v212 offset:24576
	v_exp_f32_e32 v224, v116
	v_exp_f32_e32 v225, v117
	v_exp_f32_e32 v226, v118
	v_exp_f32_e32 v227, v119
	v_mfma_f32_32x32x16_bf16 v[144:159], v[176:179], v[164:167], v[144:159]
	ds_read_b128 v[116:119], v213 offset:16384
	v_exp_f32_e32 v228, v120
	v_exp_f32_e32 v229, v121
	v_exp_f32_e32 v230, v122
	v_exp_f32_e32 v231, v123
	v_cvt_pk_bf16_f32 v112, v220, v221
	v_cvt_pk_bf16_f32 v113, v222, v223
	v_cvt_pk_bf16_f32 v114, v224, v225
	v_cvt_pk_bf16_f32 v115, v226, v227
	v_pk_add_f32 v[122:123], v[226:227], v[222:223]
	v_pk_add_f32 v[120:121], v[224:225], v[220:221]
	v_mfma_f32_32x32x16_bf16 v[128:143], v[182:185], v[164:167], v[128:143]
	ds_read_b128 v[176:179], v213 offset:24576
	v_exp_f32_e32 v124, v124
	v_exp_f32_e32 v125, v125
	v_exp_f32_e32 v126, v126
	v_exp_f32_e32 v127, v127
	s_waitcnt lgkmcnt(0)
	v_mfma_f32_32x32x16_bf16 v[144:159], v[186:189], v[168:171], v[144:159]
	v_add_f32_e64 v122, v230, v122
	v_add_f32_e64 v123, v231, v123
	v_add_f32_e64 v120, v228, v120
	v_add_f32_e64 v121, v229, v121
	v_exp_f32_e32 v182, v96
	v_exp_f32_e32 v183, v97
	v_exp_f32_e32 v184, v98
	v_exp_f32_e32 v185, v99
	v_cvt_pk_bf16_f32 v96, v228, v229
	v_cvt_pk_bf16_f32 v97, v230, v231
	v_cvt_pk_bf16_f32 v98, v124, v125
	v_cvt_pk_bf16_f32 v99, v126, v127
	v_pk_add_f32 v[122:123], v[126:127], v[122:123]
	v_pk_add_f32 v[120:121], v[124:125], v[120:121]
	v_mfma_f32_32x32x16_bf16 v[128:143], v[216:219], v[168:171], v[128:143]
	v_exp_f32_e32 v124, v100
	v_exp_f32_e32 v125, v101
	v_exp_f32_e32 v126, v102
	v_exp_f32_e32 v127, v103
	v_mfma_f32_32x32x16_bf16 v[144:159], v[116:119], v[172:175], v[144:159]
	v_exp_f32_e32 v186, v104
	v_exp_f32_e32 v187, v105
	v_exp_f32_e32 v188, v106
	v_exp_f32_e32 v189, v107
	v_pk_add_f32 v[106:107], v[184:185], v[122:123]
	v_pk_add_f32 v[104:105], v[182:183], v[120:121]
	v_cvt_pk_bf16_f32 v100, v182, v183
	v_cvt_pk_bf16_f32 v101, v184, v185
	v_cvt_pk_bf16_f32 v102, v124, v125
	v_cvt_pk_bf16_f32 v103, v126, v127
	v_pk_add_f32 v[118:119], v[126:127], v[106:107]
	v_pk_add_f32 v[116:117], v[124:125], v[104:105]
	v_mfma_f32_32x32x16_bf16 v[128:143], v[176:179], v[172:175], v[128:143]
	v_exp_f32_e32 v120, v108
	v_exp_f32_e32 v121, v109
	v_exp_f32_e32 v122, v110
	v_exp_f32_e32 v123, v111
	v_pk_add_f32 v[110:111], v[188:189], v[118:119]
	v_pk_add_f32 v[108:109], v[186:187], v[116:117]
	v_cvt_pk_bf16_f32 v104, v186, v187
	v_cvt_pk_bf16_f32 v105, v188, v189
	v_cvt_pk_bf16_f32 v106, v120, v121
	v_cvt_pk_bf16_f32 v107, v122, v123
	v_pk_add_f32 v[178:179], v[122:123], v[110:111]
	v_pk_add_f32 v[176:177], v[120:121], v[108:109]
	s_waitcnt vmcnt(4) lgkmcnt(0)
	s_barrier
	s_add_u32 s70, s98, 0x18000
	s_addc_u32 s71, s99, 0
	s_add_i32 s68, 0x4000, s57
	s_mov_b32 m0, s68
	s_nop 0
	global_load_lds_dwordx4 v198, s[70:71]
	s_add_i32 m0, s68, 0x400
	s_nop 0
	global_load_lds_dwordx4 v194, s[70:71]
	s_add_u32 s2, s100, 0x80
	s_addc_u32 s3, s101, 0
	s_add_i32 s49, s58, 0
	s_add_i32 m0, s49, 0xc000
	s_nop 0
	global_load_lds_dwordx4 v196, s[2:3]
	s_add_i32 m0, s49, 0xc400
	s_nop 0
	global_load_lds_dwordx4 v192, s[2:3]
	s_add_i32 s2, s46, 0xffff4000
	ds_read_b128 v[108:111], v236
	ds_read_b128 v[116:119], v236 offset:4096
	ds_read_b128 v[120:123], v236 offset:8192
	ds_read_b128 v[124:127], v236 offset:12288
	s_waitcnt lgkmcnt(0)
	v_mfma_f32_32x32x16_bf16 v[80:95], v[108:111], v[112:115], v[80:95]
	ds_read_b128 v[108:111], v237
	v_mfma_f32_32x32x16_bf16 v[64:79], v[116:119], v[112:115], v[64:79]
	ds_read_b128 v[116:119], v237 offset:4096
	v_mfma_f32_32x32x16_bf16 v[16:31], v[120:123], v[112:115], v[16:31]
	ds_read_b128 v[120:123], v237 offset:8192
	v_mfma_f32_32x32x16_bf16 v[0:15], v[124:127], v[112:115], v[0:15]
	ds_read_b128 v[112:115], v237 offset:12288
	s_waitcnt lgkmcnt(0)
	v_mfma_f32_32x32x16_bf16 v[80:95], v[108:111], v[96:99], v[80:95]
	ds_read_b128 v[108:111], v238
	v_mfma_f32_32x32x16_bf16 v[64:79], v[116:119], v[96:99], v[64:79]
	ds_read_b128 v[116:119], v238 offset:4096
	v_mfma_f32_32x32x16_bf16 v[16:31], v[120:123], v[96:99], v[16:31]
	ds_read_b128 v[120:123], v238 offset:8192
	v_mfma_f32_32x32x16_bf16 v[0:15], v[112:115], v[96:99], v[0:15]
	ds_read_b128 v[96:99], v238 offset:12288
	s_waitcnt lgkmcnt(0)
	v_mfma_f32_32x32x16_bf16 v[80:95], v[108:111], v[100:103], v[80:95]
	ds_read_b128 v[108:111], v239
	v_mfma_f32_32x32x16_bf16 v[64:79], v[116:119], v[100:103], v[64:79]
	ds_read_b128 v[112:115], v239 offset:4096
	v_mfma_f32_32x32x16_bf16 v[16:31], v[120:123], v[100:103], v[16:31]
	ds_read_b128 v[116:119], v239 offset:8192
	v_mfma_f32_32x32x16_bf16 v[0:15], v[96:99], v[100:103], v[0:15]
	ds_read_b128 v[120:123], v239 offset:12288
	s_waitcnt lgkmcnt(0)
	v_mfma_f32_32x32x16_bf16 v[80:95], v[108:111], v[104:107], v[80:95]
	ds_read_b128 v[96:99], v205 offset:32768
	v_mfma_f32_32x32x16_bf16 v[64:79], v[112:115], v[104:107], v[64:79]
	ds_read_b128 v[100:103], v205 offset:40960
	v_mfma_f32_32x32x16_bf16 v[16:31], v[116:119], v[104:107], v[16:31]
	ds_read_b128 v[182:185], v211 offset:32768
	v_mfma_f32_32x32x16_bf16 v[0:15], v[120:123], v[104:107], v[0:15]
	ds_read_b128 v[186:189], v211 offset:40960
	s_waitcnt lgkmcnt(0)
	v_mfma_f32_32x32x16_bf16 v[112:127], v[96:99], v[160:163], 0
	ds_read_b128 v[216:219], v212 offset:32768
	v_exp_f32_e32 v224, v144
	v_exp_f32_e32 v225, v145
	v_exp_f32_e32 v226, v146
	v_exp_f32_e32 v227, v147
	ds_read_b128 v[220:223], v212 offset:40960
	v_mfma_f32_32x32x16_bf16 v[96:111], v[100:103], v[160:163], 0
	v_exp_f32_e32 v228, v148
	v_exp_f32_e32 v229, v149
	v_exp_f32_e32 v230, v150
	v_exp_f32_e32 v231, v151
	v_mfma_f32_32x32x16_bf16 v[112:127], v[182:185], v[164:167], v[112:127]
	ds_read_b128 v[148:151], v213 offset:32768
	v_exp_f32_e32 v232, v152
	v_exp_f32_e32 v233, v153
	v_exp_f32_e32 v234, v154
	v_exp_f32_e32 v235, v155
	v_cvt_pk_bf16_f32 v144, v224, v225
	v_cvt_pk_bf16_f32 v145, v226, v227
	v_cvt_pk_bf16_f32 v146, v228, v229
	v_cvt_pk_bf16_f32 v147, v230, v231
	v_pk_add_f32 v[154:155], v[230:231], v[226:227]
	v_pk_add_f32 v[152:153], v[228:229], v[224:225]
	v_mfma_f32_32x32x16_bf16 v[96:111], v[186:189], v[164:167], v[96:111]
	ds_read_b128 v[182:185], v213 offset:40960
	v_exp_f32_e32 v156, v156
	v_exp_f32_e32 v157, v157
	v_exp_f32_e32 v158, v158
	v_exp_f32_e32 v159, v159
	s_waitcnt lgkmcnt(0)
	v_mfma_f32_32x32x16_bf16 v[112:127], v[216:219], v[168:171], v[112:127]
	v_add_f32_e64 v154, v234, v154
	v_add_f32_e64 v155, v235, v155
	v_add_f32_e64 v152, v232, v152
	v_add_f32_e64 v153, v233, v153
	v_exp_f32_e32 v186, v128
	v_exp_f32_e32 v187, v129
	v_exp_f32_e32 v188, v130
	v_exp_f32_e32 v189, v131
	v_cvt_pk_bf16_f32 v128, v232, v233
	v_cvt_pk_bf16_f32 v129, v234, v235
	v_cvt_pk_bf16_f32 v130, v156, v157
	v_cvt_pk_bf16_f32 v131, v158, v159
	v_pk_add_f32 v[154:155], v[158:159], v[154:155]
	v_pk_add_f32 v[152:153], v[156:157], v[152:153]
	v_mfma_f32_32x32x16_bf16 v[96:111], v[220:223], v[168:171], v[96:111]
	v_exp_f32_e32 v156, v132
	v_exp_f32_e32 v157, v133
	v_exp_f32_e32 v158, v134
	v_exp_f32_e32 v159, v135
	v_mfma_f32_32x32x16_bf16 v[112:127], v[148:151], v[172:175], v[112:127]
	v_exp_f32_e32 v216, v136
	v_exp_f32_e32 v217, v137
	v_exp_f32_e32 v218, v138
	v_exp_f32_e32 v219, v139
	v_pk_add_f32 v[138:139], v[188:189], v[154:155]
	v_pk_add_f32 v[136:137], v[186:187], v[152:153]
	v_cvt_pk_bf16_f32 v132, v186, v187
	v_cvt_pk_bf16_f32 v133, v188, v189
	v_cvt_pk_bf16_f32 v134, v156, v157
	v_cvt_pk_bf16_f32 v135, v158, v159
	v_pk_add_f32 v[150:151], v[158:159], v[138:139]
	v_pk_add_f32 v[148:149], v[156:157], v[136:137]
	v_mfma_f32_32x32x16_bf16 v[96:111], v[182:185], v[172:175], v[96:111]
	v_exp_f32_e32 v152, v140
	v_exp_f32_e32 v153, v141
	v_exp_f32_e32 v154, v142
	v_exp_f32_e32 v155, v143
	v_pk_add_f32 v[142:143], v[218:219], v[150:151]
	v_pk_add_f32 v[140:141], v[216:217], v[148:149]
	v_cvt_pk_bf16_f32 v136, v216, v217
	v_cvt_pk_bf16_f32 v137, v218, v219
	v_cvt_pk_bf16_f32 v138, v152, v153
	v_cvt_pk_bf16_f32 v139, v154, v155
	v_pk_add_f32 v[142:143], v[154:155], v[142:143]
	v_pk_add_f32 v[140:141], v[152:153], v[140:141]
	s_waitcnt vmcnt(4) lgkmcnt(0)
	v_add_f32_e32 v148, v176, v177
	v_add_f32_e32 v149, v178, v179
	v_add_f32_e32 v148, v148, v149
	v_add_f32_e32 v140, v140, v141
	v_add_f32_e32 v141, v142, v143
	s_barrier
	v_add_f32_e32 v148, v180, v148
	v_add_f32_e32 v140, v140, v141
	v_add_f32_e32 v180, v148, v140
	s_add_i32 s47, s47, 2
	s_addk_i32 s41, 0x80
	s_add_i32 s46, s46, 0x8000
	s_add_u32 s98, s98, 0x30000
	s_addc_u32 s99, s99, 0
	s_add_u32 s100, s100, 0x100
	s_addc_u32 s101, s101, 0
	s_add_i32 s49, s58, 0x8000
	s_mov_b32 m0, s49
	s_nop 0
	global_load_lds_dwordx4 v198, s[98:99]
	s_add_i32 m0, s49, 0x400
	s_nop 0
	global_load_lds_dwordx4 v194, s[98:99]
	s_add_i32 s49, s46, 0xffffc000
	s_add_i32 s49, s58, 0x4000
	s_add_i32 m0, s49, 0xc000
	s_nop 0
	global_load_lds_dwordx4 v196, s[100:101]
	s_add_i32 m0, s49, 0xc400
	s_nop 0
	global_load_lds_dwordx4 v192, s[100:101]
	ds_read_b128 v[140:143], v236 offset:16384
	ds_read_b128 v[148:151], v236 offset:20480
	ds_read_b128 v[152:155], v236 offset:24576
	ds_read_b128 v[156:159], v236 offset:28672
	s_waitcnt lgkmcnt(0)
	v_mfma_f32_32x32x16_bf16 v[80:95], v[140:143], v[144:147], v[80:95]
	ds_read_b128 v[140:143], v237 offset:16384
	v_mfma_f32_32x32x16_bf16 v[64:79], v[148:151], v[144:147], v[64:79]
	ds_read_b128 v[148:151], v237 offset:20480
	v_mfma_f32_32x32x16_bf16 v[16:31], v[152:155], v[144:147], v[16:31]
	ds_read_b128 v[152:155], v237 offset:24576
	v_mfma_f32_32x32x16_bf16 v[0:15], v[156:159], v[144:147], v[0:15]
	ds_read_b128 v[144:147], v237 offset:28672
	s_waitcnt lgkmcnt(0)
	v_mfma_f32_32x32x16_bf16 v[80:95], v[140:143], v[128:131], v[80:95]
	ds_read_b128 v[140:143], v238 offset:16384
	v_mfma_f32_32x32x16_bf16 v[64:79], v[148:151], v[128:131], v[64:79]
	ds_read_b128 v[148:151], v238 offset:20480
	v_mfma_f32_32x32x16_bf16 v[16:31], v[152:155], v[128:131], v[16:31]
	ds_read_b128 v[152:155], v238 offset:24576
	v_mfma_f32_32x32x16_bf16 v[0:15], v[144:147], v[128:131], v[0:15]
	ds_read_b128 v[128:131], v238 offset:28672
	s_waitcnt lgkmcnt(0)
	v_mfma_f32_32x32x16_bf16 v[80:95], v[140:143], v[132:135], v[80:95]
	ds_read_b128 v[140:143], v239 offset:16384
	v_mfma_f32_32x32x16_bf16 v[64:79], v[148:151], v[132:135], v[64:79]
	ds_read_b128 v[144:147], v239 offset:20480
	v_mfma_f32_32x32x16_bf16 v[16:31], v[152:155], v[132:135], v[16:31]
	ds_read_b128 v[148:151], v239 offset:24576
	v_mfma_f32_32x32x16_bf16 v[0:15], v[128:131], v[132:135], v[0:15]
	ds_read_b128 v[128:131], v239 offset:28672
	s_waitcnt lgkmcnt(0)
	v_mfma_f32_32x32x16_bf16 v[80:95], v[140:143], v[136:139], v[80:95]
	ds_read_b128 v[132:135], v205
	v_mfma_f32_32x32x16_bf16 v[64:79], v[144:147], v[136:139], v[64:79]
	ds_read_b128 v[140:143], v205 offset:8192
	v_mfma_f32_32x32x16_bf16 v[16:31], v[148:151], v[136:139], v[16:31]
	ds_read_b128 v[176:179], v211
	v_mfma_f32_32x32x16_bf16 v[0:15], v[128:131], v[136:139], v[0:15]
	ds_read_b128 v[182:185], v211 offset:8192
	s_waitcnt lgkmcnt(0)
	v_mfma_f32_32x32x16_bf16 v[144:159], v[132:135], v[160:163], 0
	ds_read_b128 v[186:189], v212
	v_exp_f32_e32 v220, v112
	v_exp_f32_e32 v221, v113
	v_exp_f32_e32 v222, v114
	v_exp_f32_e32 v223, v115
	v_mfma_f32_32x32x16_bf16 v[128:143], v[140:143], v[160:163], 0
	ds_read_b128 v[216:219], v212 offset:8192
	v_exp_f32_e32 v224, v116
	v_exp_f32_e32 v225, v117
	v_exp_f32_e32 v226, v118
	v_exp_f32_e32 v227, v119
	v_mfma_f32_32x32x16_bf16 v[144:159], v[176:179], v[164:167], v[144:159]
	ds_read_b128 v[116:119], v213
	v_exp_f32_e32 v228, v120
	v_exp_f32_e32 v229, v121
	v_exp_f32_e32 v230, v122
	v_exp_f32_e32 v231, v123
	v_cvt_pk_bf16_f32 v112, v220, v221
	v_cvt_pk_bf16_f32 v113, v222, v223
	v_cvt_pk_bf16_f32 v114, v224, v225
	v_cvt_pk_bf16_f32 v115, v226, v227
	v_pk_add_f32 v[122:123], v[226:227], v[222:223]
	v_pk_add_f32 v[120:121], v[224:225], v[220:221]
	v_mfma_f32_32x32x16_bf16 v[128:143], v[182:185], v[164:167], v[128:143]
	ds_read_b128 v[176:179], v213 offset:8192
	v_exp_f32_e32 v124, v124
	v_exp_f32_e32 v125, v125
	v_exp_f32_e32 v126, v126
	v_exp_f32_e32 v127, v127
	s_waitcnt lgkmcnt(0)
	v_mfma_f32_32x32x16_bf16 v[144:159], v[186:189], v[168:171], v[144:159]
	v_add_f32_e64 v122, v230, v122
	v_add_f32_e64 v123, v231, v123
	v_add_f32_e64 v120, v228, v120
	v_add_f32_e64 v121, v229, v121
	v_exp_f32_e32 v182, v96
	v_exp_f32_e32 v183, v97
	v_exp_f32_e32 v184, v98
	v_exp_f32_e32 v185, v99
	v_cvt_pk_bf16_f32 v96, v228, v229
	v_cvt_pk_bf16_f32 v97, v230, v231
	v_cvt_pk_bf16_f32 v98, v124, v125
	v_cvt_pk_bf16_f32 v99, v126, v127
	v_pk_add_f32 v[122:123], v[126:127], v[122:123]
	v_pk_add_f32 v[120:121], v[124:125], v[120:121]
	v_mfma_f32_32x32x16_bf16 v[128:143], v[216:219], v[168:171], v[128:143]
	v_exp_f32_e32 v124, v100
	v_exp_f32_e32 v125, v101
	v_exp_f32_e32 v126, v102
	v_exp_f32_e32 v127, v103
	v_mfma_f32_32x32x16_bf16 v[144:159], v[116:119], v[172:175], v[144:159]
	v_exp_f32_e32 v186, v104
	v_exp_f32_e32 v187, v105
	v_exp_f32_e32 v188, v106
	v_exp_f32_e32 v189, v107
	v_pk_add_f32 v[106:107], v[184:185], v[122:123]
	v_pk_add_f32 v[104:105], v[182:183], v[120:121]
	v_cvt_pk_bf16_f32 v100, v182, v183
	v_cvt_pk_bf16_f32 v101, v184, v185
	v_cvt_pk_bf16_f32 v102, v124, v125
	v_cvt_pk_bf16_f32 v103, v126, v127
	v_pk_add_f32 v[118:119], v[126:127], v[106:107]
	v_pk_add_f32 v[116:117], v[124:125], v[104:105]
	v_mfma_f32_32x32x16_bf16 v[128:143], v[176:179], v[172:175], v[128:143]
	v_exp_f32_e32 v120, v108
	v_exp_f32_e32 v121, v109
	v_exp_f32_e32 v122, v110
	v_exp_f32_e32 v123, v111
	v_pk_add_f32 v[110:111], v[188:189], v[118:119]
	v_pk_add_f32 v[108:109], v[186:187], v[116:117]
	v_cvt_pk_bf16_f32 v104, v186, v187
	v_cvt_pk_bf16_f32 v105, v188, v189
	v_cvt_pk_bf16_f32 v106, v120, v121
	v_cvt_pk_bf16_f32 v107, v122, v123
	v_pk_add_f32 v[178:179], v[122:123], v[110:111]
	v_pk_add_f32 v[176:177], v[120:121], v[108:109]
	s_waitcnt vmcnt(4) lgkmcnt(0)
	s_barrier
	s_add_u32 s70, s98, 0x18000
	s_addc_u32 s71, s99, 0
	s_add_i32 s68, 0, s57
	s_mov_b32 m0, s68
	s_nop 0
	global_load_lds_dwordx4 v198, s[70:71]
	s_add_i32 m0, s68, 0x400
	s_nop 0
	global_load_lds_dwordx4 v194, s[70:71]
	s_add_u32 s2, s100, 0x80
	s_addc_u32 s3, s101, 0
	s_add_i32 s49, s58, 0x8000
	s_add_i32 m0, s49, 0xc000
	s_nop 0
	global_load_lds_dwordx4 v196, s[2:3]
	s_add_i32 m0, s49, 0xc400
	s_nop 0
	global_load_lds_dwordx4 v192, s[2:3]
	s_add_i32 s2, s46, 0xffff4000
	ds_read_b128 v[108:111], v236 offset:32768
	ds_read_b128 v[116:119], v236 offset:36864
	ds_read_b128 v[120:123], v236 offset:40960
	ds_read_b128 v[124:127], v236 offset:45056
	s_waitcnt lgkmcnt(0)
	v_mfma_f32_32x32x16_bf16 v[80:95], v[108:111], v[112:115], v[80:95]
	ds_read_b128 v[108:111], v237 offset:32768
	v_mfma_f32_32x32x16_bf16 v[64:79], v[116:119], v[112:115], v[64:79]
	ds_read_b128 v[116:119], v237 offset:36864
	v_mfma_f32_32x32x16_bf16 v[16:31], v[120:123], v[112:115], v[16:31]
	ds_read_b128 v[120:123], v237 offset:40960
	v_mfma_f32_32x32x16_bf16 v[0:15], v[124:127], v[112:115], v[0:15]
	ds_read_b128 v[112:115], v237 offset:45056
	s_waitcnt lgkmcnt(0)
	v_mfma_f32_32x32x16_bf16 v[80:95], v[108:111], v[96:99], v[80:95]
	ds_read_b128 v[108:111], v238 offset:32768
	v_mfma_f32_32x32x16_bf16 v[64:79], v[116:119], v[96:99], v[64:79]
	ds_read_b128 v[116:119], v238 offset:36864
	v_mfma_f32_32x32x16_bf16 v[16:31], v[120:123], v[96:99], v[16:31]
	ds_read_b128 v[120:123], v238 offset:40960
	v_mfma_f32_32x32x16_bf16 v[0:15], v[112:115], v[96:99], v[0:15]
	ds_read_b128 v[96:99], v238 offset:45056
	s_waitcnt lgkmcnt(0)
	v_mfma_f32_32x32x16_bf16 v[80:95], v[108:111], v[100:103], v[80:95]
	ds_read_b128 v[108:111], v239 offset:32768
	v_mfma_f32_32x32x16_bf16 v[64:79], v[116:119], v[100:103], v[64:79]
	ds_read_b128 v[112:115], v239 offset:36864
	v_mfma_f32_32x32x16_bf16 v[16:31], v[120:123], v[100:103], v[16:31]
	ds_read_b128 v[116:119], v239 offset:40960
	v_mfma_f32_32x32x16_bf16 v[0:15], v[96:99], v[100:103], v[0:15]
	ds_read_b128 v[120:123], v239 offset:45056
	s_waitcnt lgkmcnt(0)
	v_mfma_f32_32x32x16_bf16 v[80:95], v[108:111], v[104:107], v[80:95]
	ds_read_b128 v[96:99], v205 offset:16384
	v_mfma_f32_32x32x16_bf16 v[64:79], v[112:115], v[104:107], v[64:79]
	ds_read_b128 v[100:103], v205 offset:24576
	v_mfma_f32_32x32x16_bf16 v[16:31], v[116:119], v[104:107], v[16:31]
	ds_read_b128 v[182:185], v211 offset:16384
	v_mfma_f32_32x32x16_bf16 v[0:15], v[120:123], v[104:107], v[0:15]
	ds_read_b128 v[186:189], v211 offset:24576
	s_waitcnt lgkmcnt(0)
	v_mfma_f32_32x32x16_bf16 v[112:127], v[96:99], v[160:163], 0
	ds_read_b128 v[216:219], v212 offset:16384
	v_exp_f32_e32 v224, v144
	v_exp_f32_e32 v225, v145
	v_exp_f32_e32 v226, v146
	v_exp_f32_e32 v227, v147
	ds_read_b128 v[220:223], v212 offset:24576
	v_mfma_f32_32x32x16_bf16 v[96:111], v[100:103], v[160:163], 0
	v_exp_f32_e32 v228, v148
	v_exp_f32_e32 v229, v149
	v_exp_f32_e32 v230, v150
	v_exp_f32_e32 v231, v151
	v_mfma_f32_32x32x16_bf16 v[112:127], v[182:185], v[164:167], v[112:127]
	ds_read_b128 v[148:151], v213 offset:16384
	v_exp_f32_e32 v232, v152
	v_exp_f32_e32 v233, v153
	v_exp_f32_e32 v234, v154
	v_exp_f32_e32 v235, v155
	v_cvt_pk_bf16_f32 v144, v224, v225
	v_cvt_pk_bf16_f32 v145, v226, v227
	v_cvt_pk_bf16_f32 v146, v228, v229
	v_cvt_pk_bf16_f32 v147, v230, v231
	v_pk_add_f32 v[154:155], v[230:231], v[226:227]
	v_pk_add_f32 v[152:153], v[228:229], v[224:225]
	v_mfma_f32_32x32x16_bf16 v[96:111], v[186:189], v[164:167], v[96:111]
	ds_read_b128 v[182:185], v213 offset:24576
	v_exp_f32_e32 v156, v156
	v_exp_f32_e32 v157, v157
	v_exp_f32_e32 v158, v158
	v_exp_f32_e32 v159, v159
	s_waitcnt lgkmcnt(0)
	v_mfma_f32_32x32x16_bf16 v[112:127], v[216:219], v[168:171], v[112:127]
	v_add_f32_e64 v154, v234, v154
	v_add_f32_e64 v155, v235, v155
	v_add_f32_e64 v152, v232, v152
	v_add_f32_e64 v153, v233, v153
	v_exp_f32_e32 v186, v128
	v_exp_f32_e32 v187, v129
	v_exp_f32_e32 v188, v130
	v_exp_f32_e32 v189, v131
	v_cvt_pk_bf16_f32 v128, v232, v233
	v_cvt_pk_bf16_f32 v129, v234, v235
	v_cvt_pk_bf16_f32 v130, v156, v157
	v_cvt_pk_bf16_f32 v131, v158, v159
	v_pk_add_f32 v[154:155], v[158:159], v[154:155]
	v_pk_add_f32 v[152:153], v[156:157], v[152:153]
	v_mfma_f32_32x32x16_bf16 v[96:111], v[220:223], v[168:171], v[96:111]
	v_exp_f32_e32 v156, v132
	v_exp_f32_e32 v157, v133
	v_exp_f32_e32 v158, v134
	v_exp_f32_e32 v159, v135
	v_mfma_f32_32x32x16_bf16 v[112:127], v[148:151], v[172:175], v[112:127]
	v_exp_f32_e32 v216, v136
	v_exp_f32_e32 v217, v137
	v_exp_f32_e32 v218, v138
	v_exp_f32_e32 v219, v139
	v_pk_add_f32 v[138:139], v[188:189], v[154:155]
	v_pk_add_f32 v[136:137], v[186:187], v[152:153]
	v_cvt_pk_bf16_f32 v132, v186, v187
	v_cvt_pk_bf16_f32 v133, v188, v189
	v_cvt_pk_bf16_f32 v134, v156, v157
	v_cvt_pk_bf16_f32 v135, v158, v159
	v_pk_add_f32 v[150:151], v[158:159], v[138:139]
	v_pk_add_f32 v[148:149], v[156:157], v[136:137]
	v_mfma_f32_32x32x16_bf16 v[96:111], v[182:185], v[172:175], v[96:111]
	v_exp_f32_e32 v152, v140
	v_exp_f32_e32 v153, v141
	v_exp_f32_e32 v154, v142
	v_exp_f32_e32 v155, v143
	v_pk_add_f32 v[142:143], v[218:219], v[150:151]
	v_pk_add_f32 v[140:141], v[216:217], v[148:149]
	v_cvt_pk_bf16_f32 v136, v216, v217
	v_cvt_pk_bf16_f32 v137, v218, v219
	v_cvt_pk_bf16_f32 v138, v152, v153
	v_cvt_pk_bf16_f32 v139, v154, v155
	v_pk_add_f32 v[142:143], v[154:155], v[142:143]
	v_pk_add_f32 v[140:141], v[152:153], v[140:141]
	s_waitcnt vmcnt(4) lgkmcnt(0)
	v_add_f32_e32 v148, v176, v177
	v_add_f32_e32 v149, v178, v179
	v_add_f32_e32 v148, v148, v149
	v_add_f32_e32 v140, v140, v141
	v_add_f32_e32 v141, v142, v143
	s_barrier
	v_add_f32_e32 v148, v180, v148
	v_add_f32_e32 v140, v140, v141
	v_add_f32_e32 v180, v148, v140
	s_add_i32 s47, s47, 2
	s_addk_i32 s41, 0x80
	s_add_i32 s46, s46, 0x8000
	s_add_u32 s98, s98, 0x30000
	s_addc_u32 s99, s99, 0
	s_add_u32 s100, s100, 0x100
	s_addc_u32 s101, s101, 0
	s_add_i32 s49, s58, 0x4000
	s_mov_b32 m0, s49
	s_nop 0
	global_load_lds_dwordx4 v198, s[98:99]
	s_add_i32 m0, s49, 0x400
	s_nop 0
	global_load_lds_dwordx4 v194, s[98:99]
	s_add_i32 s49, s46, 0xffffc000
	s_add_i32 s49, s58, 0xc000
	s_add_i32 m0, s49, 0xc000
	s_nop 0
	global_load_lds_dwordx4 v196, s[100:101]
	s_add_i32 m0, s49, 0xc400
	s_nop 0
	global_load_lds_dwordx4 v192, s[100:101]
	ds_read_b128 v[140:143], v206 offset:49152
	ds_read_b128 v[148:151], v206 offset:53248
	ds_read_b128 v[152:155], v206 offset:57344
	ds_read_b128 v[156:159], v206 offset:61440
	s_waitcnt lgkmcnt(0)
	v_mfma_f32_32x32x16_bf16 v[80:95], v[140:143], v[144:147], v[80:95]
	ds_read_b128 v[140:143], v207 offset:49152
	v_mfma_f32_32x32x16_bf16 v[64:79], v[148:151], v[144:147], v[64:79]
	ds_read_b128 v[148:151], v207 offset:53248
	v_mfma_f32_32x32x16_bf16 v[16:31], v[152:155], v[144:147], v[16:31]
	ds_read_b128 v[152:155], v207 offset:57344
	v_mfma_f32_32x32x16_bf16 v[0:15], v[156:159], v[144:147], v[0:15]
	ds_read_b128 v[144:147], v207 offset:61440
	s_waitcnt lgkmcnt(0)
	v_mfma_f32_32x32x16_bf16 v[80:95], v[140:143], v[128:131], v[80:95]
	ds_read_b128 v[140:143], v208 offset:49152
	v_mfma_f32_32x32x16_bf16 v[64:79], v[148:151], v[128:131], v[64:79]
	ds_read_b128 v[148:151], v208 offset:53248
	v_mfma_f32_32x32x16_bf16 v[16:31], v[152:155], v[128:131], v[16:31]
	ds_read_b128 v[152:155], v208 offset:57344
	v_mfma_f32_32x32x16_bf16 v[0:15], v[144:147], v[128:131], v[0:15]
	ds_read_b128 v[128:131], v208 offset:61440
	s_waitcnt lgkmcnt(0)
	v_mfma_f32_32x32x16_bf16 v[80:95], v[140:143], v[132:135], v[80:95]
	ds_read_b128 v[140:143], v209 offset:49152
	v_mfma_f32_32x32x16_bf16 v[64:79], v[148:151], v[132:135], v[64:79]
	ds_read_b128 v[144:147], v209 offset:53248
	v_mfma_f32_32x32x16_bf16 v[16:31], v[152:155], v[132:135], v[16:31]
	ds_read_b128 v[148:151], v209 offset:57344
	v_mfma_f32_32x32x16_bf16 v[0:15], v[128:131], v[132:135], v[0:15]
	ds_read_b128 v[128:131], v209 offset:61440
	s_waitcnt lgkmcnt(0)
	v_mfma_f32_32x32x16_bf16 v[80:95], v[140:143], v[136:139], v[80:95]
	ds_read_b128 v[132:135], v205 offset:32768
	v_mfma_f32_32x32x16_bf16 v[64:79], v[144:147], v[136:139], v[64:79]
	ds_read_b128 v[140:143], v205 offset:40960
	v_mfma_f32_32x32x16_bf16 v[16:31], v[148:151], v[136:139], v[16:31]
	ds_read_b128 v[176:179], v211 offset:32768
	v_mfma_f32_32x32x16_bf16 v[0:15], v[128:131], v[136:139], v[0:15]
	ds_read_b128 v[182:185], v211 offset:40960
	s_waitcnt lgkmcnt(0)
	v_mfma_f32_32x32x16_bf16 v[144:159], v[132:135], v[160:163], 0
	ds_read_b128 v[186:189], v212 offset:32768
	v_exp_f32_e32 v220, v112
	v_exp_f32_e32 v221, v113
	v_exp_f32_e32 v222, v114
	v_exp_f32_e32 v223, v115
	v_mfma_f32_32x32x16_bf16 v[128:143], v[140:143], v[160:163], 0
	ds_read_b128 v[216:219], v212 offset:40960
	v_exp_f32_e32 v224, v116
	v_exp_f32_e32 v225, v117
	v_exp_f32_e32 v226, v118
	v_exp_f32_e32 v227, v119
	v_mfma_f32_32x32x16_bf16 v[144:159], v[176:179], v[164:167], v[144:159]
	ds_read_b128 v[116:119], v213 offset:32768
	v_exp_f32_e32 v228, v120
	v_exp_f32_e32 v229, v121
	v_exp_f32_e32 v230, v122
	v_exp_f32_e32 v231, v123
	v_cvt_pk_bf16_f32 v112, v220, v221
	v_cvt_pk_bf16_f32 v113, v222, v223
	v_cvt_pk_bf16_f32 v114, v224, v225
	v_cvt_pk_bf16_f32 v115, v226, v227
	v_pk_add_f32 v[122:123], v[226:227], v[222:223]
	v_pk_add_f32 v[120:121], v[224:225], v[220:221]
	v_mfma_f32_32x32x16_bf16 v[128:143], v[182:185], v[164:167], v[128:143]
	ds_read_b128 v[176:179], v213 offset:40960
	v_exp_f32_e32 v124, v124
	v_exp_f32_e32 v125, v125
	v_exp_f32_e32 v126, v126
	v_exp_f32_e32 v127, v127
	s_waitcnt lgkmcnt(0)
	v_mfma_f32_32x32x16_bf16 v[144:159], v[186:189], v[168:171], v[144:159]
	v_add_f32_e64 v122, v230, v122
	v_add_f32_e64 v123, v231, v123
	v_add_f32_e64 v120, v228, v120
	v_add_f32_e64 v121, v229, v121
	v_exp_f32_e32 v182, v96
	v_exp_f32_e32 v183, v97
	v_exp_f32_e32 v184, v98
	v_exp_f32_e32 v185, v99
	v_cvt_pk_bf16_f32 v96, v228, v229
	v_cvt_pk_bf16_f32 v97, v230, v231
	v_cvt_pk_bf16_f32 v98, v124, v125
	v_cvt_pk_bf16_f32 v99, v126, v127
	v_pk_add_f32 v[122:123], v[126:127], v[122:123]
	v_pk_add_f32 v[120:121], v[124:125], v[120:121]
	v_mfma_f32_32x32x16_bf16 v[128:143], v[216:219], v[168:171], v[128:143]
	v_exp_f32_e32 v124, v100
	v_exp_f32_e32 v125, v101
	v_exp_f32_e32 v126, v102
	v_exp_f32_e32 v127, v103
	v_mfma_f32_32x32x16_bf16 v[144:159], v[116:119], v[172:175], v[144:159]
	v_exp_f32_e32 v186, v104
	v_exp_f32_e32 v187, v105
	v_exp_f32_e32 v188, v106
	v_exp_f32_e32 v189, v107
	v_pk_add_f32 v[106:107], v[184:185], v[122:123]
	v_pk_add_f32 v[104:105], v[182:183], v[120:121]
	v_cvt_pk_bf16_f32 v100, v182, v183
	v_cvt_pk_bf16_f32 v101, v184, v185
	v_cvt_pk_bf16_f32 v102, v124, v125
	v_cvt_pk_bf16_f32 v103, v126, v127
	v_pk_add_f32 v[118:119], v[126:127], v[106:107]
	v_pk_add_f32 v[116:117], v[124:125], v[104:105]
	v_mfma_f32_32x32x16_bf16 v[128:143], v[176:179], v[172:175], v[128:143]
	v_exp_f32_e32 v120, v108
	v_exp_f32_e32 v121, v109
	v_exp_f32_e32 v122, v110
	v_exp_f32_e32 v123, v111
	v_pk_add_f32 v[110:111], v[188:189], v[118:119]
	v_pk_add_f32 v[108:109], v[186:187], v[116:117]
	v_cvt_pk_bf16_f32 v104, v186, v187
	v_cvt_pk_bf16_f32 v105, v188, v189
	v_cvt_pk_bf16_f32 v106, v120, v121
	v_cvt_pk_bf16_f32 v107, v122, v123
	v_pk_add_f32 v[178:179], v[122:123], v[110:111]
	v_pk_add_f32 v[176:177], v[120:121], v[108:109]
	s_waitcnt vmcnt(4) lgkmcnt(0)
	s_barrier
	s_add_u32 s70, s98, 0x18000
	s_addc_u32 s71, s99, 0
	s_add_i32 s68, 0x8000, s57
	s_mov_b32 m0, s68
	s_nop 0
	global_load_lds_dwordx4 v198, s[70:71]
	s_add_i32 m0, s68, 0x400
	s_nop 0
	global_load_lds_dwordx4 v194, s[70:71]
	s_add_u32 s2, s100, 0x80
	s_addc_u32 s3, s101, 0
	s_add_i32 s49, s58, 0
	s_add_i32 m0, s49, 0xc000
	s_nop 0
	global_load_lds_dwordx4 v196, s[2:3]
	s_add_i32 m0, s49, 0xc400
	s_nop 0
	global_load_lds_dwordx4 v192, s[2:3]
	s_add_i32 s2, s46, 0xffff4000
	ds_read_b128 v[108:111], v236
	ds_read_b128 v[116:119], v236 offset:4096
	ds_read_b128 v[120:123], v236 offset:8192
	ds_read_b128 v[124:127], v236 offset:12288
	s_waitcnt lgkmcnt(0)
	v_mfma_f32_32x32x16_bf16 v[80:95], v[108:111], v[112:115], v[80:95]
	ds_read_b128 v[108:111], v237
	v_mfma_f32_32x32x16_bf16 v[64:79], v[116:119], v[112:115], v[64:79]
	ds_read_b128 v[116:119], v237 offset:4096
	v_mfma_f32_32x32x16_bf16 v[16:31], v[120:123], v[112:115], v[16:31]
	ds_read_b128 v[120:123], v237 offset:8192
	v_mfma_f32_32x32x16_bf16 v[0:15], v[124:127], v[112:115], v[0:15]
	ds_read_b128 v[112:115], v237 offset:12288
	s_waitcnt lgkmcnt(0)
	v_mfma_f32_32x32x16_bf16 v[80:95], v[108:111], v[96:99], v[80:95]
	ds_read_b128 v[108:111], v238
	v_mfma_f32_32x32x16_bf16 v[64:79], v[116:119], v[96:99], v[64:79]
	ds_read_b128 v[116:119], v238 offset:4096
	v_mfma_f32_32x32x16_bf16 v[16:31], v[120:123], v[96:99], v[16:31]
	ds_read_b128 v[120:123], v238 offset:8192
	v_mfma_f32_32x32x16_bf16 v[0:15], v[112:115], v[96:99], v[0:15]
	ds_read_b128 v[96:99], v238 offset:12288
	s_waitcnt lgkmcnt(0)
	v_mfma_f32_32x32x16_bf16 v[80:95], v[108:111], v[100:103], v[80:95]
	ds_read_b128 v[108:111], v239
	v_mfma_f32_32x32x16_bf16 v[64:79], v[116:119], v[100:103], v[64:79]
	ds_read_b128 v[112:115], v239 offset:4096
	v_mfma_f32_32x32x16_bf16 v[16:31], v[120:123], v[100:103], v[16:31]
	ds_read_b128 v[116:119], v239 offset:8192
	v_mfma_f32_32x32x16_bf16 v[0:15], v[96:99], v[100:103], v[0:15]
	ds_read_b128 v[120:123], v239 offset:12288
	s_waitcnt lgkmcnt(0)
	v_mfma_f32_32x32x16_bf16 v[80:95], v[108:111], v[104:107], v[80:95]
	ds_read_b128 v[96:99], v205
	v_mfma_f32_32x32x16_bf16 v[64:79], v[112:115], v[104:107], v[64:79]
	ds_read_b128 v[100:103], v205 offset:8192
	v_mfma_f32_32x32x16_bf16 v[16:31], v[116:119], v[104:107], v[16:31]
	ds_read_b128 v[182:185], v211
	v_mfma_f32_32x32x16_bf16 v[0:15], v[120:123], v[104:107], v[0:15]
	ds_read_b128 v[186:189], v211 offset:8192
	s_waitcnt lgkmcnt(0)
	v_mfma_f32_32x32x16_bf16 v[112:127], v[96:99], v[160:163], 0
	ds_read_b128 v[216:219], v212
	v_exp_f32_e32 v224, v144
	v_exp_f32_e32 v225, v145
	v_exp_f32_e32 v226, v146
	v_exp_f32_e32 v227, v147
	ds_read_b128 v[220:223], v212 offset:8192
	v_mfma_f32_32x32x16_bf16 v[96:111], v[100:103], v[160:163], 0
	v_exp_f32_e32 v228, v148
	v_exp_f32_e32 v229, v149
	v_exp_f32_e32 v230, v150
	v_exp_f32_e32 v231, v151
	v_mfma_f32_32x32x16_bf16 v[112:127], v[182:185], v[164:167], v[112:127]
	ds_read_b128 v[148:151], v213
	v_exp_f32_e32 v232, v152
	v_exp_f32_e32 v233, v153
	v_exp_f32_e32 v234, v154
	v_exp_f32_e32 v235, v155
	v_cvt_pk_bf16_f32 v144, v224, v225
	v_cvt_pk_bf16_f32 v145, v226, v227
	v_cvt_pk_bf16_f32 v146, v228, v229
	v_cvt_pk_bf16_f32 v147, v230, v231
	v_pk_add_f32 v[154:155], v[230:231], v[226:227]
	v_pk_add_f32 v[152:153], v[228:229], v[224:225]
	v_mfma_f32_32x32x16_bf16 v[96:111], v[186:189], v[164:167], v[96:111]
	ds_read_b128 v[182:185], v213 offset:8192
	v_exp_f32_e32 v156, v156
	v_exp_f32_e32 v157, v157
	v_exp_f32_e32 v158, v158
	v_exp_f32_e32 v159, v159
	s_waitcnt lgkmcnt(0)
	v_mfma_f32_32x32x16_bf16 v[112:127], v[216:219], v[168:171], v[112:127]
	v_add_f32_e64 v154, v234, v154
	v_add_f32_e64 v155, v235, v155
	v_add_f32_e64 v152, v232, v152
	v_add_f32_e64 v153, v233, v153
	v_exp_f32_e32 v186, v128
	v_exp_f32_e32 v187, v129
	v_exp_f32_e32 v188, v130
	v_exp_f32_e32 v189, v131
	v_cvt_pk_bf16_f32 v128, v232, v233
	v_cvt_pk_bf16_f32 v129, v234, v235
	v_cvt_pk_bf16_f32 v130, v156, v157
	v_cvt_pk_bf16_f32 v131, v158, v159
	v_pk_add_f32 v[154:155], v[158:159], v[154:155]
	v_pk_add_f32 v[152:153], v[156:157], v[152:153]
	v_mfma_f32_32x32x16_bf16 v[96:111], v[220:223], v[168:171], v[96:111]
	v_exp_f32_e32 v156, v132
	v_exp_f32_e32 v157, v133
	v_exp_f32_e32 v158, v134
	v_exp_f32_e32 v159, v135
	v_mfma_f32_32x32x16_bf16 v[112:127], v[148:151], v[172:175], v[112:127]
	v_exp_f32_e32 v216, v136
	v_exp_f32_e32 v217, v137
	v_exp_f32_e32 v218, v138
	v_exp_f32_e32 v219, v139
	v_pk_add_f32 v[138:139], v[188:189], v[154:155]
	v_pk_add_f32 v[136:137], v[186:187], v[152:153]
	v_cvt_pk_bf16_f32 v132, v186, v187
	v_cvt_pk_bf16_f32 v133, v188, v189
	v_cvt_pk_bf16_f32 v134, v156, v157
	v_cvt_pk_bf16_f32 v135, v158, v159
	v_pk_add_f32 v[150:151], v[158:159], v[138:139]
	v_pk_add_f32 v[148:149], v[156:157], v[136:137]
	v_mfma_f32_32x32x16_bf16 v[96:111], v[182:185], v[172:175], v[96:111]
	v_exp_f32_e32 v152, v140
	v_exp_f32_e32 v153, v141
	v_exp_f32_e32 v154, v142
	v_exp_f32_e32 v155, v143
	v_pk_add_f32 v[142:143], v[218:219], v[150:151]
	v_pk_add_f32 v[140:141], v[216:217], v[148:149]
	v_cvt_pk_bf16_f32 v136, v216, v217
	v_cvt_pk_bf16_f32 v137, v218, v219
	v_cvt_pk_bf16_f32 v138, v152, v153
	v_cvt_pk_bf16_f32 v139, v154, v155
	v_pk_add_f32 v[142:143], v[154:155], v[142:143]
	v_pk_add_f32 v[140:141], v[152:153], v[140:141]
	s_waitcnt vmcnt(4) lgkmcnt(0)
	v_add_f32_e32 v148, v176, v177
	v_add_f32_e32 v149, v178, v179
	v_add_f32_e32 v148, v148, v149
	v_add_f32_e32 v140, v140, v141
	v_add_f32_e32 v141, v142, v143
	s_barrier
	v_add_f32_e32 v148, v180, v148
	v_add_f32_e32 v140, v140, v141
	v_add_f32_e32 v180, v148, v140
	s_add_i32 s47, s47, 2
	s_addk_i32 s41, 0x80
	s_add_i32 s46, s46, 0x8000
	s_add_u32 s98, s98, 0x30000
	s_addc_u32 s99, s99, 0
	s_add_u32 s100, s100, 0x100
	s_addc_u32 s101, s101, 0
	s_cmp_lt_u32 s47, 50
	s_cbranch_scc1 .Lst1_u6_loop
	s_cmp_lt_u32 s47, 60
	s_cbranch_scc1 .Lst1_single
